# attention: V tiles in a 4-slot LDS ring with a 4-step loop body - every V read/write offset is an immediate (no per-step SGPR rotation, no per-step address VALU)
# baseline (speedup 1.0000x reference)
; #define AT_GLOADK(k0) do { kreg = *(const u32x4*)(Kb + (size_t)((k0) + (tid >> 3)) * 64 + (tid & 7) * 8); \
;             if (MLA) preg = *(const u32x2*)(Pb + (size_t)((k0) + (tid >> 3)) * 32 + (tid & 7) * 4); } while (0)
; #define AT_GLOADV(k0) do { vreg = *(const u32x4*)(Vb + (size_t)((k0) + (tid >> 3)) * 64 + (tid & 7) * 8); } while (0)
; #define AT_WRITEK(buf) do { *(LAS u32x4*)(lds + (buf) * KBUF + (tid >> 3) * KSTR + (tid & 7) * 16) = kreg; \
;             if (MLA) *(LAS u32x2*)(lds + (buf) * KBUF + (tid >> 3) * KSTR + 128 + (tid & 7) * 8) = preg; } while (0)
; #define AT_WRITEV(buf) do { *(LAS u32x4*)(lds + 2 * KBUF + (buf) * VBUF + (tid >> 3) * VSTR + (tid & 7) * 16) = vreg; } while (0)
; template <bool MLA>
; DI void attn_phase(const int TID, const int BID, LAS unsigned char* lds, const Params& p, bool need_ctx) {
;     ...
;         if (item < 1024) {
;             const int rnd = item >> 8, w = item & 255, xcd = w & 7, slot = w >> 3, qb = slot & 7;
;             if (MLA) { const int grp = (rnd * 8 + xcd) * 4 + (slot >> 3); b = grp >> 4; head = grp & 15; }
;             else { const int grp = rnd * 8 + xcd; b = grp >> 2; head = (grp & 3) * 4 + (slot >> 3); }
;             row0 = b * 2048 + qb * 256; nk = NKEY;
;     ...
;         const int ntile = nk >> 6;
;         AT_GLOADK(0); AT_GLOADV(0); AT_WRITEK(0); AT_WRITEV(0);
;         AT_GLOADK(64); AT_WRITEK(1);
;         __syncthreads();
;         AT_QK(sa0, sa1, 0);
;         __syncthreads();
;         int t = 0;
;         for (; t < ntile - 2; t += 2) {
.Lamla_mainitem_first:
	s_lshr_b32 s21, s6, 8
	s_and_b32 s55, s6, 7
	s_lshl_b32 s21, s21, 3
	s_add_i32 s21, s21, s55
	s_bfe_u32 s55, s6, 0x30003
	s_bfe_u32 s56, s6, 0x20006
	s_lshl_b32 s21, s21, 2
	s_add_i32 s21, s21, s56
	s_lshr_b32 s15, s21, 4
	s_and_b32 s18, s21, 15
	s_lshl_b32 s20, s15, 11
	s_lshl_b32 s55, s55, 8
	s_add_i32 s20, s20, s55
	s_mov_b32 s7, 8

.Lamla_prio:
	ds_read_b128 v[136:139], v243 offset:0
	ds_read_b128 v[140:143], v243 offset:6656
	ds_read_b128 v[144:147], v243 offset:32
	ds_read_b128 v[148:151], v243 offset:6688
	s_waitcnt lgkmcnt(3)
	v_mfma_f32_32x32x16_bf16 v[32:47], v[136:139], v[112:115], 0
	ds_read_b128 v[136:139], v243 offset:64
	s_waitcnt lgkmcnt(3)
	v_mfma_f32_32x32x16_bf16 v[48:63], v[140:143], v[112:115], 0
	ds_read_b128 v[140:143], v243 offset:6720
	s_waitcnt lgkmcnt(3)
	v_mfma_f32_32x32x16_bf16 v[32:47], v[144:147], v[116:119], v[32:47]
	ds_read_b128 v[144:147], v243 offset:96
	s_waitcnt lgkmcnt(3)
	v_mfma_f32_32x32x16_bf16 v[48:63], v[148:151], v[116:119], v[48:63]
	ds_read_b128 v[148:151], v243 offset:6752
	s_waitcnt lgkmcnt(3)
	v_mfma_f32_32x32x16_bf16 v[32:47], v[136:139], v[120:123], v[32:47]
	ds_read_b128 v[136:139], v243 offset:128
	s_waitcnt lgkmcnt(3)
	v_mfma_f32_32x32x16_bf16 v[48:63], v[140:143], v[120:123], v[48:63]
	ds_read_b128 v[140:143], v243 offset:6784
	s_waitcnt lgkmcnt(3)
	v_mfma_f32_32x32x16_bf16 v[32:47], v[144:147], v[124:127], v[32:47]
	ds_read_b128 v[144:147], v243 offset:160
	s_waitcnt lgkmcnt(3)
	v_mfma_f32_32x32x16_bf16 v[48:63], v[148:151], v[124:127], v[48:63]
	ds_read_b128 v[148:151], v243 offset:6816
	s_waitcnt lgkmcnt(3)
	v_mfma_f32_32x32x16_bf16 v[32:47], v[136:139], v[128:131], v[32:47]
	s_waitcnt lgkmcnt(2)
	v_mfma_f32_32x32x16_bf16 v[48:63], v[140:143], v[128:131], v[48:63]
	s_waitcnt lgkmcnt(1)
	v_mfma_f32_32x32x16_bf16 v[32:47], v[144:147], v[132:135], v[32:47]
	s_waitcnt lgkmcnt(0)
	v_mfma_f32_32x32x16_bf16 v[48:63], v[148:151], v[132:135], v[48:63]
	s_waitcnt lgkmcnt(0)
	s_nop 7
	s_barrier
	ds_read_b128 v[136:139], v243 offset:13312
	ds_read_b128 v[140:143], v243 offset:19968
	ds_read_b128 v[144:147], v243 offset:13344
	ds_read_b128 v[148:151], v243 offset:20000
	v_max3_f32 v168, v32, v33, v34
	v_max3_f32 v170, v48, v49, v50
	v_max3_f32 v168, v168, v35, v36
	v_max3_f32 v170, v170, v51, v52
	v_max3_f32 v168, v168, v37, v38
	v_max3_f32 v170, v170, v53, v54
	v_max3_f32 v168, v168, v39, v40
	v_max3_f32 v170, v170, v55, v56
	v_max3_f32 v168, v168, v41, v42
	v_max3_f32 v170, v170, v57, v58
	v_max3_f32 v168, v168, v43, v44
	v_max3_f32 v170, v170, v59, v60
	v_max3_f32 v168, v168, v45, v46
	v_max3_f32 v170, v170, v61, v62
	v_max3_f32 v168, v168, v170, v47
	v_max_f32_e32 v168, v168, v63
	v_mov_b32_e32 v170, v168
	s_nop 1
	v_permlane32_swap_b32_e32 v168, v170
	v_max_f32_e32 v168, v168, v170
	v_mov_b32_e32 v170, v168
	v_sub_f32_e32 v218, v218, v170
	v_sub_f32_e32 v219, v219, v170
	v_sub_f32_e32 v220, v220, v170
	v_sub_f32_e32 v221, v221, v170
	v_sub_f32_e32 v222, v222, v170
	v_sub_f32_e32 v223, v223, v170
	v_sub_f32_e32 v224, v224, v170
	v_sub_f32_e32 v225, v225, v170
	v_sub_f32_e32 v226, v226, v170
	v_sub_f32_e32 v227, v227, v170
	v_sub_f32_e32 v228, v228, v170
	v_sub_f32_e32 v229, v229, v170
	v_sub_f32_e32 v230, v230, v170
	v_sub_f32_e32 v231, v231, v170
	v_sub_f32_e32 v232, v232, v170
	v_sub_f32_e32 v233, v233, v170
	v_sub_f32_e32 v32, v32, v170
	v_sub_f32_e32 v33, v33, v170
	v_sub_f32_e32 v34, v34, v170
	v_sub_f32_e32 v35, v35, v170
	v_sub_f32_e32 v36, v36, v170
	v_sub_f32_e32 v37, v37, v170
	v_sub_f32_e32 v38, v38, v170
	v_sub_f32_e32 v39, v39, v170
	v_sub_f32_e32 v40, v40, v170
	v_sub_f32_e32 v41, v41, v170
	v_sub_f32_e32 v42, v42, v170
	v_sub_f32_e32 v43, v43, v170
	v_sub_f32_e32 v44, v44, v170
	v_sub_f32_e32 v45, v45, v170
	v_sub_f32_e32 v46, v46, v170
	v_sub_f32_e32 v47, v47, v170
	v_sub_f32_e32 v48, v48, v170
	v_sub_f32_e32 v49, v49, v170
	v_sub_f32_e32 v50, v50, v170
	v_sub_f32_e32 v51, v51, v170
	v_sub_f32_e32 v52, v52, v170
	v_sub_f32_e32 v53, v53, v170
	v_sub_f32_e32 v54, v54, v170
	v_sub_f32_e32 v55, v55, v170
	v_sub_f32_e32 v56, v56, v170
	v_sub_f32_e32 v57, v57, v170
	v_sub_f32_e32 v58, v58, v170
	v_sub_f32_e32 v59, v59, v170
	v_sub_f32_e32 v60, v60, v170
	v_sub_f32_e32 v61, v61, v170
	v_sub_f32_e32 v62, v62, v170
	v_sub_f32_e32 v63, v63, v170
	s_waitcnt lgkmcnt(3)
	v_mfma_f32_32x32x16_bf16 v[64:79], v[136:139], v[112:115], v[218:233]
	v_exp_f32_e32 v32, v32
	v_exp_f32_e32 v48, v48
	v_exp_f32_e32 v33, v33
	v_exp_f32_e32 v49, v49
	v_exp_f32_e32 v34, v34
	ds_read_b128 v[136:139], v243 offset:13376
	s_mov_b32 s9, 0
	s_waitcnt lgkmcnt(3)
	v_mfma_f32_32x32x16_bf16 v[80:95], v[140:143], v[112:115], v[218:233]
	v_exp_f32_e32 v50, v50
	v_cvt_pk_bf16_f32 v96, v32, v33
	v_cvt_pk_bf16_f32 v104, v48, v49
	v_exp_f32_e32 v35, v35
	v_exp_f32_e32 v51, v51
	ds_read_b128 v[140:143], v243 offset:20032
	global_load_dwordx4 v[208:211], v167, s[2:3]
	global_load_dwordx2 v[216:217], v165, s[10:11]
	global_load_dwordx4 v[212:215], v167, s[4:5]
	s_add_u32 s2, s2, 0x2000
	s_addc_u32 s3, s3, 0
	s_add_u32 s10, s10, 0x1000
	s_addc_u32 s11, s11, 0
	s_add_u32 s4, s4, 0x2000
	s_addc_u32 s5, s5, 0
	s_waitcnt lgkmcnt(3)
	v_mfma_f32_32x32x16_bf16 v[64:79], v[144:147], v[116:119], v[64:79]
	v_exp_f32_e32 v36, v36
	v_exp_f32_e32 v52, v52
	v_cvt_pk_bf16_f32 v97, v34, v35
	v_cvt_pk_bf16_f32 v105, v50, v51
	v_exp_f32_e32 v37, v37
	ds_read_b128 v[144:147], v243 offset:13408
	s_waitcnt lgkmcnt(3)
	v_mfma_f32_32x32x16_bf16 v[80:95], v[148:151], v[116:119], v[80:95]
	v_exp_f32_e32 v53, v53
	v_exp_f32_e32 v38, v38
	v_exp_f32_e32 v54, v54
	v_cvt_pk_bf16_f32 v98, v36, v37
	ds_read_b128 v[148:151], v243 offset:20064
	s_waitcnt lgkmcnt(3)
	v_mfma_f32_32x32x16_bf16 v[64:79], v[136:139], v[120:123], v[64:79]
	v_cvt_pk_bf16_f32 v106, v52, v53
	v_exp_f32_e32 v39, v39
	v_exp_f32_e32 v55, v55
	v_exp_f32_e32 v40, v40
	v_exp_f32_e32 v56, v56
	ds_read_b128 v[136:139], v243 offset:13440
	s_waitcnt lgkmcnt(3)
	v_mfma_f32_32x32x16_bf16 v[80:95], v[140:143], v[120:123], v[80:95]
	v_cvt_pk_bf16_f32 v99, v38, v39
	v_cvt_pk_bf16_f32 v107, v54, v55
	v_exp_f32_e32 v41, v41
	v_exp_f32_e32 v57, v57
	v_exp_f32_e32 v42, v42
	ds_read_b128 v[140:143], v243 offset:20096
	s_waitcnt lgkmcnt(3)
	v_mfma_f32_32x32x16_bf16 v[64:79], v[144:147], v[124:127], v[64:79]
	v_exp_f32_e32 v58, v58
	v_cvt_pk_bf16_f32 v100, v40, v41
	v_cvt_pk_bf16_f32 v108, v56, v57
	v_exp_f32_e32 v43, v43
	v_exp_f32_e32 v59, v59
	ds_read_b128 v[144:147], v243 offset:13472
	ds_read_b64_tr_b16 v[176:177], v240 offset:0
	ds_read_b64_tr_b16 v[178:179], v240 offset:1536
	s_waitcnt vmcnt(5)
	ds_write_b128 v238, v[152:155]
	s_waitcnt vmcnt(4)
	ds_write_b64 v239, v[160:161]
	s_waitcnt vmcnt(3)
	ds_write_b128 v241, v[156:159] offset:12288
	s_waitcnt lgkmcnt(8)
	v_mfma_f32_32x32x16_bf16 v[80:95], v[148:151], v[124:127], v[80:95]
	v_exp_f32_e32 v44, v44
	v_exp_f32_e32 v60, v60
	v_cvt_pk_bf16_f32 v101, v42, v43
	v_cvt_pk_bf16_f32 v109, v58, v59
	v_exp_f32_e32 v45, v45
	ds_read_b128 v[148:151], v243 offset:20128
	ds_read_b64_tr_b16 v[180:181], v240 offset:64
	ds_read_b64_tr_b16 v[182:183], v240 offset:1600
	s_waitcnt lgkmcnt(10)
	v_mfma_f32_32x32x16_bf16 v[64:79], v[136:139], v[128:131], v[64:79]
	v_exp_f32_e32 v61, v61
	v_exp_f32_e32 v46, v46
	v_exp_f32_e32 v62, v62
	v_cvt_pk_bf16_f32 v102, v44, v45
	v_cvt_pk_bf16_f32 v110, v60, v61
	ds_read_b64_tr_b16 v[184:185], v240 offset:6144
	ds_read_b64_tr_b16 v[186:187], v240 offset:7680
	s_waitcnt lgkmcnt(11)
	v_mfma_f32_32x32x16_bf16 v[80:95], v[140:143], v[128:131], v[80:95]
	v_exp_f32_e32 v47, v47
	v_exp_f32_e32 v63, v63
	v_cvt_pk_bf16_f32 v103, v46, v47
	v_cvt_pk_bf16_f32 v111, v62, v63
	ds_read_b64_tr_b16 v[188:189], v240 offset:6208
	ds_read_b64_tr_b16 v[190:191], v240 offset:7744
	s_waitcnt lgkmcnt(12)
	v_mfma_f32_32x32x16_bf16 v[64:79], v[144:147], v[132:135], v[64:79]
	s_waitcnt lgkmcnt(6)
	v_mfma_f32_32x32x16_bf16 v[80:95], v[148:151], v[132:135], v[80:95]
	s_nop 13
	s_waitcnt lgkmcnt(0)
	s_barrier
	s_cmp_eq_u32 s7, 0
	s_cbranch_scc1 .Lamla_tail
.Lamla_loop:
	ds_read_b128 v[136:139], v243 offset:0
	ds_read_b128 v[140:143], v243 offset:6656
	ds_read_b128 v[144:147], v243 offset:32
	ds_read_b128 v[148:151], v243 offset:6688
	s_waitcnt lgkmcnt(10)
	v_mfma_f32_32x32x16_bf16 v[0:15], v[176:179], v[96:99], v[0:15]
	v_max3_f32 v168, v64, v65, v66
	v_max3_f32 v170, v80, v81, v82
	v_max3_f32 v168, v168, v67, v68
	v_max3_f32 v170, v170, v83, v84
	v_max3_f32 v168, v168, v69, v70
	s_mov_b32 s9, 0
	s_waitcnt lgkmcnt(8)
	v_mfma_f32_32x32x16_bf16 v[16:31], v[180:183], v[96:99], v[16:31]
	v_max3_f32 v170, v170, v85, v86
	v_max3_f32 v168, v168, v71, v72
	v_max3_f32 v170, v170, v87, v88
	v_max3_f32 v168, v168, v73, v74
	global_load_dwordx4 v[152:155], v167, s[2:3]
	global_load_dwordx2 v[160:161], v165, s[10:11]
	global_load_dwordx4 v[156:159], v167, s[4:5]
	s_add_u32 s2, s2, 0x2000
	s_addc_u32 s3, s3, 0
	s_add_u32 s10, s10, 0x1000
	s_addc_u32 s11, s11, 0
	s_add_u32 s4, s4, 0x2000
	s_addc_u32 s5, s5, 0
	v_mfma_f32_16x16x32_bf16 v[234:237], v[246:249], v[96:99], v[234:237]
	v_max3_f32 v170, v170, v89, v90
	v_max3_f32 v168, v168, v75, v76
	v_max3_f32 v170, v170, v91, v92
	v_max3_f32 v168, v168, v77, v78
	v_max3_f32 v170, v170, v93, v94
	v_max3_f32 v168, v168, v170, v79
	v_max_f32_e32 v168, v168, v95
	v_cmp_lt_f32_e32 vcc, 0x41000000, v168
	s_cbranch_vccz .Lamla_nors_2
	v_mov_b32_e32 v170, v168
	s_nop 1
	v_permlane32_swap_b32_e32 v168, v170
	v_max_f32_e32 v168, v168, v170
	v_max_f32_e32 v170, 0, v168
	v_exp_f32_e64 v166, -v170
	v_sub_f32_e32 v218, v218, v170
	v_sub_f32_e32 v219, v219, v170
	v_sub_f32_e32 v220, v220, v170
	v_sub_f32_e32 v221, v221, v170
	v_sub_f32_e32 v222, v222, v170
	v_sub_f32_e32 v223, v223, v170
	v_sub_f32_e32 v224, v224, v170
	v_sub_f32_e32 v225, v225, v170
	v_sub_f32_e32 v226, v226, v170
	v_sub_f32_e32 v227, v227, v170
	v_sub_f32_e32 v228, v228, v170
	v_sub_f32_e32 v229, v229, v170
	v_sub_f32_e32 v230, v230, v170
	v_sub_f32_e32 v231, v231, v170
	v_sub_f32_e32 v232, v232, v170
	v_sub_f32_e32 v233, v233, v170
	v_sub_f32_e32 v64, v64, v170
	v_sub_f32_e32 v65, v65, v170
	v_sub_f32_e32 v66, v66, v170
	v_sub_f32_e32 v67, v67, v170
	v_sub_f32_e32 v68, v68, v170
	v_sub_f32_e32 v69, v69, v170
	v_sub_f32_e32 v70, v70, v170
	v_sub_f32_e32 v71, v71, v170
	v_sub_f32_e32 v72, v72, v170
	v_sub_f32_e32 v73, v73, v170
	v_sub_f32_e32 v74, v74, v170
	v_sub_f32_e32 v75, v75, v170
	v_sub_f32_e32 v76, v76, v170
	v_sub_f32_e32 v77, v77, v170
	v_sub_f32_e32 v78, v78, v170
	v_sub_f32_e32 v79, v79, v170
	v_sub_f32_e32 v80, v80, v170
	v_sub_f32_e32 v81, v81, v170
	v_sub_f32_e32 v82, v82, v170
	v_sub_f32_e32 v83, v83, v170
	v_sub_f32_e32 v84, v84, v170
	v_sub_f32_e32 v85, v85, v170
	v_sub_f32_e32 v86, v86, v170
	v_sub_f32_e32 v87, v87, v170
	v_sub_f32_e32 v88, v88, v170
	v_sub_f32_e32 v89, v89, v170
	v_sub_f32_e32 v90, v90, v170
	v_sub_f32_e32 v91, v91, v170
	v_sub_f32_e32 v92, v92, v170
	v_sub_f32_e32 v93, v93, v170
	v_sub_f32_e32 v94, v94, v170
	v_sub_f32_e32 v95, v95, v170
	s_mov_b32 s9, 1
.Lamla_nors_2:
	s_waitcnt lgkmcnt(3)
	v_mfma_f32_32x32x16_bf16 v[32:47], v[136:139], v[112:115], v[218:233]
	v_exp_f32_e32 v64, v64
	v_exp_f32_e32 v80, v80
	ds_read_b128 v[136:139], v243 offset:64
	ds_read_b64_tr_b16 v[192:193], v240 offset:3072
	ds_read_b64_tr_b16 v[194:195], v240 offset:4608
	s_waitcnt lgkmcnt(5)
	v_mfma_f32_32x32x16_bf16 v[48:63], v[140:143], v[112:115], v[218:233]
	v_exp_f32_e32 v65, v65
	v_exp_f32_e32 v81, v81
	ds_read_b128 v[140:143], v243 offset:6720
	ds_read_b64_tr_b16 v[196:197], v240 offset:3136
	ds_read_b64_tr_b16 v[198:199], v240 offset:4672
	v_mfma_f32_32x32x16_bf16 v[0:15], v[184:187], v[104:107], v[0:15]
	v_exp_f32_e32 v66, v66
	v_exp_f32_e32 v82, v82
	ds_read_b64_tr_b16 v[200:201], v240 offset:9216
	ds_read_b64_tr_b16 v[202:203], v240 offset:10752
	s_waitcnt lgkmcnt(9)
	v_mfma_f32_32x32x16_bf16 v[32:47], v[144:147], v[116:119], v[32:47]
	v_cvt_pk_bf16_f32 v96, v64, v65
	v_exp_f32_e32 v67, v67
	v_exp_f32_e32 v83, v83
	ds_read_b128 v[144:147], v243 offset:96
	ds_read_b64_tr_b16 v[204:205], v240 offset:9280
	ds_read_b64_tr_b16 v[206:207], v240 offset:10816
	v_mfma_f32_32x32x16_bf16 v[16:31], v[188:191], v[104:107], v[16:31]
	v_exp_f32_e32 v68, v68
	v_exp_f32_e32 v84, v84
	s_waitcnt lgkmcnt(11)
	v_mfma_f32_32x32x16_bf16 v[48:63], v[148:151], v[116:119], v[48:63]
	v_cvt_pk_bf16_f32 v97, v66, v67
	v_exp_f32_e32 v69, v69
	ds_read_b128 v[148:151], v243 offset:6752
	v_mfma_f32_16x16x32_bf16 v[234:237], v[246:249], v[104:107], v[234:237]
	v_cvt_pk_bf16_f32 v104, v80, v81
	v_cvt_pk_bf16_f32 v105, v82, v83
	v_exp_f32_e32 v85, v85
	v_exp_f32_e32 v70, v70
	s_waitcnt lgkmcnt(11)
	v_mfma_f32_32x32x16_bf16 v[32:47], v[136:139], v[120:123], v[32:47]
	v_exp_f32_e32 v86, v86
	v_cvt_pk_bf16_f32 v98, v68, v69
	v_cvt_pk_bf16_f32 v106, v84, v85
	ds_read_b128 v[136:139], v243 offset:128
	s_waitcnt lgkmcnt(9)
	v_mfma_f32_32x32x16_bf16 v[48:63], v[140:143], v[120:123], v[48:63]
	v_exp_f32_e32 v71, v71
	v_exp_f32_e32 v87, v87
	ds_read_b128 v[140:143], v243 offset:6784
	v_mfma_f32_32x32x16_bf16 v[0:15], v[192:195], v[100:103], v[0:15]
	v_exp_f32_e32 v72, v72
	v_exp_f32_e32 v88, v88
	v_cvt_pk_bf16_f32 v99, v70, v71
	s_waitcnt lgkmcnt(5)
	v_mfma_f32_32x32x16_bf16 v[32:47], v[144:147], v[124:127], v[32:47]
	v_cvt_pk_bf16_f32 v107, v86, v87
	v_exp_f32_e32 v73, v73
	v_exp_f32_e32 v89, v89
	ds_read_b128 v[144:147], v243 offset:160
	v_mfma_f32_32x32x16_bf16 v[16:31], v[196:199], v[100:103], v[16:31]
	v_exp_f32_e32 v74, v74
	v_exp_f32_e32 v90, v90
	s_waitcnt vmcnt(5)
	ds_write_b128 v238, v[208:211] offset:13312
	s_waitcnt vmcnt(4)
	ds_write_b64 v239, v[216:217] offset:13312
	s_waitcnt vmcnt(3)
	ds_write_b128 v241, v[212:215] offset:24576
	s_waitcnt lgkmcnt(6)
	v_mfma_f32_32x32x16_bf16 v[48:63], v[148:151], v[124:127], v[48:63]
	v_exp_f32_e32 v75, v75
	v_exp_f32_e32 v91, v91
	ds_read_b128 v[148:151], v243 offset:6816
	v_mfma_f32_16x16x32_bf16 v[234:237], v[246:249], v[100:103], v[234:237]
	v_cvt_pk_bf16_f32 v100, v72, v73
	v_exp_f32_e32 v76, v76
	v_exp_f32_e32 v92, v92
	s_waitcnt lgkmcnt(6)
	v_mfma_f32_32x32x16_bf16 v[32:47], v[136:139], v[128:131], v[32:47]
	v_cvt_pk_bf16_f32 v101, v74, v75
	v_exp_f32_e32 v77, v77
	s_waitcnt lgkmcnt(5)
	v_mfma_f32_32x32x16_bf16 v[48:63], v[140:143], v[128:131], v[48:63]
	v_exp_f32_e32 v93, v93
	v_exp_f32_e32 v78, v78
	ds_read_b64_tr_b16 v[176:177], v240 offset:12288
	ds_read_b64_tr_b16 v[178:179], v240 offset:13824
	v_mfma_f32_32x32x16_bf16 v[0:15], v[200:203], v[108:111], v[0:15]
	v_exp_f32_e32 v94, v94
	v_cvt_pk_bf16_f32 v102, v76, v77
	v_exp_f32_e32 v79, v79
	ds_read_b64_tr_b16 v[180:181], v240 offset:12352
	ds_read_b64_tr_b16 v[182:183], v240 offset:13888
	s_waitcnt lgkmcnt(8)
	v_mfma_f32_32x32x16_bf16 v[32:47], v[144:147], v[132:135], v[32:47]
	v_exp_f32_e32 v95, v95
	v_cvt_pk_bf16_f32 v103, v78, v79
	ds_read_b64_tr_b16 v[184:185], v240 offset:18432
	ds_read_b64_tr_b16 v[186:187], v240 offset:19968
	v_mfma_f32_32x32x16_bf16 v[16:31], v[204:207], v[108:111], v[16:31]
	ds_read_b64_tr_b16 v[188:189], v240 offset:18496
	ds_read_b64_tr_b16 v[190:191], v240 offset:20032
	s_waitcnt lgkmcnt(8)
	v_mfma_f32_32x32x16_bf16 v[48:63], v[148:151], v[132:135], v[48:63]
	v_mfma_f32_16x16x32_bf16 v[234:237], v[246:249], v[108:111], v[234:237]
	v_cvt_pk_bf16_f32 v108, v88, v89
	v_cvt_pk_bf16_f32 v109, v90, v91
	v_cvt_pk_bf16_f32 v110, v92, v93
	v_cvt_pk_bf16_f32 v111, v94, v95
	s_cmp_lg_u32 s9, 0
	s_cbranch_scc0 .Lamla_noresc_3
	s_nop 15
	v_mul_f32_e32 v0, v0, v166
	v_mul_f32_e32 v1, v1, v166
	v_mul_f32_e32 v2, v2, v166
	v_mul_f32_e32 v3, v3, v166
	v_mul_f32_e32 v4, v4, v166
	v_mul_f32_e32 v5, v5, v166
	v_mul_f32_e32 v6, v6, v166
	v_mul_f32_e32 v7, v7, v166
	v_mul_f32_e32 v8, v8, v166
	v_mul_f32_e32 v9, v9, v166
	v_mul_f32_e32 v10, v10, v166
	v_mul_f32_e32 v11, v11, v166
	v_mul_f32_e32 v12, v12, v166
	v_mul_f32_e32 v13, v13, v166
	v_mul_f32_e32 v14, v14, v166
	v_mul_f32_e32 v15, v15, v166
	v_mul_f32_e32 v16, v16, v166
	v_mul_f32_e32 v17, v17, v166
	v_mul_f32_e32 v18, v18, v166
	v_mul_f32_e32 v19, v19, v166
	v_mul_f32_e32 v20, v20, v166
	v_mul_f32_e32 v21, v21, v166
	v_mul_f32_e32 v22, v22, v166
	v_mul_f32_e32 v23, v23, v166
	v_mul_f32_e32 v24, v24, v166
	v_mul_f32_e32 v25, v25, v166
	v_mul_f32_e32 v26, v26, v166
	v_mul_f32_e32 v27, v27, v166
	v_mul_f32_e32 v28, v28, v166
	v_mul_f32_e32 v29, v29, v166
	v_mul_f32_e32 v30, v30, v166
	v_mul_f32_e32 v31, v31, v166
	v_add_u32_e32 v170, 64, v175
	ds_bpermute_b32 v173, v170, v166
	v_mul_f32_e32 v234, v234, v166
	s_waitcnt lgkmcnt(0)
	v_mul_f32_e32 v235, v235, v173
.Lamla_noresc_3:
	s_nop 6
	s_barrier
	ds_read_b128 v[136:139], v243 offset:13312
	ds_read_b128 v[140:143], v243 offset:19968
	ds_read_b128 v[144:147], v243 offset:13344
	ds_read_b128 v[148:151], v243 offset:20000
	s_waitcnt lgkmcnt(10)
	v_mfma_f32_32x32x16_bf16 v[0:15], v[176:179], v[96:99], v[0:15]
	v_max3_f32 v168, v32, v33, v34
	v_max3_f32 v170, v48, v49, v50
	v_max3_f32 v168, v168, v35, v36
	v_max3_f32 v170, v170, v51, v52
	v_max3_f32 v168, v168, v37, v38
	s_mov_b32 s9, 0
	s_waitcnt lgkmcnt(8)
	v_mfma_f32_32x32x16_bf16 v[16:31], v[180:183], v[96:99], v[16:31]
	v_max3_f32 v170, v170, v53, v54
	v_max3_f32 v168, v168, v39, v40
	v_max3_f32 v170, v170, v55, v56
	v_max3_f32 v168, v168, v41, v42
	global_load_dwordx4 v[208:211], v167, s[2:3]
	global_load_dwordx2 v[216:217], v165, s[10:11]
	global_load_dwordx4 v[212:215], v167, s[4:5]
	s_add_u32 s2, s2, 0x2000
	s_addc_u32 s3, s3, 0
	s_add_u32 s10, s10, 0x1000
	s_addc_u32 s11, s11, 0
	s_add_u32 s4, s4, 0x2000
	s_addc_u32 s5, s5, 0
	v_mfma_f32_16x16x32_bf16 v[234:237], v[246:249], v[96:99], v[234:237]
	v_max3_f32 v170, v170, v57, v58
	v_max3_f32 v168, v168, v43, v44
	v_max3_f32 v170, v170, v59, v60
	v_max3_f32 v168, v168, v45, v46
	v_max3_f32 v170, v170, v61, v62
	v_max3_f32 v168, v168, v170, v47
	v_max_f32_e32 v168, v168, v63
	v_cmp_lt_f32_e32 vcc, 0x41000000, v168
	s_cbranch_vccz .Lamla_nors_4
	v_mov_b32_e32 v170, v168
	s_nop 1
	v_permlane32_swap_b32_e32 v168, v170
	v_max_f32_e32 v168, v168, v170
	v_max_f32_e32 v170, 0, v168
	v_exp_f32_e64 v166, -v170
	v_sub_f32_e32 v218, v218, v170
	v_sub_f32_e32 v219, v219, v170
	v_sub_f32_e32 v220, v220, v170
	v_sub_f32_e32 v221, v221, v170
	v_sub_f32_e32 v222, v222, v170
	v_sub_f32_e32 v223, v223, v170
	v_sub_f32_e32 v224, v224, v170
	v_sub_f32_e32 v225, v225, v170
	v_sub_f32_e32 v226, v226, v170
	v_sub_f32_e32 v227, v227, v170
	v_sub_f32_e32 v228, v228, v170
	v_sub_f32_e32 v229, v229, v170
	v_sub_f32_e32 v230, v230, v170
	v_sub_f32_e32 v231, v231, v170
	v_sub_f32_e32 v232, v232, v170
	v_sub_f32_e32 v233, v233, v170
	v_sub_f32_e32 v32, v32, v170
	v_sub_f32_e32 v33, v33, v170
	v_sub_f32_e32 v34, v34, v170
	v_sub_f32_e32 v35, v35, v170
	v_sub_f32_e32 v36, v36, v170
	v_sub_f32_e32 v37, v37, v170
	v_sub_f32_e32 v38, v38, v170
	v_sub_f32_e32 v39, v39, v170
	v_sub_f32_e32 v40, v40, v170
	v_sub_f32_e32 v41, v41, v170
	v_sub_f32_e32 v42, v42, v170
	v_sub_f32_e32 v43, v43, v170
	v_sub_f32_e32 v44, v44, v170
	v_sub_f32_e32 v45, v45, v170
	v_sub_f32_e32 v46, v46, v170
	v_sub_f32_e32 v47, v47, v170
	v_sub_f32_e32 v48, v48, v170
	v_sub_f32_e32 v49, v49, v170
	v_sub_f32_e32 v50, v50, v170
	v_sub_f32_e32 v51, v51, v170
	v_sub_f32_e32 v52, v52, v170
	v_sub_f32_e32 v53, v53, v170
	v_sub_f32_e32 v54, v54, v170
	v_sub_f32_e32 v55, v55, v170
	v_sub_f32_e32 v56, v56, v170
	v_sub_f32_e32 v57, v57, v170
	v_sub_f32_e32 v58, v58, v170
	v_sub_f32_e32 v59, v59, v170
	v_sub_f32_e32 v60, v60, v170
	v_sub_f32_e32 v61, v61, v170
	v_sub_f32_e32 v62, v62, v170
	v_sub_f32_e32 v63, v63, v170
	s_mov_b32 s9, 1
.Lamla_nors_4:
	s_waitcnt lgkmcnt(3)
	v_mfma_f32_32x32x16_bf16 v[64:79], v[136:139], v[112:115], v[218:233]
	v_exp_f32_e32 v32, v32
	v_exp_f32_e32 v48, v48
	ds_read_b128 v[136:139], v243 offset:13376
	ds_read_b64_tr_b16 v[192:193], v240 offset:15360
	ds_read_b64_tr_b16 v[194:195], v240 offset:16896
	s_waitcnt lgkmcnt(5)
	v_mfma_f32_32x32x16_bf16 v[80:95], v[140:143], v[112:115], v[218:233]
	v_exp_f32_e32 v33, v33
	v_exp_f32_e32 v49, v49
	ds_read_b128 v[140:143], v243 offset:20032
	ds_read_b64_tr_b16 v[196:197], v240 offset:15424
	ds_read_b64_tr_b16 v[198:199], v240 offset:16960
	v_mfma_f32_32x32x16_bf16 v[0:15], v[184:187], v[104:107], v[0:15]
	v_exp_f32_e32 v34, v34
	v_exp_f32_e32 v50, v50
	ds_read_b64_tr_b16 v[200:201], v240 offset:21504
	ds_read_b64_tr_b16 v[202:203], v240 offset:23040
	s_waitcnt lgkmcnt(9)
	v_mfma_f32_32x32x16_bf16 v[64:79], v[144:147], v[116:119], v[64:79]
	v_cvt_pk_bf16_f32 v96, v32, v33
	v_exp_f32_e32 v35, v35
	v_exp_f32_e32 v51, v51
	ds_read_b128 v[144:147], v243 offset:13408
	ds_read_b64_tr_b16 v[204:205], v240 offset:21568
	ds_read_b64_tr_b16 v[206:207], v240 offset:23104
	v_mfma_f32_32x32x16_bf16 v[16:31], v[188:191], v[104:107], v[16:31]
	v_exp_f32_e32 v36, v36
	v_exp_f32_e32 v52, v52
	s_waitcnt lgkmcnt(11)
	v_mfma_f32_32x32x16_bf16 v[80:95], v[148:151], v[116:119], v[80:95]
	v_cvt_pk_bf16_f32 v97, v34, v35
	v_exp_f32_e32 v37, v37
	ds_read_b128 v[148:151], v243 offset:20064
	v_mfma_f32_16x16x32_bf16 v[234:237], v[246:249], v[104:107], v[234:237]
	v_cvt_pk_bf16_f32 v104, v48, v49
	v_cvt_pk_bf16_f32 v105, v50, v51
	v_exp_f32_e32 v53, v53
	v_exp_f32_e32 v38, v38
	s_waitcnt lgkmcnt(11)
	v_mfma_f32_32x32x16_bf16 v[64:79], v[136:139], v[120:123], v[64:79]
	v_exp_f32_e32 v54, v54
	v_cvt_pk_bf16_f32 v98, v36, v37
	v_cvt_pk_bf16_f32 v106, v52, v53
	ds_read_b128 v[136:139], v243 offset:13440
	s_waitcnt lgkmcnt(9)
	v_mfma_f32_32x32x16_bf16 v[80:95], v[140:143], v[120:123], v[80:95]
	v_exp_f32_e32 v39, v39
	v_exp_f32_e32 v55, v55
	ds_read_b128 v[140:143], v243 offset:20096
	v_mfma_f32_32x32x16_bf16 v[0:15], v[192:195], v[100:103], v[0:15]
	v_exp_f32_e32 v40, v40
	v_exp_f32_e32 v56, v56
	v_cvt_pk_bf16_f32 v99, v38, v39
	s_waitcnt lgkmcnt(5)
	v_mfma_f32_32x32x16_bf16 v[64:79], v[144:147], v[124:127], v[64:79]
	v_cvt_pk_bf16_f32 v107, v54, v55
	v_exp_f32_e32 v41, v41
	v_exp_f32_e32 v57, v57
	ds_read_b128 v[144:147], v243 offset:13472
	v_mfma_f32_32x32x16_bf16 v[16:31], v[196:199], v[100:103], v[16:31]
	v_exp_f32_e32 v42, v42
	v_exp_f32_e32 v58, v58
	s_waitcnt vmcnt(5)
	ds_write_b128 v238, v[152:155]
	s_waitcnt vmcnt(4)
	ds_write_b64 v239, v[160:161]
	s_waitcnt vmcnt(3)
	ds_write_b128 v241, v[156:159] offset:36864
	s_waitcnt lgkmcnt(6)
	v_mfma_f32_32x32x16_bf16 v[80:95], v[148:151], v[124:127], v[80:95]
	v_exp_f32_e32 v43, v43
	v_exp_f32_e32 v59, v59
	ds_read_b128 v[148:151], v243 offset:20128
	v_mfma_f32_16x16x32_bf16 v[234:237], v[246:249], v[100:103], v[234:237]
	v_cvt_pk_bf16_f32 v100, v40, v41
	v_exp_f32_e32 v44, v44
	v_exp_f32_e32 v60, v60
	s_waitcnt lgkmcnt(6)
	v_mfma_f32_32x32x16_bf16 v[64:79], v[136:139], v[128:131], v[64:79]
	v_cvt_pk_bf16_f32 v101, v42, v43
	v_exp_f32_e32 v45, v45
	s_waitcnt lgkmcnt(5)
	v_mfma_f32_32x32x16_bf16 v[80:95], v[140:143], v[128:131], v[80:95]
	v_exp_f32_e32 v61, v61
	v_exp_f32_e32 v46, v46
	ds_read_b64_tr_b16 v[176:177], v240 offset:24576
	ds_read_b64_tr_b16 v[178:179], v240 offset:26112
	v_mfma_f32_32x32x16_bf16 v[0:15], v[200:203], v[108:111], v[0:15]
	v_exp_f32_e32 v62, v62
	v_cvt_pk_bf16_f32 v102, v44, v45
	v_exp_f32_e32 v47, v47
	ds_read_b64_tr_b16 v[180:181], v240 offset:24640
	ds_read_b64_tr_b16 v[182:183], v240 offset:26176
	s_waitcnt lgkmcnt(8)
	v_mfma_f32_32x32x16_bf16 v[64:79], v[144:147], v[132:135], v[64:79]
	v_exp_f32_e32 v63, v63
	v_cvt_pk_bf16_f32 v103, v46, v47
	ds_read_b64_tr_b16 v[184:185], v240 offset:30720
	ds_read_b64_tr_b16 v[186:187], v240 offset:32256
	v_mfma_f32_32x32x16_bf16 v[16:31], v[204:207], v[108:111], v[16:31]
	ds_read_b64_tr_b16 v[188:189], v240 offset:30784
	ds_read_b64_tr_b16 v[190:191], v240 offset:32320
	s_waitcnt lgkmcnt(8)
	v_mfma_f32_32x32x16_bf16 v[80:95], v[148:151], v[132:135], v[80:95]
	v_mfma_f32_16x16x32_bf16 v[234:237], v[246:249], v[108:111], v[234:237]
	v_cvt_pk_bf16_f32 v108, v56, v57
	v_cvt_pk_bf16_f32 v109, v58, v59
	v_cvt_pk_bf16_f32 v110, v60, v61
	v_cvt_pk_bf16_f32 v111, v62, v63
	s_cmp_lg_u32 s9, 0
	s_cbranch_scc0 .Lamla_noresc_5
	s_nop 15
	v_mul_f32_e32 v0, v0, v166
	v_mul_f32_e32 v1, v1, v166
	v_mul_f32_e32 v2, v2, v166
	v_mul_f32_e32 v3, v3, v166
	v_mul_f32_e32 v4, v4, v166
	v_mul_f32_e32 v5, v5, v166
	v_mul_f32_e32 v6, v6, v166
	v_mul_f32_e32 v7, v7, v166
	v_mul_f32_e32 v8, v8, v166
	v_mul_f32_e32 v9, v9, v166
	v_mul_f32_e32 v10, v10, v166
	v_mul_f32_e32 v11, v11, v166
	v_mul_f32_e32 v12, v12, v166
	v_mul_f32_e32 v13, v13, v166
	v_mul_f32_e32 v14, v14, v166
	v_mul_f32_e32 v15, v15, v166
	v_mul_f32_e32 v16, v16, v166
	v_mul_f32_e32 v17, v17, v166
	v_mul_f32_e32 v18, v18, v166
	v_mul_f32_e32 v19, v19, v166
	v_mul_f32_e32 v20, v20, v166
	v_mul_f32_e32 v21, v21, v166
	v_mul_f32_e32 v22, v22, v166
	v_mul_f32_e32 v23, v23, v166
	v_mul_f32_e32 v24, v24, v166
	v_mul_f32_e32 v25, v25, v166
	v_mul_f32_e32 v26, v26, v166
	v_mul_f32_e32 v27, v27, v166
	v_mul_f32_e32 v28, v28, v166
	v_mul_f32_e32 v29, v29, v166
	v_mul_f32_e32 v30, v30, v166
	v_mul_f32_e32 v31, v31, v166
	v_add_u32_e32 v170, 64, v175
	ds_bpermute_b32 v173, v170, v166
	v_mul_f32_e32 v234, v234, v166
	s_waitcnt lgkmcnt(0)
	v_mul_f32_e32 v235, v235, v173
.Lamla_noresc_5:
	s_nop 6
	s_barrier
	ds_read_b128 v[136:139], v243 offset:0
	ds_read_b128 v[140:143], v243 offset:6656
	ds_read_b128 v[144:147], v243 offset:32
	ds_read_b128 v[148:151], v243 offset:6688
	s_waitcnt lgkmcnt(10)
	v_mfma_f32_32x32x16_bf16 v[0:15], v[176:179], v[96:99], v[0:15]
	v_max3_f32 v168, v64, v65, v66
	v_max3_f32 v170, v80, v81, v82
	v_max3_f32 v168, v168, v67, v68
	v_max3_f32 v170, v170, v83, v84
	v_max3_f32 v168, v168, v69, v70
	s_mov_b32 s9, 0
	s_waitcnt lgkmcnt(8)
	v_mfma_f32_32x32x16_bf16 v[16:31], v[180:183], v[96:99], v[16:31]
	v_max3_f32 v170, v170, v85, v86
	v_max3_f32 v168, v168, v71, v72
	v_max3_f32 v170, v170, v87, v88
	v_max3_f32 v168, v168, v73, v74
	global_load_dwordx4 v[152:155], v167, s[2:3]
	global_load_dwordx2 v[160:161], v165, s[10:11]
	global_load_dwordx4 v[156:159], v167, s[4:5]
	s_add_u32 s2, s2, 0x2000
	s_addc_u32 s3, s3, 0
	s_add_u32 s10, s10, 0x1000
	s_addc_u32 s11, s11, 0
	s_add_u32 s4, s4, 0x2000
	s_addc_u32 s5, s5, 0
	v_mfma_f32_16x16x32_bf16 v[234:237], v[246:249], v[96:99], v[234:237]
	v_max3_f32 v170, v170, v89, v90
	v_max3_f32 v168, v168, v75, v76
	v_max3_f32 v170, v170, v91, v92
	v_max3_f32 v168, v168, v77, v78
	v_max3_f32 v170, v170, v93, v94
	v_max3_f32 v168, v168, v170, v79
	v_max_f32_e32 v168, v168, v95
	v_cmp_lt_f32_e32 vcc, 0x41000000, v168
	s_cbranch_vccz .Lamla_nors_6
	v_mov_b32_e32 v170, v168
	s_nop 1
	v_permlane32_swap_b32_e32 v168, v170
	v_max_f32_e32 v168, v168, v170
	v_max_f32_e32 v170, 0, v168
	v_exp_f32_e64 v166, -v170
	v_sub_f32_e32 v218, v218, v170
	v_sub_f32_e32 v219, v219, v170
	v_sub_f32_e32 v220, v220, v170
	v_sub_f32_e32 v221, v221, v170
	v_sub_f32_e32 v222, v222, v170
	v_sub_f32_e32 v223, v223, v170
	v_sub_f32_e32 v224, v224, v170
	v_sub_f32_e32 v225, v225, v170
	v_sub_f32_e32 v226, v226, v170
	v_sub_f32_e32 v227, v227, v170
	v_sub_f32_e32 v228, v228, v170
	v_sub_f32_e32 v229, v229, v170
	v_sub_f32_e32 v230, v230, v170
	v_sub_f32_e32 v231, v231, v170
	v_sub_f32_e32 v232, v232, v170
	v_sub_f32_e32 v233, v233, v170
	v_sub_f32_e32 v64, v64, v170
	v_sub_f32_e32 v65, v65, v170
	v_sub_f32_e32 v66, v66, v170
	v_sub_f32_e32 v67, v67, v170
	v_sub_f32_e32 v68, v68, v170
	v_sub_f32_e32 v69, v69, v170
	v_sub_f32_e32 v70, v70, v170
	v_sub_f32_e32 v71, v71, v170
	v_sub_f32_e32 v72, v72, v170
	v_sub_f32_e32 v73, v73, v170
	v_sub_f32_e32 v74, v74, v170
	v_sub_f32_e32 v75, v75, v170
	v_sub_f32_e32 v76, v76, v170
	v_sub_f32_e32 v77, v77, v170
	v_sub_f32_e32 v78, v78, v170
	v_sub_f32_e32 v79, v79, v170
	v_sub_f32_e32 v80, v80, v170
	v_sub_f32_e32 v81, v81, v170
	v_sub_f32_e32 v82, v82, v170
	v_sub_f32_e32 v83, v83, v170
	v_sub_f32_e32 v84, v84, v170
	v_sub_f32_e32 v85, v85, v170
	v_sub_f32_e32 v86, v86, v170
	v_sub_f32_e32 v87, v87, v170
	v_sub_f32_e32 v88, v88, v170
	v_sub_f32_e32 v89, v89, v170
	v_sub_f32_e32 v90, v90, v170
	v_sub_f32_e32 v91, v91, v170
	v_sub_f32_e32 v92, v92, v170
	v_sub_f32_e32 v93, v93, v170
	v_sub_f32_e32 v94, v94, v170
	v_sub_f32_e32 v95, v95, v170
	s_mov_b32 s9, 1
.Lamla_nors_6:
	s_waitcnt lgkmcnt(3)
	v_mfma_f32_32x32x16_bf16 v[32:47], v[136:139], v[112:115], v[218:233]
	v_exp_f32_e32 v64, v64
	v_exp_f32_e32 v80, v80
	ds_read_b128 v[136:139], v243 offset:64
	ds_read_b64_tr_b16 v[192:193], v240 offset:27648
	ds_read_b64_tr_b16 v[194:195], v240 offset:29184
	s_waitcnt lgkmcnt(5)
	v_mfma_f32_32x32x16_bf16 v[48:63], v[140:143], v[112:115], v[218:233]
	v_exp_f32_e32 v65, v65
	v_exp_f32_e32 v81, v81
	ds_read_b128 v[140:143], v243 offset:6720
	ds_read_b64_tr_b16 v[196:197], v240 offset:27712
	ds_read_b64_tr_b16 v[198:199], v240 offset:29248
	v_mfma_f32_32x32x16_bf16 v[0:15], v[184:187], v[104:107], v[0:15]
	v_exp_f32_e32 v66, v66
	v_exp_f32_e32 v82, v82
	ds_read_b64_tr_b16 v[200:201], v240 offset:33792
	ds_read_b64_tr_b16 v[202:203], v240 offset:35328
	s_waitcnt lgkmcnt(9)
	v_mfma_f32_32x32x16_bf16 v[32:47], v[144:147], v[116:119], v[32:47]
	v_cvt_pk_bf16_f32 v96, v64, v65
	v_exp_f32_e32 v67, v67
	v_exp_f32_e32 v83, v83
	ds_read_b128 v[144:147], v243 offset:96
	ds_read_b64_tr_b16 v[204:205], v240 offset:33856
	ds_read_b64_tr_b16 v[206:207], v240 offset:35392
	v_mfma_f32_32x32x16_bf16 v[16:31], v[188:191], v[104:107], v[16:31]
	v_exp_f32_e32 v68, v68
	v_exp_f32_e32 v84, v84
	s_waitcnt lgkmcnt(11)
	v_mfma_f32_32x32x16_bf16 v[48:63], v[148:151], v[116:119], v[48:63]
	v_cvt_pk_bf16_f32 v97, v66, v67
	v_exp_f32_e32 v69, v69
	ds_read_b128 v[148:151], v243 offset:6752
	v_mfma_f32_16x16x32_bf16 v[234:237], v[246:249], v[104:107], v[234:237]
	v_cvt_pk_bf16_f32 v104, v80, v81
	v_cvt_pk_bf16_f32 v105, v82, v83
	v_exp_f32_e32 v85, v85
	v_exp_f32_e32 v70, v70
	s_waitcnt lgkmcnt(11)
	v_mfma_f32_32x32x16_bf16 v[32:47], v[136:139], v[120:123], v[32:47]
	v_exp_f32_e32 v86, v86
	v_cvt_pk_bf16_f32 v98, v68, v69
	v_cvt_pk_bf16_f32 v106, v84, v85
	ds_read_b128 v[136:139], v243 offset:128
	s_waitcnt lgkmcnt(9)
	v_mfma_f32_32x32x16_bf16 v[48:63], v[140:143], v[120:123], v[48:63]
	v_exp_f32_e32 v71, v71
	v_exp_f32_e32 v87, v87
	ds_read_b128 v[140:143], v243 offset:6784
	v_mfma_f32_32x32x16_bf16 v[0:15], v[192:195], v[100:103], v[0:15]
	v_exp_f32_e32 v72, v72
	v_exp_f32_e32 v88, v88
	v_cvt_pk_bf16_f32 v99, v70, v71
	s_waitcnt lgkmcnt(5)
	v_mfma_f32_32x32x16_bf16 v[32:47], v[144:147], v[124:127], v[32:47]
	v_cvt_pk_bf16_f32 v107, v86, v87
	v_exp_f32_e32 v73, v73
	v_exp_f32_e32 v89, v89
	ds_read_b128 v[144:147], v243 offset:160
	v_mfma_f32_32x32x16_bf16 v[16:31], v[196:199], v[100:103], v[16:31]
	v_exp_f32_e32 v74, v74
	v_exp_f32_e32 v90, v90
	s_waitcnt vmcnt(5)
	ds_write_b128 v238, v[208:211] offset:13312
	s_waitcnt vmcnt(4)
	ds_write_b64 v239, v[216:217] offset:13312
	s_waitcnt vmcnt(3)
	ds_write_b128 v241, v[212:215]
	s_waitcnt lgkmcnt(6)
	v_mfma_f32_32x32x16_bf16 v[48:63], v[148:151], v[124:127], v[48:63]
	v_exp_f32_e32 v75, v75
	v_exp_f32_e32 v91, v91
	ds_read_b128 v[148:151], v243 offset:6816
	v_mfma_f32_16x16x32_bf16 v[234:237], v[246:249], v[100:103], v[234:237]
	v_cvt_pk_bf16_f32 v100, v72, v73
	v_exp_f32_e32 v76, v76
	v_exp_f32_e32 v92, v92
	s_waitcnt lgkmcnt(6)
	v_mfma_f32_32x32x16_bf16 v[32:47], v[136:139], v[128:131], v[32:47]
	v_cvt_pk_bf16_f32 v101, v74, v75
	v_exp_f32_e32 v77, v77
	s_waitcnt lgkmcnt(5)
	v_mfma_f32_32x32x16_bf16 v[48:63], v[140:143], v[128:131], v[48:63]
	v_exp_f32_e32 v93, v93
	v_exp_f32_e32 v78, v78
	ds_read_b64_tr_b16 v[176:177], v240 offset:36864
	ds_read_b64_tr_b16 v[178:179], v240 offset:38400
	v_mfma_f32_32x32x16_bf16 v[0:15], v[200:203], v[108:111], v[0:15]
	v_exp_f32_e32 v94, v94
	v_cvt_pk_bf16_f32 v102, v76, v77
	v_exp_f32_e32 v79, v79
	ds_read_b64_tr_b16 v[180:181], v240 offset:36928
	ds_read_b64_tr_b16 v[182:183], v240 offset:38464
	s_waitcnt lgkmcnt(8)
	v_mfma_f32_32x32x16_bf16 v[32:47], v[144:147], v[132:135], v[32:47]
	v_exp_f32_e32 v95, v95
	v_cvt_pk_bf16_f32 v103, v78, v79
	ds_read_b64_tr_b16 v[184:185], v240 offset:43008
	ds_read_b64_tr_b16 v[186:187], v240 offset:44544
	v_mfma_f32_32x32x16_bf16 v[16:31], v[204:207], v[108:111], v[16:31]
	ds_read_b64_tr_b16 v[188:189], v240 offset:43072
	ds_read_b64_tr_b16 v[190:191], v240 offset:44608
	s_waitcnt lgkmcnt(8)
	v_mfma_f32_32x32x16_bf16 v[48:63], v[148:151], v[132:135], v[48:63]
	v_mfma_f32_16x16x32_bf16 v[234:237], v[246:249], v[108:111], v[234:237]
	v_cvt_pk_bf16_f32 v108, v88, v89
	v_cvt_pk_bf16_f32 v109, v90, v91
	v_cvt_pk_bf16_f32 v110, v92, v93
	v_cvt_pk_bf16_f32 v111, v94, v95
	s_cmp_lg_u32 s9, 0
	s_cbranch_scc0 .Lamla_noresc_7
	s_nop 15
	v_mul_f32_e32 v0, v0, v166
	v_mul_f32_e32 v1, v1, v166
	v_mul_f32_e32 v2, v2, v166
	v_mul_f32_e32 v3, v3, v166
	v_mul_f32_e32 v4, v4, v166
	v_mul_f32_e32 v5, v5, v166
	v_mul_f32_e32 v6, v6, v166
	v_mul_f32_e32 v7, v7, v166
	v_mul_f32_e32 v8, v8, v166
	v_mul_f32_e32 v9, v9, v166
	v_mul_f32_e32 v10, v10, v166
	v_mul_f32_e32 v11, v11, v166
	v_mul_f32_e32 v12, v12, v166
	v_mul_f32_e32 v13, v13, v166
	v_mul_f32_e32 v14, v14, v166
	v_mul_f32_e32 v15, v15, v166
	v_mul_f32_e32 v16, v16, v166
	v_mul_f32_e32 v17, v17, v166
	v_mul_f32_e32 v18, v18, v166
	v_mul_f32_e32 v19, v19, v166
	v_mul_f32_e32 v20, v20, v166
	v_mul_f32_e32 v21, v21, v166
	v_mul_f32_e32 v22, v22, v166
	v_mul_f32_e32 v23, v23, v166
	v_mul_f32_e32 v24, v24, v166
	v_mul_f32_e32 v25, v25, v166
	v_mul_f32_e32 v26, v26, v166
	v_mul_f32_e32 v27, v27, v166
	v_mul_f32_e32 v28, v28, v166
	v_mul_f32_e32 v29, v29, v166
	v_mul_f32_e32 v30, v30, v166
	v_mul_f32_e32 v31, v31, v166
	v_add_u32_e32 v170, 64, v175
	ds_bpermute_b32 v173, v170, v166
	v_mul_f32_e32 v234, v234, v166
	s_waitcnt lgkmcnt(0)
	v_mul_f32_e32 v235, v235, v173

.Lamla_nors_8:
	s_waitcnt lgkmcnt(3)
	v_mfma_f32_32x32x16_bf16 v[64:79], v[136:139], v[112:115], v[218:233]
	v_exp_f32_e32 v32, v32
	v_exp_f32_e32 v48, v48
	ds_read_b128 v[136:139], v243 offset:13376
	ds_read_b64_tr_b16 v[192:193], v240 offset:39936
	ds_read_b64_tr_b16 v[194:195], v240 offset:41472
	s_waitcnt lgkmcnt(5)
	v_mfma_f32_32x32x16_bf16 v[80:95], v[140:143], v[112:115], v[218:233]
	v_exp_f32_e32 v33, v33
	v_exp_f32_e32 v49, v49
	ds_read_b128 v[140:143], v243 offset:20032
	ds_read_b64_tr_b16 v[196:197], v240 offset:40000
	ds_read_b64_tr_b16 v[198:199], v240 offset:41536
	v_mfma_f32_32x32x16_bf16 v[0:15], v[184:187], v[104:107], v[0:15]
	v_exp_f32_e32 v34, v34
	v_exp_f32_e32 v50, v50
	ds_read_b64_tr_b16 v[200:201], v240 offset:46080
	ds_read_b64_tr_b16 v[202:203], v240 offset:47616
	s_waitcnt lgkmcnt(9)
	v_mfma_f32_32x32x16_bf16 v[64:79], v[144:147], v[116:119], v[64:79]
	v_cvt_pk_bf16_f32 v96, v32, v33
	v_exp_f32_e32 v35, v35
	v_exp_f32_e32 v51, v51
	ds_read_b128 v[144:147], v243 offset:13408
	ds_read_b64_tr_b16 v[204:205], v240 offset:46144
	ds_read_b64_tr_b16 v[206:207], v240 offset:47680
	v_mfma_f32_32x32x16_bf16 v[16:31], v[188:191], v[104:107], v[16:31]
	v_exp_f32_e32 v36, v36
	v_exp_f32_e32 v52, v52
	s_waitcnt lgkmcnt(11)
	v_mfma_f32_32x32x16_bf16 v[80:95], v[148:151], v[116:119], v[80:95]
	v_cvt_pk_bf16_f32 v97, v34, v35
	v_exp_f32_e32 v37, v37
	ds_read_b128 v[148:151], v243 offset:20064
	v_mfma_f32_16x16x32_bf16 v[234:237], v[246:249], v[104:107], v[234:237]
	v_cvt_pk_bf16_f32 v104, v48, v49
	v_cvt_pk_bf16_f32 v105, v50, v51
	v_exp_f32_e32 v53, v53
	v_exp_f32_e32 v38, v38
	s_waitcnt lgkmcnt(11)
	v_mfma_f32_32x32x16_bf16 v[64:79], v[136:139], v[120:123], v[64:79]
	v_exp_f32_e32 v54, v54
	v_cvt_pk_bf16_f32 v98, v36, v37
	v_cvt_pk_bf16_f32 v106, v52, v53
	ds_read_b128 v[136:139], v243 offset:13440
	s_waitcnt lgkmcnt(9)
	v_mfma_f32_32x32x16_bf16 v[80:95], v[140:143], v[120:123], v[80:95]
	v_exp_f32_e32 v39, v39
	v_exp_f32_e32 v55, v55
	ds_read_b128 v[140:143], v243 offset:20096
	v_mfma_f32_32x32x16_bf16 v[0:15], v[192:195], v[100:103], v[0:15]
	v_exp_f32_e32 v40, v40
	v_exp_f32_e32 v56, v56
	v_cvt_pk_bf16_f32 v99, v38, v39
	s_waitcnt lgkmcnt(5)
	v_mfma_f32_32x32x16_bf16 v[64:79], v[144:147], v[124:127], v[64:79]
	v_cvt_pk_bf16_f32 v107, v54, v55
	v_exp_f32_e32 v41, v41
	v_exp_f32_e32 v57, v57
	ds_read_b128 v[144:147], v243 offset:13472
	v_mfma_f32_32x32x16_bf16 v[16:31], v[196:199], v[100:103], v[16:31]
	v_exp_f32_e32 v42, v42
	v_exp_f32_e32 v58, v58
	s_waitcnt vmcnt(5)
	ds_write_b128 v238, v[152:155]
	s_waitcnt vmcnt(4)
	ds_write_b64 v239, v[160:161]
	s_waitcnt vmcnt(3)
	ds_write_b128 v241, v[156:159] offset:12288
	s_waitcnt lgkmcnt(6)
	v_mfma_f32_32x32x16_bf16 v[80:95], v[148:151], v[124:127], v[80:95]
	v_exp_f32_e32 v43, v43
	v_exp_f32_e32 v59, v59
	ds_read_b128 v[148:151], v243 offset:20128
	v_mfma_f32_16x16x32_bf16 v[234:237], v[246:249], v[100:103], v[234:237]
	v_cvt_pk_bf16_f32 v100, v40, v41
	v_exp_f32_e32 v44, v44
	v_exp_f32_e32 v60, v60
	s_waitcnt lgkmcnt(6)
	v_mfma_f32_32x32x16_bf16 v[64:79], v[136:139], v[128:131], v[64:79]
	v_cvt_pk_bf16_f32 v101, v42, v43
	v_exp_f32_e32 v45, v45
	s_waitcnt lgkmcnt(5)
	v_mfma_f32_32x32x16_bf16 v[80:95], v[140:143], v[128:131], v[80:95]
	v_exp_f32_e32 v61, v61
	v_exp_f32_e32 v46, v46
	ds_read_b64_tr_b16 v[176:177], v240 offset:0
	ds_read_b64_tr_b16 v[178:179], v240 offset:1536
	v_mfma_f32_32x32x16_bf16 v[0:15], v[200:203], v[108:111], v[0:15]
	v_exp_f32_e32 v62, v62
	v_cvt_pk_bf16_f32 v102, v44, v45
	v_exp_f32_e32 v47, v47
	ds_read_b64_tr_b16 v[180:181], v240 offset:64
	ds_read_b64_tr_b16 v[182:183], v240 offset:1600
	s_waitcnt lgkmcnt(8)
	v_mfma_f32_32x32x16_bf16 v[64:79], v[144:147], v[132:135], v[64:79]
	v_exp_f32_e32 v63, v63
	v_cvt_pk_bf16_f32 v103, v46, v47
	ds_read_b64_tr_b16 v[184:185], v240 offset:6144
	ds_read_b64_tr_b16 v[186:187], v240 offset:7680
	v_mfma_f32_32x32x16_bf16 v[16:31], v[204:207], v[108:111], v[16:31]
	ds_read_b64_tr_b16 v[188:189], v240 offset:6208
	ds_read_b64_tr_b16 v[190:191], v240 offset:7744
	s_waitcnt lgkmcnt(8)
	v_mfma_f32_32x32x16_bf16 v[80:95], v[148:151], v[132:135], v[80:95]
	v_mfma_f32_16x16x32_bf16 v[234:237], v[246:249], v[108:111], v[234:237]
	v_cvt_pk_bf16_f32 v108, v56, v57
	v_cvt_pk_bf16_f32 v109, v58, v59
	v_cvt_pk_bf16_f32 v110, v60, v61
	v_cvt_pk_bf16_f32 v111, v62, v63
	s_cmp_lg_u32 s9, 0
	s_cbranch_scc0 .Lamla_noresc_9
	s_nop 15
	v_mul_f32_e32 v0, v0, v166
	v_mul_f32_e32 v1, v1, v166
	v_mul_f32_e32 v2, v2, v166
	v_mul_f32_e32 v3, v3, v166
	v_mul_f32_e32 v4, v4, v166
	v_mul_f32_e32 v5, v5, v166
	v_mul_f32_e32 v6, v6, v166
	v_mul_f32_e32 v7, v7, v166
	v_mul_f32_e32 v8, v8, v166
	v_mul_f32_e32 v9, v9, v166
	v_mul_f32_e32 v10, v10, v166
	v_mul_f32_e32 v11, v11, v166
	v_mul_f32_e32 v12, v12, v166
	v_mul_f32_e32 v13, v13, v166
	v_mul_f32_e32 v14, v14, v166
	v_mul_f32_e32 v15, v15, v166
	v_mul_f32_e32 v16, v16, v166
	v_mul_f32_e32 v17, v17, v166
	v_mul_f32_e32 v18, v18, v166
	v_mul_f32_e32 v19, v19, v166
	v_mul_f32_e32 v20, v20, v166
	v_mul_f32_e32 v21, v21, v166
	v_mul_f32_e32 v22, v22, v166
	v_mul_f32_e32 v23, v23, v166
	v_mul_f32_e32 v24, v24, v166
	v_mul_f32_e32 v25, v25, v166
	v_mul_f32_e32 v26, v26, v166
	v_mul_f32_e32 v27, v27, v166
	v_mul_f32_e32 v28, v28, v166
	v_mul_f32_e32 v29, v29, v166
	v_mul_f32_e32 v30, v30, v166
	v_mul_f32_e32 v31, v31, v166
	v_add_u32_e32 v170, 64, v175
	ds_bpermute_b32 v173, v170, v166
	v_mul_f32_e32 v234, v234, v166
	s_waitcnt lgkmcnt(0)
	v_mul_f32_e32 v235, v235, v173

.Lamla_tail:
	ds_read_b128 v[136:139], v243 offset:0
	ds_read_b128 v[140:143], v243 offset:6656
	ds_read_b128 v[144:147], v243 offset:32
	ds_read_b128 v[148:151], v243 offset:6688
	s_waitcnt lgkmcnt(10)
	v_mfma_f32_32x32x16_bf16 v[0:15], v[176:179], v[96:99], v[0:15]
	v_max3_f32 v168, v64, v65, v66
	v_max3_f32 v170, v80, v81, v82
	v_max3_f32 v168, v168, v67, v68
	v_max3_f32 v170, v170, v83, v84
	v_max3_f32 v168, v168, v69, v70
	s_mov_b32 s9, 0
	s_waitcnt lgkmcnt(8)
	v_mfma_f32_32x32x16_bf16 v[16:31], v[180:183], v[96:99], v[16:31]
	v_max3_f32 v170, v170, v85, v86
	v_max3_f32 v168, v168, v71, v72
	v_max3_f32 v170, v170, v87, v88
	v_max3_f32 v168, v168, v73, v74
	global_load_dwordx4 v[156:159], v167, s[4:5]
	s_add_u32 s4, s4, 0x2000
	s_addc_u32 s5, s5, 0
	v_mfma_f32_16x16x32_bf16 v[234:237], v[246:249], v[96:99], v[234:237]
	v_max3_f32 v170, v170, v89, v90
	v_max3_f32 v168, v168, v75, v76
	v_max3_f32 v170, v170, v91, v92
	v_max3_f32 v168, v168, v77, v78
	v_max3_f32 v170, v170, v93, v94
	v_max3_f32 v168, v168, v170, v79
	v_max_f32_e32 v168, v168, v95
	v_cmp_lt_f32_e32 vcc, 0x41000000, v168
	s_cbranch_vccz .Lamla_nors_10
	v_mov_b32_e32 v170, v168
	s_nop 1
	v_permlane32_swap_b32_e32 v168, v170
	v_max_f32_e32 v168, v168, v170
	v_max_f32_e32 v170, 0, v168
	v_exp_f32_e64 v166, -v170
	v_sub_f32_e32 v218, v218, v170
	v_sub_f32_e32 v219, v219, v170
	v_sub_f32_e32 v220, v220, v170
	v_sub_f32_e32 v221, v221, v170
	v_sub_f32_e32 v222, v222, v170
	v_sub_f32_e32 v223, v223, v170
	v_sub_f32_e32 v224, v224, v170
	v_sub_f32_e32 v225, v225, v170
	v_sub_f32_e32 v226, v226, v170
	v_sub_f32_e32 v227, v227, v170
	v_sub_f32_e32 v228, v228, v170
	v_sub_f32_e32 v229, v229, v170
	v_sub_f32_e32 v230, v230, v170
	v_sub_f32_e32 v231, v231, v170
	v_sub_f32_e32 v232, v232, v170
	v_sub_f32_e32 v233, v233, v170
	v_sub_f32_e32 v64, v64, v170
	v_sub_f32_e32 v65, v65, v170
	v_sub_f32_e32 v66, v66, v170
	v_sub_f32_e32 v67, v67, v170
	v_sub_f32_e32 v68, v68, v170
	v_sub_f32_e32 v69, v69, v170
	v_sub_f32_e32 v70, v70, v170
	v_sub_f32_e32 v71, v71, v170
	v_sub_f32_e32 v72, v72, v170
	v_sub_f32_e32 v73, v73, v170
	v_sub_f32_e32 v74, v74, v170
	v_sub_f32_e32 v75, v75, v170
	v_sub_f32_e32 v76, v76, v170
	v_sub_f32_e32 v77, v77, v170
	v_sub_f32_e32 v78, v78, v170
	v_sub_f32_e32 v79, v79, v170
	v_sub_f32_e32 v80, v80, v170
	v_sub_f32_e32 v81, v81, v170
	v_sub_f32_e32 v82, v82, v170
	v_sub_f32_e32 v83, v83, v170
	v_sub_f32_e32 v84, v84, v170
	v_sub_f32_e32 v85, v85, v170
	v_sub_f32_e32 v86, v86, v170
	v_sub_f32_e32 v87, v87, v170
	v_sub_f32_e32 v88, v88, v170
	v_sub_f32_e32 v89, v89, v170
	v_sub_f32_e32 v90, v90, v170
	v_sub_f32_e32 v91, v91, v170
	v_sub_f32_e32 v92, v92, v170
	v_sub_f32_e32 v93, v93, v170
	v_sub_f32_e32 v94, v94, v170
	v_sub_f32_e32 v95, v95, v170
	s_mov_b32 s9, 1
.Lamla_nors_10:
	s_waitcnt lgkmcnt(3)
	v_mfma_f32_32x32x16_bf16 v[32:47], v[136:139], v[112:115], v[218:233]
	v_exp_f32_e32 v64, v64
	v_exp_f32_e32 v80, v80
	ds_read_b128 v[136:139], v243 offset:64
	ds_read_b64_tr_b16 v[192:193], v240 offset:3072
	ds_read_b64_tr_b16 v[194:195], v240 offset:4608
	s_waitcnt lgkmcnt(5)
	v_mfma_f32_32x32x16_bf16 v[48:63], v[140:143], v[112:115], v[218:233]
	v_exp_f32_e32 v65, v65
	v_exp_f32_e32 v81, v81
	ds_read_b128 v[140:143], v243 offset:6720
	ds_read_b64_tr_b16 v[196:197], v240 offset:3136
	ds_read_b64_tr_b16 v[198:199], v240 offset:4672
	v_mfma_f32_32x32x16_bf16 v[0:15], v[184:187], v[104:107], v[0:15]
	v_exp_f32_e32 v66, v66
	v_exp_f32_e32 v82, v82
	ds_read_b64_tr_b16 v[200:201], v240 offset:9216
	ds_read_b64_tr_b16 v[202:203], v240 offset:10752
	s_waitcnt lgkmcnt(9)
	v_mfma_f32_32x32x16_bf16 v[32:47], v[144:147], v[116:119], v[32:47]
	v_cvt_pk_bf16_f32 v96, v64, v65
	v_exp_f32_e32 v67, v67
	v_exp_f32_e32 v83, v83
	ds_read_b128 v[144:147], v243 offset:96
	ds_read_b64_tr_b16 v[204:205], v240 offset:9280
	ds_read_b64_tr_b16 v[206:207], v240 offset:10816
	v_mfma_f32_32x32x16_bf16 v[16:31], v[188:191], v[104:107], v[16:31]
	v_exp_f32_e32 v68, v68
	v_exp_f32_e32 v84, v84
	s_waitcnt lgkmcnt(11)
	v_mfma_f32_32x32x16_bf16 v[48:63], v[148:151], v[116:119], v[48:63]
	v_cvt_pk_bf16_f32 v97, v66, v67
	v_exp_f32_e32 v69, v69
	ds_read_b128 v[148:151], v243 offset:6752
	v_mfma_f32_16x16x32_bf16 v[234:237], v[246:249], v[104:107], v[234:237]
	v_cvt_pk_bf16_f32 v104, v80, v81
	v_cvt_pk_bf16_f32 v105, v82, v83
	v_exp_f32_e32 v85, v85
	v_exp_f32_e32 v70, v70
	s_waitcnt lgkmcnt(11)
	v_mfma_f32_32x32x16_bf16 v[32:47], v[136:139], v[120:123], v[32:47]
	v_exp_f32_e32 v86, v86
	v_cvt_pk_bf16_f32 v98, v68, v69
	v_cvt_pk_bf16_f32 v106, v84, v85
	ds_read_b128 v[136:139], v243 offset:128
	s_waitcnt lgkmcnt(9)
	v_mfma_f32_32x32x16_bf16 v[48:63], v[140:143], v[120:123], v[48:63]
	v_exp_f32_e32 v71, v71
	v_exp_f32_e32 v87, v87
	ds_read_b128 v[140:143], v243 offset:6784
	v_mfma_f32_32x32x16_bf16 v[0:15], v[192:195], v[100:103], v[0:15]
	v_exp_f32_e32 v72, v72
	v_exp_f32_e32 v88, v88
	v_cvt_pk_bf16_f32 v99, v70, v71
	s_waitcnt lgkmcnt(5)
	v_mfma_f32_32x32x16_bf16 v[32:47], v[144:147], v[124:127], v[32:47]
	v_cvt_pk_bf16_f32 v107, v86, v87
	v_exp_f32_e32 v73, v73
	v_exp_f32_e32 v89, v89
	ds_read_b128 v[144:147], v243 offset:160
	v_mfma_f32_32x32x16_bf16 v[16:31], v[196:199], v[100:103], v[16:31]
	v_exp_f32_e32 v74, v74
	v_exp_f32_e32 v90, v90
	s_waitcnt vmcnt(3)
	ds_write_b128 v238, v[208:211] offset:13312
	s_waitcnt vmcnt(2)
	ds_write_b64 v239, v[216:217] offset:13312
	s_waitcnt vmcnt(1)
	ds_write_b128 v241, v[212:215] offset:24576
	s_waitcnt lgkmcnt(6)
	v_mfma_f32_32x32x16_bf16 v[48:63], v[148:151], v[124:127], v[48:63]
	v_exp_f32_e32 v75, v75
	v_exp_f32_e32 v91, v91
	ds_read_b128 v[148:151], v243 offset:6816
	v_mfma_f32_16x16x32_bf16 v[234:237], v[246:249], v[100:103], v[234:237]
	v_cvt_pk_bf16_f32 v100, v72, v73
	v_exp_f32_e32 v76, v76
	v_exp_f32_e32 v92, v92
	s_waitcnt lgkmcnt(6)
	v_mfma_f32_32x32x16_bf16 v[32:47], v[136:139], v[128:131], v[32:47]
	v_cvt_pk_bf16_f32 v101, v74, v75
	v_exp_f32_e32 v77, v77
	s_waitcnt lgkmcnt(5)
	v_mfma_f32_32x32x16_bf16 v[48:63], v[140:143], v[128:131], v[48:63]
	v_exp_f32_e32 v93, v93
	v_exp_f32_e32 v78, v78
	ds_read_b64_tr_b16 v[176:177], v240 offset:12288
	ds_read_b64_tr_b16 v[178:179], v240 offset:13824
	v_mfma_f32_32x32x16_bf16 v[0:15], v[200:203], v[108:111], v[0:15]
	v_exp_f32_e32 v94, v94
	v_cvt_pk_bf16_f32 v102, v76, v77
	v_exp_f32_e32 v79, v79
	ds_read_b64_tr_b16 v[180:181], v240 offset:12352
	ds_read_b64_tr_b16 v[182:183], v240 offset:13888
	s_waitcnt lgkmcnt(8)
	v_mfma_f32_32x32x16_bf16 v[32:47], v[144:147], v[132:135], v[32:47]
	v_exp_f32_e32 v95, v95
	v_cvt_pk_bf16_f32 v103, v78, v79
	ds_read_b64_tr_b16 v[184:185], v240 offset:18432
	ds_read_b64_tr_b16 v[186:187], v240 offset:19968
	v_mfma_f32_32x32x16_bf16 v[16:31], v[204:207], v[108:111], v[16:31]
	ds_read_b64_tr_b16 v[188:189], v240 offset:18496
	ds_read_b64_tr_b16 v[190:191], v240 offset:20032
	s_waitcnt lgkmcnt(8)
	v_mfma_f32_32x32x16_bf16 v[48:63], v[148:151], v[132:135], v[48:63]
	v_mfma_f32_16x16x32_bf16 v[234:237], v[246:249], v[108:111], v[234:237]
	v_cvt_pk_bf16_f32 v108, v88, v89
	v_cvt_pk_bf16_f32 v109, v90, v91
	v_cvt_pk_bf16_f32 v110, v92, v93
	v_cvt_pk_bf16_f32 v111, v94, v95
	s_cmp_lg_u32 s9, 0
	s_cbranch_scc0 .Lamla_noresc_11
	s_nop 15
	v_mul_f32_e32 v0, v0, v166
	v_mul_f32_e32 v1, v1, v166
	v_mul_f32_e32 v2, v2, v166
	v_mul_f32_e32 v3, v3, v166
	v_mul_f32_e32 v4, v4, v166
	v_mul_f32_e32 v5, v5, v166
	v_mul_f32_e32 v6, v6, v166
	v_mul_f32_e32 v7, v7, v166
	v_mul_f32_e32 v8, v8, v166
	v_mul_f32_e32 v9, v9, v166
	v_mul_f32_e32 v10, v10, v166
	v_mul_f32_e32 v11, v11, v166
	v_mul_f32_e32 v12, v12, v166
	v_mul_f32_e32 v13, v13, v166
	v_mul_f32_e32 v14, v14, v166
	v_mul_f32_e32 v15, v15, v166
	v_mul_f32_e32 v16, v16, v166
	v_mul_f32_e32 v17, v17, v166
	v_mul_f32_e32 v18, v18, v166
	v_mul_f32_e32 v19, v19, v166
	v_mul_f32_e32 v20, v20, v166
	v_mul_f32_e32 v21, v21, v166
	v_mul_f32_e32 v22, v22, v166
	v_mul_f32_e32 v23, v23, v166
	v_mul_f32_e32 v24, v24, v166
	v_mul_f32_e32 v25, v25, v166
	v_mul_f32_e32 v26, v26, v166
	v_mul_f32_e32 v27, v27, v166
	v_mul_f32_e32 v28, v28, v166
	v_mul_f32_e32 v29, v29, v166
	v_mul_f32_e32 v30, v30, v166
	v_mul_f32_e32 v31, v31, v166
	v_add_u32_e32 v170, 64, v175
	ds_bpermute_b32 v173, v170, v166
	v_mul_f32_e32 v234, v234, v166
	s_waitcnt lgkmcnt(0)
	v_mul_f32_e32 v235, v235, v173
.Lamla_noresc_11:
	s_nop 6
	s_barrier
	ds_read_b128 v[136:139], v243 offset:13312
	ds_read_b128 v[140:143], v243 offset:19968
	ds_read_b128 v[144:147], v243 offset:13344
	ds_read_b128 v[148:151], v243 offset:20000
	s_waitcnt lgkmcnt(10)
	v_mfma_f32_32x32x16_bf16 v[0:15], v[176:179], v[96:99], v[0:15]
	v_max3_f32 v168, v32, v33, v34
	v_max3_f32 v170, v48, v49, v50
	v_max3_f32 v168, v168, v35, v36
	v_max3_f32 v170, v170, v51, v52
	v_max3_f32 v168, v168, v37, v38
	s_mov_b32 s9, 0
	s_waitcnt lgkmcnt(8)
	v_mfma_f32_32x32x16_bf16 v[16:31], v[180:183], v[96:99], v[16:31]
	v_max3_f32 v170, v170, v53, v54
	v_max3_f32 v168, v168, v39, v40
	v_max3_f32 v170, v170, v55, v56
	v_max3_f32 v168, v168, v41, v42
	v_mfma_f32_16x16x32_bf16 v[234:237], v[246:249], v[96:99], v[234:237]
	v_max3_f32 v170, v170, v57, v58
	v_max3_f32 v168, v168, v43, v44
	v_max3_f32 v170, v170, v59, v60
	v_max3_f32 v168, v168, v45, v46
	v_max3_f32 v170, v170, v61, v62
	v_max3_f32 v168, v168, v170, v47
	v_max_f32_e32 v168, v168, v63
	v_cmp_lt_f32_e32 vcc, 0x41000000, v168
	s_cbranch_vccz .Lamla_nors_12
	v_mov_b32_e32 v170, v168
	s_nop 1
	v_permlane32_swap_b32_e32 v168, v170
	v_max_f32_e32 v168, v168, v170
	v_max_f32_e32 v170, 0, v168
	v_exp_f32_e64 v166, -v170
	v_sub_f32_e32 v218, v218, v170
	v_sub_f32_e32 v219, v219, v170
	v_sub_f32_e32 v220, v220, v170
	v_sub_f32_e32 v221, v221, v170
	v_sub_f32_e32 v222, v222, v170
	v_sub_f32_e32 v223, v223, v170
	v_sub_f32_e32 v224, v224, v170
	v_sub_f32_e32 v225, v225, v170
	v_sub_f32_e32 v226, v226, v170
	v_sub_f32_e32 v227, v227, v170
	v_sub_f32_e32 v228, v228, v170
	v_sub_f32_e32 v229, v229, v170
	v_sub_f32_e32 v230, v230, v170
	v_sub_f32_e32 v231, v231, v170
	v_sub_f32_e32 v232, v232, v170
	v_sub_f32_e32 v233, v233, v170
	v_sub_f32_e32 v32, v32, v170
	v_sub_f32_e32 v33, v33, v170
	v_sub_f32_e32 v34, v34, v170
	v_sub_f32_e32 v35, v35, v170
	v_sub_f32_e32 v36, v36, v170
	v_sub_f32_e32 v37, v37, v170
	v_sub_f32_e32 v38, v38, v170
	v_sub_f32_e32 v39, v39, v170
	v_sub_f32_e32 v40, v40, v170
	v_sub_f32_e32 v41, v41, v170
	v_sub_f32_e32 v42, v42, v170
	v_sub_f32_e32 v43, v43, v170
	v_sub_f32_e32 v44, v44, v170
	v_sub_f32_e32 v45, v45, v170
	v_sub_f32_e32 v46, v46, v170
	v_sub_f32_e32 v47, v47, v170
	v_sub_f32_e32 v48, v48, v170
	v_sub_f32_e32 v49, v49, v170
	v_sub_f32_e32 v50, v50, v170
	v_sub_f32_e32 v51, v51, v170
	v_sub_f32_e32 v52, v52, v170
	v_sub_f32_e32 v53, v53, v170
	v_sub_f32_e32 v54, v54, v170
	v_sub_f32_e32 v55, v55, v170
	v_sub_f32_e32 v56, v56, v170
	v_sub_f32_e32 v57, v57, v170
	v_sub_f32_e32 v58, v58, v170
	v_sub_f32_e32 v59, v59, v170
	v_sub_f32_e32 v60, v60, v170
	v_sub_f32_e32 v61, v61, v170
	v_sub_f32_e32 v62, v62, v170
	v_sub_f32_e32 v63, v63, v170
	s_mov_b32 s9, 1
.Lamla_nors_12:
	s_waitcnt lgkmcnt(3)
	v_mfma_f32_32x32x16_bf16 v[64:79], v[136:139], v[112:115], v[218:233]
	v_exp_f32_e32 v32, v32
	v_exp_f32_e32 v48, v48
	ds_read_b128 v[136:139], v243 offset:13376
	ds_read_b64_tr_b16 v[192:193], v240 offset:15360
	ds_read_b64_tr_b16 v[194:195], v240 offset:16896
	s_waitcnt lgkmcnt(5)
	v_mfma_f32_32x32x16_bf16 v[80:95], v[140:143], v[112:115], v[218:233]
	v_exp_f32_e32 v33, v33
	v_exp_f32_e32 v49, v49
	ds_read_b128 v[140:143], v243 offset:20032
	ds_read_b64_tr_b16 v[196:197], v240 offset:15424
	ds_read_b64_tr_b16 v[198:199], v240 offset:16960
	v_mfma_f32_32x32x16_bf16 v[0:15], v[184:187], v[104:107], v[0:15]
	v_exp_f32_e32 v34, v34
	v_exp_f32_e32 v50, v50
	ds_read_b64_tr_b16 v[200:201], v240 offset:21504
	ds_read_b64_tr_b16 v[202:203], v240 offset:23040
	s_waitcnt lgkmcnt(9)
	v_mfma_f32_32x32x16_bf16 v[64:79], v[144:147], v[116:119], v[64:79]
	v_cvt_pk_bf16_f32 v96, v32, v33
	v_exp_f32_e32 v35, v35
	v_exp_f32_e32 v51, v51
	ds_read_b128 v[144:147], v243 offset:13408
	ds_read_b64_tr_b16 v[204:205], v240 offset:21568
	ds_read_b64_tr_b16 v[206:207], v240 offset:23104
	v_mfma_f32_32x32x16_bf16 v[16:31], v[188:191], v[104:107], v[16:31]
	v_exp_f32_e32 v36, v36
	v_exp_f32_e32 v52, v52
	s_waitcnt lgkmcnt(11)
	v_mfma_f32_32x32x16_bf16 v[80:95], v[148:151], v[116:119], v[80:95]
	v_cvt_pk_bf16_f32 v97, v34, v35
	v_exp_f32_e32 v37, v37
	ds_read_b128 v[148:151], v243 offset:20064
	v_mfma_f32_16x16x32_bf16 v[234:237], v[246:249], v[104:107], v[234:237]
	v_cvt_pk_bf16_f32 v104, v48, v49
	v_cvt_pk_bf16_f32 v105, v50, v51
	v_exp_f32_e32 v53, v53
	v_exp_f32_e32 v38, v38
	s_waitcnt lgkmcnt(11)
	v_mfma_f32_32x32x16_bf16 v[64:79], v[136:139], v[120:123], v[64:79]
	v_exp_f32_e32 v54, v54
	v_cvt_pk_bf16_f32 v98, v36, v37
	v_cvt_pk_bf16_f32 v106, v52, v53
	ds_read_b128 v[136:139], v243 offset:13440
	s_waitcnt lgkmcnt(9)
	v_mfma_f32_32x32x16_bf16 v[80:95], v[140:143], v[120:123], v[80:95]
	v_exp_f32_e32 v39, v39
	v_exp_f32_e32 v55, v55
	ds_read_b128 v[140:143], v243 offset:20096
	v_mfma_f32_32x32x16_bf16 v[0:15], v[192:195], v[100:103], v[0:15]
	v_exp_f32_e32 v40, v40
	v_exp_f32_e32 v56, v56
	v_cvt_pk_bf16_f32 v99, v38, v39
	s_waitcnt lgkmcnt(5)
	v_mfma_f32_32x32x16_bf16 v[64:79], v[144:147], v[124:127], v[64:79]
	v_cvt_pk_bf16_f32 v107, v54, v55
	v_exp_f32_e32 v41, v41
	v_exp_f32_e32 v57, v57
	ds_read_b128 v[144:147], v243 offset:13472
	v_mfma_f32_32x32x16_bf16 v[16:31], v[196:199], v[100:103], v[16:31]
	v_exp_f32_e32 v42, v42
	v_exp_f32_e32 v58, v58
	s_waitcnt vmcnt(0)
	ds_write_b128 v241, v[156:159] offset:36864
	s_waitcnt lgkmcnt(4)
	v_mfma_f32_32x32x16_bf16 v[80:95], v[148:151], v[124:127], v[80:95]
	v_exp_f32_e32 v43, v43
	v_exp_f32_e32 v59, v59
	ds_read_b128 v[148:151], v243 offset:20128
	v_mfma_f32_16x16x32_bf16 v[234:237], v[246:249], v[100:103], v[234:237]
	v_cvt_pk_bf16_f32 v100, v40, v41
	v_exp_f32_e32 v44, v44
	v_exp_f32_e32 v60, v60
	s_waitcnt lgkmcnt(4)
	v_mfma_f32_32x32x16_bf16 v[64:79], v[136:139], v[128:131], v[64:79]
	v_cvt_pk_bf16_f32 v101, v42, v43
	v_exp_f32_e32 v45, v45
	s_waitcnt lgkmcnt(3)
	v_mfma_f32_32x32x16_bf16 v[80:95], v[140:143], v[128:131], v[80:95]
	v_exp_f32_e32 v61, v61
	v_exp_f32_e32 v46, v46
	ds_read_b64_tr_b16 v[176:177], v240 offset:24576
	ds_read_b64_tr_b16 v[178:179], v240 offset:26112
	v_mfma_f32_32x32x16_bf16 v[0:15], v[200:203], v[108:111], v[0:15]
	v_exp_f32_e32 v62, v62
	v_cvt_pk_bf16_f32 v102, v44, v45
	v_exp_f32_e32 v47, v47
	ds_read_b64_tr_b16 v[180:181], v240 offset:24640
	ds_read_b64_tr_b16 v[182:183], v240 offset:26176
	s_waitcnt lgkmcnt(6)
	v_mfma_f32_32x32x16_bf16 v[64:79], v[144:147], v[132:135], v[64:79]
	v_exp_f32_e32 v63, v63
	v_cvt_pk_bf16_f32 v103, v46, v47
	ds_read_b64_tr_b16 v[184:185], v240 offset:30720
	ds_read_b64_tr_b16 v[186:187], v240 offset:32256
	v_mfma_f32_32x32x16_bf16 v[16:31], v[204:207], v[108:111], v[16:31]
	ds_read_b64_tr_b16 v[188:189], v240 offset:30784
	ds_read_b64_tr_b16 v[190:191], v240 offset:32320
	s_waitcnt lgkmcnt(8)
	v_mfma_f32_32x32x16_bf16 v[80:95], v[148:151], v[132:135], v[80:95]
	v_mfma_f32_16x16x32_bf16 v[234:237], v[246:249], v[108:111], v[234:237]
	v_cvt_pk_bf16_f32 v108, v56, v57
	v_cvt_pk_bf16_f32 v109, v58, v59
	v_cvt_pk_bf16_f32 v110, v60, v61
	v_cvt_pk_bf16_f32 v111, v62, v63
	s_cmp_lg_u32 s9, 0
	s_cbranch_scc0 .Lamla_noresc_13
	s_nop 15
	v_mul_f32_e32 v0, v0, v166
	v_mul_f32_e32 v1, v1, v166
	v_mul_f32_e32 v2, v2, v166
	v_mul_f32_e32 v3, v3, v166
	v_mul_f32_e32 v4, v4, v166
	v_mul_f32_e32 v5, v5, v166
	v_mul_f32_e32 v6, v6, v166
	v_mul_f32_e32 v7, v7, v166
	v_mul_f32_e32 v8, v8, v166
	v_mul_f32_e32 v9, v9, v166
	v_mul_f32_e32 v10, v10, v166
	v_mul_f32_e32 v11, v11, v166
	v_mul_f32_e32 v12, v12, v166
	v_mul_f32_e32 v13, v13, v166
	v_mul_f32_e32 v14, v14, v166
	v_mul_f32_e32 v15, v15, v166
	v_mul_f32_e32 v16, v16, v166
	v_mul_f32_e32 v17, v17, v166
	v_mul_f32_e32 v18, v18, v166
	v_mul_f32_e32 v19, v19, v166
	v_mul_f32_e32 v20, v20, v166
	v_mul_f32_e32 v21, v21, v166
	v_mul_f32_e32 v22, v22, v166
	v_mul_f32_e32 v23, v23, v166
	v_mul_f32_e32 v24, v24, v166
	v_mul_f32_e32 v25, v25, v166
	v_mul_f32_e32 v26, v26, v166
	v_mul_f32_e32 v27, v27, v166
	v_mul_f32_e32 v28, v28, v166
	v_mul_f32_e32 v29, v29, v166
	v_mul_f32_e32 v30, v30, v166
	v_mul_f32_e32 v31, v31, v166
	v_add_u32_e32 v170, 64, v175
	ds_bpermute_b32 v173, v170, v166
	v_mul_f32_e32 v234, v234, v166
	s_waitcnt lgkmcnt(0)
	v_mul_f32_e32 v235, v235, v173

; template <bool MLA>
; DI void attn_phase(const int TID, const int BID, LAS unsigned char* lds, const Params& p, bool need_ctx) {
;     ...
;         if (item < 1024) {
;             const int rnd = item >> 8, w = item & 255, xcd = w & 7, slot = w >> 3, qb = slot & 7;
;             if (MLA) { const int grp = (rnd * 8 + xcd) * 4 + (slot >> 3); b = grp >> 4; head = grp & 15; }
;             else { const int grp = rnd * 8 + xcd; b = grp >> 2; head = (grp & 3) * 4 + (slot >> 3); }
;             row0 = b * 2048 + qb * 256; nk = NKEY;
.Lamla_mainitem_next:
	s_lshr_b32 s21, s59, 8
	s_and_b32 s55, s59, 7
	s_lshl_b32 s21, s21, 3
	s_add_i32 s21, s21, s55
	s_bfe_u32 s55, s59, 0x30003
	s_bfe_u32 s56, s59, 0x20006
	s_lshl_b32 s21, s21, 2
	s_add_i32 s21, s21, s56
	s_lshr_b32 s15, s21, 4
	s_and_b32 s18, s21, 15
	s_lshl_b32 s20, s15, 11
	s_lshl_b32 s55, s55, 8
	s_add_i32 s20, s20, s55
	s_mov_b32 s7, 8

.Lamla_nonext:
	ds_read_b64_tr_b16 v[192:193], v240 offset:27648
	ds_read_b64_tr_b16 v[194:195], v240 offset:29184
	ds_read_b64_tr_b16 v[196:197], v240 offset:27712
	ds_read_b64_tr_b16 v[198:199], v240 offset:29248
	s_waitcnt lgkmcnt(10)
	v_mfma_f32_32x32x16_bf16 v[0:15], v[176:179], v[96:99], v[0:15]
	v_max3_f32 v168, v64, v65, v66
	v_max3_f32 v170, v80, v81, v82
	v_max3_f32 v168, v168, v67, v68
	v_max3_f32 v170, v170, v83, v84
	v_max3_f32 v168, v168, v69, v70
	v_max3_f32 v170, v170, v85, v86
	v_max3_f32 v168, v168, v71, v72
	v_max3_f32 v170, v170, v87, v88
	v_max3_f32 v168, v168, v73, v74
	s_mov_b32 s9, 0
	ds_read_b64_tr_b16 v[200:201], v240 offset:33792
	ds_read_b64_tr_b16 v[202:203], v240 offset:35328
	ds_read_b64_tr_b16 v[204:205], v240 offset:33856
	ds_read_b64_tr_b16 v[206:207], v240 offset:35392
	s_waitcnt lgkmcnt(12)
	v_mfma_f32_32x32x16_bf16 v[16:31], v[180:183], v[96:99], v[16:31]
	v_max3_f32 v170, v170, v89, v90
	v_max3_f32 v168, v168, v75, v76
	v_max3_f32 v170, v170, v91, v92
	v_max3_f32 v168, v168, v77, v78
	v_max3_f32 v170, v170, v93, v94
	v_max3_f32 v168, v168, v170, v79
	v_max_f32_e32 v168, v168, v95
	v_cmp_lt_f32_e32 vcc, 0x41000000, v168
	s_cbranch_vccz .Lamla_nors_14
	v_mov_b32_e32 v170, v168
	s_nop 1
	v_permlane32_swap_b32_e32 v168, v170
	v_max_f32_e32 v168, v168, v170
	v_max_f32_e32 v170, 0, v168
	v_exp_f32_e64 v166, -v170
	v_sub_f32_e32 v218, v218, v170
	v_sub_f32_e32 v219, v219, v170
	v_sub_f32_e32 v220, v220, v170
	v_sub_f32_e32 v221, v221, v170
	v_sub_f32_e32 v222, v222, v170
	v_sub_f32_e32 v223, v223, v170
	v_sub_f32_e32 v224, v224, v170
	v_sub_f32_e32 v225, v225, v170
	v_sub_f32_e32 v226, v226, v170
	v_sub_f32_e32 v227, v227, v170
	v_sub_f32_e32 v228, v228, v170
	v_sub_f32_e32 v229, v229, v170
	v_sub_f32_e32 v230, v230, v170
	v_sub_f32_e32 v231, v231, v170
	v_sub_f32_e32 v232, v232, v170
	v_sub_f32_e32 v233, v233, v170
	v_sub_f32_e32 v64, v64, v170
	v_sub_f32_e32 v65, v65, v170
	v_sub_f32_e32 v66, v66, v170
	v_sub_f32_e32 v67, v67, v170
	v_sub_f32_e32 v68, v68, v170
	v_sub_f32_e32 v69, v69, v170
	v_sub_f32_e32 v70, v70, v170
	v_sub_f32_e32 v71, v71, v170
	v_sub_f32_e32 v72, v72, v170
	v_sub_f32_e32 v73, v73, v170
	v_sub_f32_e32 v74, v74, v170
	v_sub_f32_e32 v75, v75, v170
	v_sub_f32_e32 v76, v76, v170
	v_sub_f32_e32 v77, v77, v170
	v_sub_f32_e32 v78, v78, v170
	v_sub_f32_e32 v79, v79, v170
	v_sub_f32_e32 v80, v80, v170
	v_sub_f32_e32 v81, v81, v170
	v_sub_f32_e32 v82, v82, v170
	v_sub_f32_e32 v83, v83, v170
	v_sub_f32_e32 v84, v84, v170
	v_sub_f32_e32 v85, v85, v170
	v_sub_f32_e32 v86, v86, v170
	v_sub_f32_e32 v87, v87, v170
	v_sub_f32_e32 v88, v88, v170
	v_sub_f32_e32 v89, v89, v170
	v_sub_f32_e32 v90, v90, v170
	v_sub_f32_e32 v91, v91, v170
	v_sub_f32_e32 v92, v92, v170
	v_sub_f32_e32 v93, v93, v170
	v_sub_f32_e32 v94, v94, v170
	v_sub_f32_e32 v95, v95, v170
	s_mov_b32 s9, 1
.Lamla_nors_14:
	v_mfma_f32_16x16x32_bf16 v[234:237], v[246:249], v[96:99], v[234:237]
	v_exp_f32_e32 v64, v64
	v_exp_f32_e32 v80, v80
	v_exp_f32_e32 v65, v65
	v_exp_f32_e32 v81, v81
	s_waitcnt lgkmcnt(10)
	v_mfma_f32_32x32x16_bf16 v[0:15], v[184:187], v[104:107], v[0:15]
	v_exp_f32_e32 v66, v66
	v_exp_f32_e32 v82, v82
	v_cvt_pk_bf16_f32 v96, v64, v65
	v_exp_f32_e32 v67, v67
	s_waitcnt lgkmcnt(8)
	v_mfma_f32_32x32x16_bf16 v[16:31], v[188:191], v[104:107], v[16:31]
	v_exp_f32_e32 v83, v83
	v_exp_f32_e32 v68, v68
	v_exp_f32_e32 v84, v84
	v_cvt_pk_bf16_f32 v97, v66, v67
	v_exp_f32_e32 v69, v69
	v_mfma_f32_16x16x32_bf16 v[234:237], v[246:249], v[104:107], v[234:237]
	v_cvt_pk_bf16_f32 v104, v80, v81
	v_cvt_pk_bf16_f32 v105, v82, v83
	v_exp_f32_e32 v85, v85
	v_exp_f32_e32 v70, v70
	v_exp_f32_e32 v86, v86
	v_cvt_pk_bf16_f32 v98, v68, v69
	s_waitcnt lgkmcnt(6)
	v_mfma_f32_32x32x16_bf16 v[0:15], v[192:195], v[100:103], v[0:15]
	v_cvt_pk_bf16_f32 v106, v84, v85
	v_exp_f32_e32 v71, v71
	v_exp_f32_e32 v87, v87
	v_exp_f32_e32 v72, v72
	v_exp_f32_e32 v88, v88
	ds_read_b64_tr_b16 v[176:177], v240 offset:36864
	ds_read_b64_tr_b16 v[178:179], v240 offset:38400
	s_waitcnt lgkmcnt(6)
	v_mfma_f32_32x32x16_bf16 v[16:31], v[196:199], v[100:103], v[16:31]
	v_cvt_pk_bf16_f32 v99, v70, v71
	v_cvt_pk_bf16_f32 v107, v86, v87
	v_exp_f32_e32 v73, v73
	v_exp_f32_e32 v89, v89
	v_exp_f32_e32 v74, v74
	ds_read_b64_tr_b16 v[180:181], v240 offset:36928
	ds_read_b64_tr_b16 v[182:183], v240 offset:38464
	v_mfma_f32_16x16x32_bf16 v[234:237], v[246:249], v[100:103], v[234:237]
	v_exp_f32_e32 v90, v90
	v_cvt_pk_bf16_f32 v100, v72, v73
	v_exp_f32_e32 v75, v75
	v_exp_f32_e32 v91, v91
	v_exp_f32_e32 v76, v76
	ds_read_b64_tr_b16 v[184:185], v240 offset:43008
	ds_read_b64_tr_b16 v[186:187], v240 offset:44544
	s_waitcnt lgkmcnt(8)
	v_mfma_f32_32x32x16_bf16 v[0:15], v[200:203], v[108:111], v[0:15]
	v_exp_f32_e32 v92, v92
	v_cvt_pk_bf16_f32 v101, v74, v75
	v_exp_f32_e32 v77, v77
	v_exp_f32_e32 v93, v93
	ds_read_b64_tr_b16 v[188:189], v240 offset:43072
	ds_read_b64_tr_b16 v[190:191], v240 offset:44608
	s_waitcnt lgkmcnt(8)
	v_mfma_f32_32x32x16_bf16 v[16:31], v[204:207], v[108:111], v[16:31]
	v_exp_f32_e32 v78, v78
	v_exp_f32_e32 v94, v94
	v_cvt_pk_bf16_f32 v102, v76, v77
	v_exp_f32_e32 v79, v79
	v_exp_f32_e32 v95, v95
	v_mfma_f32_16x16x32_bf16 v[234:237], v[246:249], v[108:111], v[234:237]
	v_cvt_pk_bf16_f32 v108, v88, v89
	v_cvt_pk_bf16_f32 v109, v90, v91
	v_cvt_pk_bf16_f32 v110, v92, v93
	v_cvt_pk_bf16_f32 v103, v78, v79
	v_cvt_pk_bf16_f32 v111, v94, v95
	s_cmp_lg_u32 s9, 0
	s_cbranch_scc0 .Lamla_noresc_15
	s_nop 15
	v_mul_f32_e32 v0, v0, v166
	v_mul_f32_e32 v1, v1, v166
	v_mul_f32_e32 v2, v2, v166
	v_mul_f32_e32 v3, v3, v166
	v_mul_f32_e32 v4, v4, v166
	v_mul_f32_e32 v5, v5, v166
	v_mul_f32_e32 v6, v6, v166
	v_mul_f32_e32 v7, v7, v166
	v_mul_f32_e32 v8, v8, v166
	v_mul_f32_e32 v9, v9, v166
	v_mul_f32_e32 v10, v10, v166
	v_mul_f32_e32 v11, v11, v166
	v_mul_f32_e32 v12, v12, v166
	v_mul_f32_e32 v13, v13, v166
	v_mul_f32_e32 v14, v14, v166
	v_mul_f32_e32 v15, v15, v166
	v_mul_f32_e32 v16, v16, v166
	v_mul_f32_e32 v17, v17, v166
	v_mul_f32_e32 v18, v18, v166
	v_mul_f32_e32 v19, v19, v166
	v_mul_f32_e32 v20, v20, v166
	v_mul_f32_e32 v21, v21, v166
	v_mul_f32_e32 v22, v22, v166
	v_mul_f32_e32 v23, v23, v166
	v_mul_f32_e32 v24, v24, v166
	v_mul_f32_e32 v25, v25, v166
	v_mul_f32_e32 v26, v26, v166
	v_mul_f32_e32 v27, v27, v166
	v_mul_f32_e32 v28, v28, v166
	v_mul_f32_e32 v29, v29, v166
	v_mul_f32_e32 v30, v30, v166
	v_mul_f32_e32 v31, v31, v166
	v_add_u32_e32 v170, 64, v175
	ds_bpermute_b32 v173, v170, v166
	v_mul_f32_e32 v234, v234, v166
	s_waitcnt lgkmcnt(0)
	v_mul_f32_e32 v235, v235, v173
; #define AT_PK4(OX, jg) u32x2 { pk_bf16(OX[4 * (jg)] * inv, OX[4 * (jg) + 1] * inv), pk_bf16(OX[4 * (jg) + 2] * inv, OX[4 * (jg) + 3] * inv) }
; template <bool MLA>
; DI void attn_phase(const int TID, const int BID, LAS unsigned char* lds, const Params& p, bool need_ctx) {
;     ...
;         __builtin_amdgcn_s_setprio(0);
;         lsum = xsum32(lsum);
;         const float inv = 1.f / lsum;
;         bf16_t* op = O + (size_t)(row0 + wid * 32 + r) * 1024 + head * 64 + 8 * hh;
;     ...
; #pragma unroll
;         for (int k = 0; k < 2; ++k) {
;             const u32x2 a = AT_PK4(o0, 2 * k), b2 = AT_PK4(o0, 2 * k + 1), c = AT_PK4(o1, 2 * k), d = AT_PK4(o1, 2 * k + 1);
;             const u32x2 s0 = __builtin_amdgcn_permlane32_swap(a[0], b2[0], false, false), s1 = __builtin_amdgcn_permlane32_swap(a[1], b2[1], false, false);
;             const u32x2 t0 = __builtin_amdgcn_permlane32_swap(c[0], d[0], false, false), t1 = __builtin_amdgcn_permlane32_swap(c[1], d[1], false, false);
;             const u32x4 w0 = {s0[0], s1[0], s0[1], s1[1]}, w1 = {t0[0], t1[0], t0[1], t1[1]};
;             *(u32x4*)(op + 16 * k) = w0; *(u32x4*)(op + 32 + 16 * k) = w1;
;         }
.Lamla_noresc_15:
	s_barrier
	ds_read_b64_tr_b16 v[192:193], v240 offset:39936
	ds_read_b64_tr_b16 v[194:195], v240 offset:41472
	ds_read_b64_tr_b16 v[196:197], v240 offset:40000
	ds_read_b64_tr_b16 v[198:199], v240 offset:41536
	s_waitcnt lgkmcnt(10)
	v_mfma_f32_32x32x16_bf16 v[0:15], v[176:179], v[96:99], v[0:15]
	ds_read_b64_tr_b16 v[200:201], v240 offset:46080
	ds_read_b64_tr_b16 v[202:203], v240 offset:47616
	ds_read_b64_tr_b16 v[204:205], v240 offset:46144
	ds_read_b64_tr_b16 v[206:207], v240 offset:47680
	s_waitcnt lgkmcnt(12)
	v_mfma_f32_32x32x16_bf16 v[16:31], v[180:183], v[96:99], v[16:31]
	v_mfma_f32_16x16x32_bf16 v[234:237], v[246:249], v[96:99], v[234:237]
	s_waitcnt lgkmcnt(10)
	v_mfma_f32_32x32x16_bf16 v[0:15], v[184:187], v[104:107], v[0:15]
	s_waitcnt lgkmcnt(8)
	v_mfma_f32_32x32x16_bf16 v[16:31], v[188:191], v[104:107], v[16:31]
	v_mfma_f32_16x16x32_bf16 v[234:237], v[246:249], v[104:107], v[234:237]
	s_waitcnt lgkmcnt(6)
	v_mfma_f32_32x32x16_bf16 v[0:15], v[192:195], v[100:103], v[0:15]
	s_waitcnt lgkmcnt(4)
	v_mfma_f32_32x32x16_bf16 v[16:31], v[196:199], v[100:103], v[16:31]
	v_mfma_f32_16x16x32_bf16 v[234:237], v[246:249], v[100:103], v[234:237]
	s_waitcnt lgkmcnt(2)
	v_mfma_f32_32x32x16_bf16 v[0:15], v[200:203], v[108:111], v[0:15]
	s_waitcnt lgkmcnt(0)
	v_mfma_f32_32x32x16_bf16 v[16:31], v[204:207], v[108:111], v[16:31]
	v_mfma_f32_16x16x32_bf16 v[234:237], v[246:249], v[108:111], v[234:237]
	s_setprio 0
	s_nop 11
	ds_bpermute_b32 v173, v175, v234
	ds_bpermute_b32 v217, v175, v235
	s_mov_b32 s60, 0xffff0000
	s_mov_b32 s61, 0xffff0000
	s_waitcnt lgkmcnt(0)
	v_cndmask_b32_e64 v234, v173, v217, s[60:61]
	v_div_scale_f32 v148, s[60:61], v234, v234, 1.0
	v_rcp_f32_e32 v149, v148
	s_nop 0
	v_fma_f32 v150, -v148, v149, 1.0
	v_fmac_f32_e32 v149, v150, v149
	v_div_scale_f32 v150, vcc, 1.0, v234, 1.0
	v_mul_f32_e32 v151, v150, v149
	v_fma_f32 v173, -v148, v151, v150
	v_fmac_f32_e32 v151, v173, v149
	v_fma_f32 v148, -v148, v151, v150
	s_nop 1
	v_div_fmas_f32 v148, v148, v149, v151
	v_div_fixup_f32 v212, v148, v234, 1.0
	v_pk_mul_f32 v[0:1], v[0:1], v[212:213] op_sel_hi:[1,0]
	v_pk_mul_f32 v[2:3], v[2:3], v[212:213] op_sel_hi:[1,0]
	v_pk_mul_f32 v[4:5], v[4:5], v[212:213] op_sel_hi:[1,0]
	v_pk_mul_f32 v[6:7], v[6:7], v[212:213] op_sel_hi:[1,0]
	v_pk_mul_f32 v[8:9], v[8:9], v[212:213] op_sel_hi:[1,0]
	v_pk_mul_f32 v[10:11], v[10:11], v[212:213] op_sel_hi:[1,0]
	v_pk_mul_f32 v[12:13], v[12:13], v[212:213] op_sel_hi:[1,0]
	v_pk_mul_f32 v[14:15], v[14:15], v[212:213] op_sel_hi:[1,0]
	v_pk_mul_f32 v[16:17], v[16:17], v[212:213] op_sel_hi:[1,0]
	v_pk_mul_f32 v[18:19], v[18:19], v[212:213] op_sel_hi:[1,0]
	v_pk_mul_f32 v[20:21], v[20:21], v[212:213] op_sel_hi:[1,0]
	v_pk_mul_f32 v[22:23], v[22:23], v[212:213] op_sel_hi:[1,0]
	v_pk_mul_f32 v[24:25], v[24:25], v[212:213] op_sel_hi:[1,0]
	v_pk_mul_f32 v[26:27], v[26:27], v[212:213] op_sel_hi:[1,0]
	v_pk_mul_f32 v[28:29], v[28:29], v[212:213] op_sel_hi:[1,0]
	v_pk_mul_f32 v[30:31], v[30:31], v[212:213] op_sel_hi:[1,0]
	v_cvt_pk_bf16_f32 v96, v0, v1
	v_cvt_pk_bf16_f32 v97, v2, v3
	v_cvt_pk_bf16_f32 v98, v4, v5
	v_cvt_pk_bf16_f32 v99, v6, v7
	v_cvt_pk_bf16_f32 v100, v16, v17
	v_cvt_pk_bf16_f32 v101, v18, v19
	v_cvt_pk_bf16_f32 v102, v20, v21
	v_cvt_pk_bf16_f32 v103, v22, v23
	v_cvt_pk_bf16_f32 v104, v8, v9
	v_cvt_pk_bf16_f32 v105, v10, v11
	v_cvt_pk_bf16_f32 v106, v12, v13
	v_cvt_pk_bf16_f32 v107, v14, v15
	v_cvt_pk_bf16_f32 v108, v24, v25
	v_cvt_pk_bf16_f32 v109, v26, v27
	v_cvt_pk_bf16_f32 v110, v28, v29
	v_cvt_pk_bf16_f32 v111, v30, v31
	s_nop 1
	v_permlane32_swap_b32_e32 v96, v98
	v_permlane32_swap_b32_e32 v97, v99
	v_permlane32_swap_b32_e32 v100, v102
	v_permlane32_swap_b32_e32 v101, v103
	v_permlane32_swap_b32_e32 v104, v106
	v_permlane32_swap_b32_e32 v105, v107
	v_permlane32_swap_b32_e32 v108, v110
	v_permlane32_swap_b32_e32 v109, v111
	global_store_dwordx4 v172, v[96:99], s[16:17]
	global_store_dwordx4 v172, v[100:103], s[16:17] offset:64
	global_store_dwordx4 v172, v[104:107], s[16:17] offset:32
	global_store_dwordx4 v172, v[108:111], s[16:17] offset:96
	s_mov_b32 s6, s59
	s_mov_b64 s[16:17], s[62:63]
	s_cmp_ge_i32 s6, s8
	s_cbranch_scc0 .Lamla_item
.Lamla_done:
	s_branch .LBB0_317
.Lisland_774:
	s_branch .LBB0_774

; template <bool MLA>
; DI void attn_phase(const int TID, const int BID, LAS unsigned char* lds, const Params& p, bool need_ctx) {
;     ...
;         if (item < 1024) {
;             const int rnd = item >> 8, w = item & 255, xcd = w & 7, slot = w >> 3, qb = slot & 7;
;             if (MLA) { const int grp = (rnd * 8 + xcd) * 4 + (slot >> 3); b = grp >> 4; head = grp & 15; }
;             else { const int grp = rnd * 8 + xcd; b = grp >> 2; head = (grp & 3) * 4 + (slot >> 3); }
;             row0 = b * 2048 + qb * 256; nk = NKEY;
.Lagqa_mainitem_first:
	s_lshr_b32 s21, s6, 8
	s_and_b32 s55, s6, 7
	s_lshl_b32 s21, s21, 3
	s_add_i32 s21, s21, s55
	s_bfe_u32 s55, s6, 0x30003
	s_bfe_u32 s56, s6, 0x20006
	s_lshr_b32 s15, s21, 2
	s_and_b32 s57, s21, 3
	s_lshl_b32 s18, s57, 2
	s_add_i32 s18, s18, s56
	s_lshl_b32 s20, s15, 11
	s_lshl_b32 s55, s55, 8
	s_add_i32 s20, s20, s55
	s_mov_b32 s7, 8

.Lagqa_prio:
	ds_read_b128 v[136:139], v243 offset:0
	ds_read_b128 v[140:143], v243 offset:4608
	ds_read_b128 v[144:147], v243 offset:32
	ds_read_b128 v[148:151], v243 offset:4640
	s_waitcnt lgkmcnt(3)
	v_mfma_f32_32x32x16_bf16 v[32:47], v[136:139], v[112:115], 0
	ds_read_b128 v[136:139], v243 offset:64
	s_waitcnt lgkmcnt(3)
	v_mfma_f32_32x32x16_bf16 v[48:63], v[140:143], v[112:115], 0
	ds_read_b128 v[140:143], v243 offset:4672
	s_waitcnt lgkmcnt(3)
	v_mfma_f32_32x32x16_bf16 v[32:47], v[144:147], v[116:119], v[32:47]
	ds_read_b128 v[144:147], v243 offset:96
	s_waitcnt lgkmcnt(3)
	v_mfma_f32_32x32x16_bf16 v[48:63], v[148:151], v[116:119], v[48:63]
	ds_read_b128 v[148:151], v243 offset:4704
	s_waitcnt lgkmcnt(3)
	v_mfma_f32_32x32x16_bf16 v[32:47], v[136:139], v[120:123], v[32:47]
	s_waitcnt lgkmcnt(2)
	v_mfma_f32_32x32x16_bf16 v[48:63], v[140:143], v[120:123], v[48:63]
	s_waitcnt lgkmcnt(1)
	v_mfma_f32_32x32x16_bf16 v[32:47], v[144:147], v[124:127], v[32:47]
	s_waitcnt lgkmcnt(0)
	v_mfma_f32_32x32x16_bf16 v[48:63], v[148:151], v[124:127], v[48:63]
	s_waitcnt lgkmcnt(0)
	s_nop 7
	s_barrier
	ds_read_b128 v[136:139], v243 offset:9216
	ds_read_b128 v[140:143], v243 offset:13824
	ds_read_b128 v[144:147], v243 offset:9248
	ds_read_b128 v[148:151], v243 offset:13856
	v_max3_f32 v168, v32, v33, v34
	v_max3_f32 v170, v48, v49, v50
	v_max3_f32 v168, v168, v35, v36
	v_max3_f32 v170, v170, v51, v52
	v_max3_f32 v168, v168, v37, v38
	v_max3_f32 v170, v170, v53, v54
	v_max3_f32 v168, v168, v39, v40
	v_max3_f32 v170, v170, v55, v56
	v_max3_f32 v168, v168, v41, v42
	v_max3_f32 v170, v170, v57, v58
	v_max3_f32 v168, v168, v43, v44
	v_max3_f32 v170, v170, v59, v60
	v_max3_f32 v168, v168, v45, v46
	v_max3_f32 v170, v170, v61, v62
	v_max3_f32 v168, v168, v170, v47
	v_max_f32_e32 v168, v168, v63
	v_mov_b32_e32 v170, v168
	s_nop 1
	v_permlane32_swap_b32_e32 v168, v170
	v_max_f32_e32 v168, v168, v170
	v_mov_b32_e32 v170, v168
	v_sub_f32_e32 v218, v218, v170
	v_sub_f32_e32 v219, v219, v170
	v_sub_f32_e32 v220, v220, v170
	v_sub_f32_e32 v221, v221, v170
	v_sub_f32_e32 v222, v222, v170
	v_sub_f32_e32 v223, v223, v170
	v_sub_f32_e32 v224, v224, v170
	v_sub_f32_e32 v225, v225, v170
	v_sub_f32_e32 v226, v226, v170
	v_sub_f32_e32 v227, v227, v170
	v_sub_f32_e32 v228, v228, v170
	v_sub_f32_e32 v229, v229, v170
	v_sub_f32_e32 v230, v230, v170
	v_sub_f32_e32 v231, v231, v170
	v_sub_f32_e32 v232, v232, v170
	v_sub_f32_e32 v233, v233, v170
	v_sub_f32_e32 v32, v32, v170
	v_sub_f32_e32 v33, v33, v170
	v_sub_f32_e32 v34, v34, v170
	v_sub_f32_e32 v35, v35, v170
	v_sub_f32_e32 v36, v36, v170
	v_sub_f32_e32 v37, v37, v170
	v_sub_f32_e32 v38, v38, v170
	v_sub_f32_e32 v39, v39, v170
	v_sub_f32_e32 v40, v40, v170
	v_sub_f32_e32 v41, v41, v170
	v_sub_f32_e32 v42, v42, v170
	v_sub_f32_e32 v43, v43, v170
	v_sub_f32_e32 v44, v44, v170
	v_sub_f32_e32 v45, v45, v170
	v_sub_f32_e32 v46, v46, v170
	v_sub_f32_e32 v47, v47, v170
	v_sub_f32_e32 v48, v48, v170
	v_sub_f32_e32 v49, v49, v170
	v_sub_f32_e32 v50, v50, v170
	v_sub_f32_e32 v51, v51, v170
	v_sub_f32_e32 v52, v52, v170
	v_sub_f32_e32 v53, v53, v170
	v_sub_f32_e32 v54, v54, v170
	v_sub_f32_e32 v55, v55, v170
	v_sub_f32_e32 v56, v56, v170
	v_sub_f32_e32 v57, v57, v170
	v_sub_f32_e32 v58, v58, v170
	v_sub_f32_e32 v59, v59, v170
	v_sub_f32_e32 v60, v60, v170
	v_sub_f32_e32 v61, v61, v170
	v_sub_f32_e32 v62, v62, v170
	v_sub_f32_e32 v63, v63, v170
	s_waitcnt lgkmcnt(3)
	v_mfma_f32_32x32x16_bf16 v[64:79], v[136:139], v[112:115], v[218:233]
	v_exp_f32_e32 v32, v32
	v_exp_f32_e32 v48, v48
	v_exp_f32_e32 v33, v33
	v_exp_f32_e32 v49, v49
	v_exp_f32_e32 v34, v34
	v_exp_f32_e32 v50, v50
	v_cvt_pk_bf16_f32 v96, v32, v33
	ds_read_b128 v[136:139], v243 offset:9280
	s_mov_b32 s9, 0
	s_waitcnt lgkmcnt(3)
	v_mfma_f32_32x32x16_bf16 v[80:95], v[140:143], v[112:115], v[218:233]
	v_cvt_pk_bf16_f32 v104, v48, v49
	v_exp_f32_e32 v35, v35
	v_exp_f32_e32 v51, v51
	v_exp_f32_e32 v36, v36
	v_exp_f32_e32 v52, v52
	v_cvt_pk_bf16_f32 v97, v34, v35
	v_cvt_pk_bf16_f32 v105, v50, v51
	v_exp_f32_e32 v37, v37
	ds_read_b128 v[140:143], v243 offset:13888
	global_load_dwordx4 v[208:211], v167, s[2:3]
	global_load_dwordx4 v[212:215], v167, s[4:5]
	s_add_u32 s2, s2, 0x2000
	s_addc_u32 s3, s3, 0
	s_add_u32 s4, s4, 0x2000
	s_addc_u32 s5, s5, 0
	s_waitcnt lgkmcnt(3)
	v_mfma_f32_32x32x16_bf16 v[64:79], v[144:147], v[116:119], v[64:79]
	v_exp_f32_e32 v53, v53
	v_exp_f32_e32 v38, v38
	v_exp_f32_e32 v54, v54
	v_cvt_pk_bf16_f32 v98, v36, v37
	v_cvt_pk_bf16_f32 v106, v52, v53
	v_exp_f32_e32 v39, v39
	v_exp_f32_e32 v55, v55
	ds_read_b128 v[144:147], v243 offset:9312
	ds_read_b64_tr_b16 v[176:177], v240 offset:0
	ds_read_b64_tr_b16 v[178:179], v240 offset:1536
	s_waitcnt lgkmcnt(5)
	v_mfma_f32_32x32x16_bf16 v[80:95], v[148:151], v[116:119], v[80:95]
	v_exp_f32_e32 v40, v40
	v_exp_f32_e32 v56, v56
	v_cvt_pk_bf16_f32 v99, v38, v39
	v_cvt_pk_bf16_f32 v107, v54, v55
	v_exp_f32_e32 v41, v41
	v_exp_f32_e32 v57, v57
	v_exp_f32_e32 v42, v42
	ds_read_b128 v[148:151], v243 offset:13920
	ds_read_b64_tr_b16 v[180:181], v240 offset:64
	ds_read_b64_tr_b16 v[182:183], v240 offset:1600
	s_waitcnt lgkmcnt(7)
	v_mfma_f32_32x32x16_bf16 v[64:79], v[136:139], v[120:123], v[64:79]
	v_exp_f32_e32 v58, v58
	v_cvt_pk_bf16_f32 v100, v40, v41
	v_cvt_pk_bf16_f32 v108, v56, v57
	v_exp_f32_e32 v43, v43
	v_exp_f32_e32 v59, v59
	v_exp_f32_e32 v44, v44
	v_exp_f32_e32 v60, v60
	ds_read_b64_tr_b16 v[184:185], v240 offset:6144
	ds_read_b64_tr_b16 v[186:187], v240 offset:7680
	s_waitcnt vmcnt(3)
	ds_write_b128 v238, v[152:155]
	s_waitcnt vmcnt(2)
	ds_write_b128 v241, v[156:159] offset:12288
	s_waitcnt lgkmcnt(10)
	v_mfma_f32_32x32x16_bf16 v[80:95], v[140:143], v[120:123], v[80:95]
	v_cvt_pk_bf16_f32 v101, v42, v43
	v_cvt_pk_bf16_f32 v109, v58, v59
	v_exp_f32_e32 v45, v45
	v_exp_f32_e32 v61, v61
	v_exp_f32_e32 v46, v46
	v_exp_f32_e32 v62, v62
	v_cvt_pk_bf16_f32 v102, v44, v45
	v_cvt_pk_bf16_f32 v110, v60, v61
	ds_read_b64_tr_b16 v[188:189], v240 offset:6208
	ds_read_b64_tr_b16 v[190:191], v240 offset:7744
	s_waitcnt lgkmcnt(11)
	v_mfma_f32_32x32x16_bf16 v[64:79], v[144:147], v[124:127], v[64:79]
	v_exp_f32_e32 v47, v47
	v_exp_f32_e32 v63, v63
	v_cvt_pk_bf16_f32 v103, v46, v47
	v_cvt_pk_bf16_f32 v111, v62, v63
	s_waitcnt lgkmcnt(8)
	v_mfma_f32_32x32x16_bf16 v[80:95], v[148:151], v[124:127], v[80:95]
	s_nop 13
	s_waitcnt lgkmcnt(2)
	s_waitcnt lgkmcnt(0)
	s_barrier
	s_cmp_eq_u32 s7, 0
	s_cbranch_scc1 .Lagqa_tail
.Lagqa_loop:
	ds_read_b128 v[136:139], v243 offset:0
	ds_read_b128 v[140:143], v243 offset:4608
	ds_read_b128 v[144:147], v243 offset:32
	ds_read_b128 v[148:151], v243 offset:4640
	s_waitcnt lgkmcnt(10)
	v_mfma_f32_32x32x16_bf16 v[0:15], v[176:179], v[96:99], v[0:15]
	v_max3_f32 v168, v64, v65, v66
	v_max3_f32 v170, v80, v81, v82
	v_max3_f32 v168, v168, v67, v68
	v_max3_f32 v170, v170, v83, v84
	v_max3_f32 v168, v168, v69, v70
	s_mov_b32 s9, 0
	s_waitcnt lgkmcnt(8)
	v_mfma_f32_32x32x16_bf16 v[16:31], v[180:183], v[96:99], v[16:31]
	v_max3_f32 v170, v170, v85, v86
	v_max3_f32 v168, v168, v71, v72
	v_max3_f32 v170, v170, v87, v88
	v_max3_f32 v168, v168, v73, v74
	v_max3_f32 v170, v170, v89, v90
	global_load_dwordx4 v[152:155], v167, s[2:3]
	global_load_dwordx4 v[156:159], v167, s[4:5]
	s_add_u32 s2, s2, 0x2000
	s_addc_u32 s3, s3, 0
	s_add_u32 s4, s4, 0x2000
	s_addc_u32 s5, s5, 0
	v_mfma_f32_16x16x32_bf16 v[234:237], v[246:249], v[96:99], v[234:237]
	v_max3_f32 v168, v168, v75, v76
	v_max3_f32 v170, v170, v91, v92
	v_max3_f32 v168, v168, v77, v78
	v_max3_f32 v170, v170, v93, v94
	v_max3_f32 v168, v168, v170, v79
	v_max_f32_e32 v168, v168, v95
	v_cmp_lt_f32_e32 vcc, 0x41000000, v168
	s_cbranch_vccz .Lagqa_nors_2
	v_mov_b32_e32 v170, v168
	s_nop 1
	v_permlane32_swap_b32_e32 v168, v170
	v_max_f32_e32 v168, v168, v170
	v_max_f32_e32 v170, 0, v168
	v_exp_f32_e64 v166, -v170
	v_sub_f32_e32 v218, v218, v170
	v_sub_f32_e32 v219, v219, v170
	v_sub_f32_e32 v220, v220, v170
	v_sub_f32_e32 v221, v221, v170
	v_sub_f32_e32 v222, v222, v170
	v_sub_f32_e32 v223, v223, v170
	v_sub_f32_e32 v224, v224, v170
	v_sub_f32_e32 v225, v225, v170
	v_sub_f32_e32 v226, v226, v170
	v_sub_f32_e32 v227, v227, v170
	v_sub_f32_e32 v228, v228, v170
	v_sub_f32_e32 v229, v229, v170
	v_sub_f32_e32 v230, v230, v170
	v_sub_f32_e32 v231, v231, v170
	v_sub_f32_e32 v232, v232, v170
	v_sub_f32_e32 v233, v233, v170
	v_sub_f32_e32 v64, v64, v170
	v_sub_f32_e32 v65, v65, v170
	v_sub_f32_e32 v66, v66, v170
	v_sub_f32_e32 v67, v67, v170
	v_sub_f32_e32 v68, v68, v170
	v_sub_f32_e32 v69, v69, v170
	v_sub_f32_e32 v70, v70, v170
	v_sub_f32_e32 v71, v71, v170
	v_sub_f32_e32 v72, v72, v170
	v_sub_f32_e32 v73, v73, v170
	v_sub_f32_e32 v74, v74, v170
	v_sub_f32_e32 v75, v75, v170
	v_sub_f32_e32 v76, v76, v170
	v_sub_f32_e32 v77, v77, v170
	v_sub_f32_e32 v78, v78, v170
	v_sub_f32_e32 v79, v79, v170
	v_sub_f32_e32 v80, v80, v170
	v_sub_f32_e32 v81, v81, v170
	v_sub_f32_e32 v82, v82, v170
	v_sub_f32_e32 v83, v83, v170
	v_sub_f32_e32 v84, v84, v170
	v_sub_f32_e32 v85, v85, v170
	v_sub_f32_e32 v86, v86, v170
	v_sub_f32_e32 v87, v87, v170
	v_sub_f32_e32 v88, v88, v170
	v_sub_f32_e32 v89, v89, v170
	v_sub_f32_e32 v90, v90, v170
	v_sub_f32_e32 v91, v91, v170
	v_sub_f32_e32 v92, v92, v170
	v_sub_f32_e32 v93, v93, v170
	v_sub_f32_e32 v94, v94, v170
	v_sub_f32_e32 v95, v95, v170
	s_mov_b32 s9, 1
.Lagqa_nors_2:
	s_waitcnt lgkmcnt(3)
	v_mfma_f32_32x32x16_bf16 v[32:47], v[136:139], v[112:115], v[218:233]
	v_exp_f32_e32 v64, v64
	v_exp_f32_e32 v80, v80
	v_exp_f32_e32 v65, v65
	ds_read_b128 v[136:139], v243 offset:64
	ds_read_b64_tr_b16 v[192:193], v240 offset:3072
	ds_read_b64_tr_b16 v[194:195], v240 offset:4608
	v_mfma_f32_32x32x16_bf16 v[0:15], v[184:187], v[104:107], v[0:15]
	v_exp_f32_e32 v81, v81
	v_exp_f32_e32 v66, v66
	ds_read_b64_tr_b16 v[196:197], v240 offset:3136
	ds_read_b64_tr_b16 v[198:199], v240 offset:4672
	s_waitcnt lgkmcnt(7)
	v_mfma_f32_32x32x16_bf16 v[48:63], v[140:143], v[112:115], v[218:233]
	v_exp_f32_e32 v82, v82
	v_cvt_pk_bf16_f32 v96, v64, v65
	v_exp_f32_e32 v67, v67
	ds_read_b128 v[140:143], v243 offset:4672
	ds_read_b64_tr_b16 v[200:201], v240 offset:9216
	ds_read_b64_tr_b16 v[202:203], v240 offset:10752
	v_mfma_f32_32x32x16_bf16 v[16:31], v[188:191], v[104:107], v[16:31]
	v_exp_f32_e32 v83, v83
	v_exp_f32_e32 v68, v68
	v_exp_f32_e32 v84, v84
	ds_read_b64_tr_b16 v[204:205], v240 offset:9280
	ds_read_b64_tr_b16 v[206:207], v240 offset:10816
	s_waitcnt lgkmcnt(11)
	v_mfma_f32_32x32x16_bf16 v[32:47], v[144:147], v[116:119], v[32:47]
	v_cvt_pk_bf16_f32 v97, v66, v67
	v_exp_f32_e32 v69, v69
	v_exp_f32_e32 v85, v85
	ds_read_b128 v[144:147], v243 offset:96
	v_mfma_f32_16x16x32_bf16 v[234:237], v[246:249], v[104:107], v[234:237]
	v_cvt_pk_bf16_f32 v104, v80, v81
	v_cvt_pk_bf16_f32 v105, v82, v83
	v_exp_f32_e32 v70, v70
	v_exp_f32_e32 v86, v86
	s_waitcnt lgkmcnt(11)
	v_mfma_f32_32x32x16_bf16 v[48:63], v[148:151], v[116:119], v[48:63]
	v_cvt_pk_bf16_f32 v98, v68, v69
	v_cvt_pk_bf16_f32 v106, v84, v85
	v_exp_f32_e32 v71, v71
	v_exp_f32_e32 v87, v87
	ds_read_b128 v[148:151], v243 offset:4704
	s_waitcnt lgkmcnt(9)
	v_mfma_f32_32x32x16_bf16 v[0:15], v[192:195], v[100:103], v[0:15]
	v_exp_f32_e32 v72, v72
	v_exp_f32_e32 v88, v88
	v_mfma_f32_32x32x16_bf16 v[32:47], v[136:139], v[120:123], v[32:47]
	v_cvt_pk_bf16_f32 v99, v70, v71
	v_cvt_pk_bf16_f32 v107, v86, v87
	v_exp_f32_e32 v73, v73
	s_waitcnt vmcnt(3)
	ds_write_b128 v238, v[208:211] offset:9216
	s_waitcnt vmcnt(2)
	ds_write_b128 v241, v[212:215] offset:24576
	s_waitcnt lgkmcnt(9)
	v_mfma_f32_32x32x16_bf16 v[16:31], v[196:199], v[100:103], v[16:31]
	v_exp_f32_e32 v89, v89
	v_exp_f32_e32 v74, v74
	v_exp_f32_e32 v90, v90
	s_waitcnt lgkmcnt(8)
	v_mfma_f32_32x32x16_bf16 v[48:63], v[140:143], v[120:123], v[48:63]
	v_exp_f32_e32 v75, v75
	v_exp_f32_e32 v91, v91
	v_mfma_f32_16x16x32_bf16 v[234:237], v[246:249], v[100:103], v[234:237]
	v_cvt_pk_bf16_f32 v100, v72, v73
	v_exp_f32_e32 v76, v76
	v_exp_f32_e32 v92, v92
	v_cvt_pk_bf16_f32 v101, v74, v75
	ds_read_b64_tr_b16 v[176:177], v240 offset:12288
	ds_read_b64_tr_b16 v[178:179], v240 offset:13824
	s_waitcnt lgkmcnt(5)
	v_mfma_f32_32x32x16_bf16 v[32:47], v[144:147], v[124:127], v[32:47]
	v_exp_f32_e32 v77, v77
	v_exp_f32_e32 v93, v93
	v_exp_f32_e32 v78, v78
	ds_read_b64_tr_b16 v[180:181], v240 offset:12352
	ds_read_b64_tr_b16 v[182:183], v240 offset:13888
	v_mfma_f32_32x32x16_bf16 v[0:15], v[200:203], v[108:111], v[0:15]
	v_exp_f32_e32 v94, v94
	v_cvt_pk_bf16_f32 v102, v76, v77
	v_exp_f32_e32 v79, v79
	ds_read_b64_tr_b16 v[184:185], v240 offset:18432
	ds_read_b64_tr_b16 v[186:187], v240 offset:19968
	s_waitcnt lgkmcnt(8)
	v_mfma_f32_32x32x16_bf16 v[48:63], v[148:151], v[124:127], v[48:63]
	v_exp_f32_e32 v95, v95
	v_cvt_pk_bf16_f32 v103, v78, v79
	ds_read_b64_tr_b16 v[188:189], v240 offset:18496
	ds_read_b64_tr_b16 v[190:191], v240 offset:20032
	v_mfma_f32_32x32x16_bf16 v[16:31], v[204:207], v[108:111], v[16:31]
	v_mfma_f32_16x16x32_bf16 v[234:237], v[246:249], v[108:111], v[234:237]
	v_cvt_pk_bf16_f32 v108, v88, v89
	v_cvt_pk_bf16_f32 v109, v90, v91
	v_cvt_pk_bf16_f32 v110, v92, v93
	v_cvt_pk_bf16_f32 v111, v94, v95
	s_cmp_lg_u32 s9, 0
	s_cbranch_scc0 .Lagqa_noresc_3
	s_nop 15
	v_mul_f32_e32 v0, v0, v166
	v_mul_f32_e32 v1, v1, v166
	v_mul_f32_e32 v2, v2, v166
	v_mul_f32_e32 v3, v3, v166
	v_mul_f32_e32 v4, v4, v166
	v_mul_f32_e32 v5, v5, v166
	v_mul_f32_e32 v6, v6, v166
	v_mul_f32_e32 v7, v7, v166
	v_mul_f32_e32 v8, v8, v166
	v_mul_f32_e32 v9, v9, v166
	v_mul_f32_e32 v10, v10, v166
	v_mul_f32_e32 v11, v11, v166
	v_mul_f32_e32 v12, v12, v166
	v_mul_f32_e32 v13, v13, v166
	v_mul_f32_e32 v14, v14, v166
	v_mul_f32_e32 v15, v15, v166
	v_mul_f32_e32 v16, v16, v166
	v_mul_f32_e32 v17, v17, v166
	v_mul_f32_e32 v18, v18, v166
	v_mul_f32_e32 v19, v19, v166
	v_mul_f32_e32 v20, v20, v166
	v_mul_f32_e32 v21, v21, v166
	v_mul_f32_e32 v22, v22, v166
	v_mul_f32_e32 v23, v23, v166
	v_mul_f32_e32 v24, v24, v166
	v_mul_f32_e32 v25, v25, v166
	v_mul_f32_e32 v26, v26, v166
	v_mul_f32_e32 v27, v27, v166
	v_mul_f32_e32 v28, v28, v166
	v_mul_f32_e32 v29, v29, v166
	v_mul_f32_e32 v30, v30, v166
	v_mul_f32_e32 v31, v31, v166
	v_add_u32_e32 v170, 64, v175
	ds_bpermute_b32 v173, v170, v166
	v_mul_f32_e32 v234, v234, v166
	s_waitcnt lgkmcnt(0)
	v_mul_f32_e32 v235, v235, v173
.Lagqa_noresc_3:
	s_nop 1
	s_waitcnt lgkmcnt(8)
	s_barrier
	ds_read_b128 v[136:139], v243 offset:9216
	ds_read_b128 v[140:143], v243 offset:13824
	ds_read_b128 v[144:147], v243 offset:9248
	ds_read_b128 v[148:151], v243 offset:13856
	s_waitcnt lgkmcnt(10)
	v_mfma_f32_32x32x16_bf16 v[0:15], v[176:179], v[96:99], v[0:15]
	v_max3_f32 v168, v32, v33, v34
	v_max3_f32 v170, v48, v49, v50
	v_max3_f32 v168, v168, v35, v36
	v_max3_f32 v170, v170, v51, v52
	v_max3_f32 v168, v168, v37, v38
	s_mov_b32 s9, 0
	s_waitcnt lgkmcnt(8)
	v_mfma_f32_32x32x16_bf16 v[16:31], v[180:183], v[96:99], v[16:31]
	v_max3_f32 v170, v170, v53, v54
	v_max3_f32 v168, v168, v39, v40
	v_max3_f32 v170, v170, v55, v56
	v_max3_f32 v168, v168, v41, v42
	v_max3_f32 v170, v170, v57, v58
	global_load_dwordx4 v[208:211], v167, s[2:3]
	global_load_dwordx4 v[212:215], v167, s[4:5]
	s_add_u32 s2, s2, 0x2000
	s_addc_u32 s3, s3, 0
	s_add_u32 s4, s4, 0x2000
	s_addc_u32 s5, s5, 0
	v_mfma_f32_16x16x32_bf16 v[234:237], v[246:249], v[96:99], v[234:237]
	v_max3_f32 v168, v168, v43, v44
	v_max3_f32 v170, v170, v59, v60
	v_max3_f32 v168, v168, v45, v46
	v_max3_f32 v170, v170, v61, v62
	v_max3_f32 v168, v168, v170, v47
	v_max_f32_e32 v168, v168, v63
	v_cmp_lt_f32_e32 vcc, 0x41000000, v168
	s_cbranch_vccz .Lagqa_nors_4
	v_mov_b32_e32 v170, v168
	s_nop 1
	v_permlane32_swap_b32_e32 v168, v170
	v_max_f32_e32 v168, v168, v170
	v_max_f32_e32 v170, 0, v168
	v_exp_f32_e64 v166, -v170
	v_sub_f32_e32 v218, v218, v170
	v_sub_f32_e32 v219, v219, v170
	v_sub_f32_e32 v220, v220, v170
	v_sub_f32_e32 v221, v221, v170
	v_sub_f32_e32 v222, v222, v170
	v_sub_f32_e32 v223, v223, v170
	v_sub_f32_e32 v224, v224, v170
	v_sub_f32_e32 v225, v225, v170
	v_sub_f32_e32 v226, v226, v170
	v_sub_f32_e32 v227, v227, v170
	v_sub_f32_e32 v228, v228, v170
	v_sub_f32_e32 v229, v229, v170
	v_sub_f32_e32 v230, v230, v170
	v_sub_f32_e32 v231, v231, v170
	v_sub_f32_e32 v232, v232, v170
	v_sub_f32_e32 v233, v233, v170
	v_sub_f32_e32 v32, v32, v170
	v_sub_f32_e32 v33, v33, v170
	v_sub_f32_e32 v34, v34, v170
	v_sub_f32_e32 v35, v35, v170
	v_sub_f32_e32 v36, v36, v170
	v_sub_f32_e32 v37, v37, v170
	v_sub_f32_e32 v38, v38, v170
	v_sub_f32_e32 v39, v39, v170
	v_sub_f32_e32 v40, v40, v170
	v_sub_f32_e32 v41, v41, v170
	v_sub_f32_e32 v42, v42, v170
	v_sub_f32_e32 v43, v43, v170
	v_sub_f32_e32 v44, v44, v170
	v_sub_f32_e32 v45, v45, v170
	v_sub_f32_e32 v46, v46, v170
	v_sub_f32_e32 v47, v47, v170
	v_sub_f32_e32 v48, v48, v170
	v_sub_f32_e32 v49, v49, v170
	v_sub_f32_e32 v50, v50, v170
	v_sub_f32_e32 v51, v51, v170
	v_sub_f32_e32 v52, v52, v170
	v_sub_f32_e32 v53, v53, v170
	v_sub_f32_e32 v54, v54, v170
	v_sub_f32_e32 v55, v55, v170
	v_sub_f32_e32 v56, v56, v170
	v_sub_f32_e32 v57, v57, v170
	v_sub_f32_e32 v58, v58, v170
	v_sub_f32_e32 v59, v59, v170
	v_sub_f32_e32 v60, v60, v170
	v_sub_f32_e32 v61, v61, v170
	v_sub_f32_e32 v62, v62, v170
	v_sub_f32_e32 v63, v63, v170
	s_mov_b32 s9, 1
.Lagqa_nors_4:
	s_waitcnt lgkmcnt(3)
	v_mfma_f32_32x32x16_bf16 v[64:79], v[136:139], v[112:115], v[218:233]
	v_exp_f32_e32 v32, v32
	v_exp_f32_e32 v48, v48
	v_exp_f32_e32 v33, v33
	ds_read_b128 v[136:139], v243 offset:9280
	ds_read_b64_tr_b16 v[192:193], v240 offset:15360
	ds_read_b64_tr_b16 v[194:195], v240 offset:16896
	v_mfma_f32_32x32x16_bf16 v[0:15], v[184:187], v[104:107], v[0:15]
	v_exp_f32_e32 v49, v49
	v_exp_f32_e32 v34, v34
	ds_read_b64_tr_b16 v[196:197], v240 offset:15424
	ds_read_b64_tr_b16 v[198:199], v240 offset:16960
	s_waitcnt lgkmcnt(7)
	v_mfma_f32_32x32x16_bf16 v[80:95], v[140:143], v[112:115], v[218:233]
	v_exp_f32_e32 v50, v50
	v_cvt_pk_bf16_f32 v96, v32, v33
	v_exp_f32_e32 v35, v35
	ds_read_b128 v[140:143], v243 offset:13888
	ds_read_b64_tr_b16 v[200:201], v240 offset:21504
	ds_read_b64_tr_b16 v[202:203], v240 offset:23040
	v_mfma_f32_32x32x16_bf16 v[16:31], v[188:191], v[104:107], v[16:31]
	v_exp_f32_e32 v51, v51
	v_exp_f32_e32 v36, v36
	v_exp_f32_e32 v52, v52
	ds_read_b64_tr_b16 v[204:205], v240 offset:21568
	ds_read_b64_tr_b16 v[206:207], v240 offset:23104
	s_waitcnt lgkmcnt(11)
	v_mfma_f32_32x32x16_bf16 v[64:79], v[144:147], v[116:119], v[64:79]
	v_cvt_pk_bf16_f32 v97, v34, v35
	v_exp_f32_e32 v37, v37
	v_exp_f32_e32 v53, v53
	ds_read_b128 v[144:147], v243 offset:9312
	v_mfma_f32_16x16x32_bf16 v[234:237], v[246:249], v[104:107], v[234:237]
	v_cvt_pk_bf16_f32 v104, v48, v49
	v_cvt_pk_bf16_f32 v105, v50, v51
	v_exp_f32_e32 v38, v38
	v_exp_f32_e32 v54, v54
	s_waitcnt lgkmcnt(11)
; #define AT_STEP(SC0, SC1, SN0, SN1, t, DOK, DOV) do { \
;             if (DOK) AT_GLOADK(((t) + 2) * 64); \
;             if (DOV) { AT_GLOADV(((t) + 1) * 64); AT_QK(SN0, SN1, ((t) + 1) & 1); } \
;             AT_SMPV(SC0, SC1, (t) & 1); \
;             if (DOK) AT_WRITEK((t) & 1); \
;             if (DOV) AT_WRITEV(((t) + 1) & 1); \
;             __syncthreads(); } while (0)
; template <bool MLA>
; DI void attn_phase(const int TID, const int BID, LAS unsigned char* lds, const Params& p, bool need_ctx) {
;     ...
;         for (; t < ntile - 2; t += 2) {
;             AT_STEP(sa0, sa1, sb0, sb1, t, true, true);
;             AT_STEP(sb0, sb1, sa0, sa1, t + 1, true, true);
;         }
	v_mfma_f32_32x32x16_bf16 v[80:95], v[148:151], v[116:119], v[80:95]
	v_cvt_pk_bf16_f32 v98, v36, v37
	v_cvt_pk_bf16_f32 v106, v52, v53
	v_exp_f32_e32 v39, v39
	v_exp_f32_e32 v55, v55
	ds_read_b128 v[148:151], v243 offset:13920
	s_waitcnt lgkmcnt(9)
	v_mfma_f32_32x32x16_bf16 v[0:15], v[192:195], v[100:103], v[0:15]
	v_exp_f32_e32 v40, v40
	v_exp_f32_e32 v56, v56
	v_mfma_f32_32x32x16_bf16 v[64:79], v[136:139], v[120:123], v[64:79]
	v_cvt_pk_bf16_f32 v99, v38, v39
	v_cvt_pk_bf16_f32 v107, v54, v55
	v_exp_f32_e32 v41, v41
	s_waitcnt vmcnt(3)
	ds_write_b128 v238, v[152:155]
	s_waitcnt vmcnt(2)
	ds_write_b128 v241, v[156:159] offset:36864
	s_waitcnt lgkmcnt(9)
	v_mfma_f32_32x32x16_bf16 v[16:31], v[196:199], v[100:103], v[16:31]
	v_exp_f32_e32 v57, v57
	v_exp_f32_e32 v42, v42
	v_exp_f32_e32 v58, v58
	s_waitcnt lgkmcnt(8)
	v_mfma_f32_32x32x16_bf16 v[80:95], v[140:143], v[120:123], v[80:95]
	v_exp_f32_e32 v43, v43
	v_exp_f32_e32 v59, v59
	v_mfma_f32_16x16x32_bf16 v[234:237], v[246:249], v[100:103], v[234:237]
	v_cvt_pk_bf16_f32 v100, v40, v41
	v_exp_f32_e32 v44, v44
	v_exp_f32_e32 v60, v60
	v_cvt_pk_bf16_f32 v101, v42, v43
	ds_read_b64_tr_b16 v[176:177], v240 offset:24576
	ds_read_b64_tr_b16 v[178:179], v240 offset:26112
	s_waitcnt lgkmcnt(5)
	v_mfma_f32_32x32x16_bf16 v[64:79], v[144:147], v[124:127], v[64:79]
	v_exp_f32_e32 v45, v45
	v_exp_f32_e32 v61, v61
	v_exp_f32_e32 v46, v46
	ds_read_b64_tr_b16 v[180:181], v240 offset:24640
	ds_read_b64_tr_b16 v[182:183], v240 offset:26176
	v_mfma_f32_32x32x16_bf16 v[0:15], v[200:203], v[108:111], v[0:15]
	v_exp_f32_e32 v62, v62
	v_cvt_pk_bf16_f32 v102, v44, v45
	v_exp_f32_e32 v47, v47
	ds_read_b64_tr_b16 v[184:185], v240 offset:30720
	ds_read_b64_tr_b16 v[186:187], v240 offset:32256
	s_waitcnt lgkmcnt(8)
	v_mfma_f32_32x32x16_bf16 v[80:95], v[148:151], v[124:127], v[80:95]
	v_exp_f32_e32 v63, v63
	v_cvt_pk_bf16_f32 v103, v46, v47
	ds_read_b64_tr_b16 v[188:189], v240 offset:30784
	ds_read_b64_tr_b16 v[190:191], v240 offset:32320
	v_mfma_f32_32x32x16_bf16 v[16:31], v[204:207], v[108:111], v[16:31]
	v_mfma_f32_16x16x32_bf16 v[234:237], v[246:249], v[108:111], v[234:237]
	v_cvt_pk_bf16_f32 v108, v56, v57
	v_cvt_pk_bf16_f32 v109, v58, v59
	v_cvt_pk_bf16_f32 v110, v60, v61
	v_cvt_pk_bf16_f32 v111, v62, v63
	s_cmp_lg_u32 s9, 0
	s_cbranch_scc0 .Lagqa_noresc_5
	s_nop 15
	v_mul_f32_e32 v0, v0, v166
	v_mul_f32_e32 v1, v1, v166
	v_mul_f32_e32 v2, v2, v166
	v_mul_f32_e32 v3, v3, v166
	v_mul_f32_e32 v4, v4, v166
	v_mul_f32_e32 v5, v5, v166
	v_mul_f32_e32 v6, v6, v166
	v_mul_f32_e32 v7, v7, v166
	v_mul_f32_e32 v8, v8, v166
	v_mul_f32_e32 v9, v9, v166
	v_mul_f32_e32 v10, v10, v166
	v_mul_f32_e32 v11, v11, v166
	v_mul_f32_e32 v12, v12, v166
	v_mul_f32_e32 v13, v13, v166
	v_mul_f32_e32 v14, v14, v166
	v_mul_f32_e32 v15, v15, v166
	v_mul_f32_e32 v16, v16, v166
	v_mul_f32_e32 v17, v17, v166
	v_mul_f32_e32 v18, v18, v166
	v_mul_f32_e32 v19, v19, v166
	v_mul_f32_e32 v20, v20, v166
	v_mul_f32_e32 v21, v21, v166
	v_mul_f32_e32 v22, v22, v166
	v_mul_f32_e32 v23, v23, v166
	v_mul_f32_e32 v24, v24, v166
	v_mul_f32_e32 v25, v25, v166
	v_mul_f32_e32 v26, v26, v166
	v_mul_f32_e32 v27, v27, v166
	v_mul_f32_e32 v28, v28, v166
	v_mul_f32_e32 v29, v29, v166
	v_mul_f32_e32 v30, v30, v166
	v_mul_f32_e32 v31, v31, v166
	v_add_u32_e32 v170, 64, v175
	ds_bpermute_b32 v173, v170, v166
	v_mul_f32_e32 v234, v234, v166
	s_waitcnt lgkmcnt(0)
	v_mul_f32_e32 v235, v235, v173
.Lagqa_noresc_5:
	s_nop 1
	s_waitcnt lgkmcnt(8)
	s_barrier
	ds_read_b128 v[136:139], v243 offset:0
	ds_read_b128 v[140:143], v243 offset:4608
	ds_read_b128 v[144:147], v243 offset:32
	ds_read_b128 v[148:151], v243 offset:4640
	s_waitcnt lgkmcnt(10)
	v_mfma_f32_32x32x16_bf16 v[0:15], v[176:179], v[96:99], v[0:15]
	v_max3_f32 v168, v64, v65, v66
	v_max3_f32 v170, v80, v81, v82
	v_max3_f32 v168, v168, v67, v68
	v_max3_f32 v170, v170, v83, v84
	v_max3_f32 v168, v168, v69, v70
	s_mov_b32 s9, 0
	s_waitcnt lgkmcnt(8)
	v_mfma_f32_32x32x16_bf16 v[16:31], v[180:183], v[96:99], v[16:31]
	v_max3_f32 v170, v170, v85, v86
	v_max3_f32 v168, v168, v71, v72
	v_max3_f32 v170, v170, v87, v88
	v_max3_f32 v168, v168, v73, v74
	v_max3_f32 v170, v170, v89, v90
	global_load_dwordx4 v[152:155], v167, s[2:3]
	global_load_dwordx4 v[156:159], v167, s[4:5]
	s_add_u32 s2, s2, 0x2000
	s_addc_u32 s3, s3, 0
	s_add_u32 s4, s4, 0x2000
	s_addc_u32 s5, s5, 0
	v_mfma_f32_16x16x32_bf16 v[234:237], v[246:249], v[96:99], v[234:237]
	v_max3_f32 v168, v168, v75, v76
	v_max3_f32 v170, v170, v91, v92
	v_max3_f32 v168, v168, v77, v78
	v_max3_f32 v170, v170, v93, v94
	v_max3_f32 v168, v168, v170, v79
	v_max_f32_e32 v168, v168, v95
	v_cmp_lt_f32_e32 vcc, 0x41000000, v168
	s_cbranch_vccz .Lagqa_nors_6
	v_mov_b32_e32 v170, v168
	s_nop 1
	v_permlane32_swap_b32_e32 v168, v170
	v_max_f32_e32 v168, v168, v170
	v_max_f32_e32 v170, 0, v168
	v_exp_f32_e64 v166, -v170
	v_sub_f32_e32 v218, v218, v170
	v_sub_f32_e32 v219, v219, v170
	v_sub_f32_e32 v220, v220, v170
	v_sub_f32_e32 v221, v221, v170
	v_sub_f32_e32 v222, v222, v170
	v_sub_f32_e32 v223, v223, v170
	v_sub_f32_e32 v224, v224, v170
	v_sub_f32_e32 v225, v225, v170
	v_sub_f32_e32 v226, v226, v170
	v_sub_f32_e32 v227, v227, v170
	v_sub_f32_e32 v228, v228, v170
	v_sub_f32_e32 v229, v229, v170
	v_sub_f32_e32 v230, v230, v170
	v_sub_f32_e32 v231, v231, v170
	v_sub_f32_e32 v232, v232, v170
	v_sub_f32_e32 v233, v233, v170
	v_sub_f32_e32 v64, v64, v170
	v_sub_f32_e32 v65, v65, v170
	v_sub_f32_e32 v66, v66, v170
	v_sub_f32_e32 v67, v67, v170
	v_sub_f32_e32 v68, v68, v170
	v_sub_f32_e32 v69, v69, v170
	v_sub_f32_e32 v70, v70, v170
	v_sub_f32_e32 v71, v71, v170
	v_sub_f32_e32 v72, v72, v170
	v_sub_f32_e32 v73, v73, v170
	v_sub_f32_e32 v74, v74, v170
	v_sub_f32_e32 v75, v75, v170
	v_sub_f32_e32 v76, v76, v170
	v_sub_f32_e32 v77, v77, v170
	v_sub_f32_e32 v78, v78, v170
	v_sub_f32_e32 v79, v79, v170
	v_sub_f32_e32 v80, v80, v170
	v_sub_f32_e32 v81, v81, v170
	v_sub_f32_e32 v82, v82, v170
	v_sub_f32_e32 v83, v83, v170
	v_sub_f32_e32 v84, v84, v170
	v_sub_f32_e32 v85, v85, v170
	v_sub_f32_e32 v86, v86, v170
	v_sub_f32_e32 v87, v87, v170
	v_sub_f32_e32 v88, v88, v170
	v_sub_f32_e32 v89, v89, v170
	v_sub_f32_e32 v90, v90, v170
	v_sub_f32_e32 v91, v91, v170
	v_sub_f32_e32 v92, v92, v170
	v_sub_f32_e32 v93, v93, v170
	v_sub_f32_e32 v94, v94, v170
	v_sub_f32_e32 v95, v95, v170
	s_mov_b32 s9, 1
.Lagqa_nors_6:
	s_waitcnt lgkmcnt(3)
	v_mfma_f32_32x32x16_bf16 v[32:47], v[136:139], v[112:115], v[218:233]
	v_exp_f32_e32 v64, v64
	v_exp_f32_e32 v80, v80
	v_exp_f32_e32 v65, v65
	ds_read_b128 v[136:139], v243 offset:64
	ds_read_b64_tr_b16 v[192:193], v240 offset:27648
	ds_read_b64_tr_b16 v[194:195], v240 offset:29184
	v_mfma_f32_32x32x16_bf16 v[0:15], v[184:187], v[104:107], v[0:15]
	v_exp_f32_e32 v81, v81
	v_exp_f32_e32 v66, v66
	ds_read_b64_tr_b16 v[196:197], v240 offset:27712
	ds_read_b64_tr_b16 v[198:199], v240 offset:29248
	s_waitcnt lgkmcnt(7)
	v_mfma_f32_32x32x16_bf16 v[48:63], v[140:143], v[112:115], v[218:233]
	v_exp_f32_e32 v82, v82
	v_cvt_pk_bf16_f32 v96, v64, v65
	v_exp_f32_e32 v67, v67
	ds_read_b128 v[140:143], v243 offset:4672
	ds_read_b64_tr_b16 v[200:201], v240 offset:33792
	ds_read_b64_tr_b16 v[202:203], v240 offset:35328
	v_mfma_f32_32x32x16_bf16 v[16:31], v[188:191], v[104:107], v[16:31]
	v_exp_f32_e32 v83, v83
	v_exp_f32_e32 v68, v68
	v_exp_f32_e32 v84, v84
	ds_read_b64_tr_b16 v[204:205], v240 offset:33856
	ds_read_b64_tr_b16 v[206:207], v240 offset:35392
	s_waitcnt lgkmcnt(11)
	v_mfma_f32_32x32x16_bf16 v[32:47], v[144:147], v[116:119], v[32:47]
	v_cvt_pk_bf16_f32 v97, v66, v67
	v_exp_f32_e32 v69, v69
	v_exp_f32_e32 v85, v85
	ds_read_b128 v[144:147], v243 offset:96
	v_mfma_f32_16x16x32_bf16 v[234:237], v[246:249], v[104:107], v[234:237]
	v_cvt_pk_bf16_f32 v104, v80, v81
	v_cvt_pk_bf16_f32 v105, v82, v83
	v_exp_f32_e32 v70, v70
	v_exp_f32_e32 v86, v86
	s_waitcnt lgkmcnt(11)
	v_mfma_f32_32x32x16_bf16 v[48:63], v[148:151], v[116:119], v[48:63]
	v_cvt_pk_bf16_f32 v98, v68, v69
	v_cvt_pk_bf16_f32 v106, v84, v85
	v_exp_f32_e32 v71, v71
	v_exp_f32_e32 v87, v87
	ds_read_b128 v[148:151], v243 offset:4704
	s_waitcnt lgkmcnt(9)
	v_mfma_f32_32x32x16_bf16 v[0:15], v[192:195], v[100:103], v[0:15]
	v_exp_f32_e32 v72, v72
	v_exp_f32_e32 v88, v88
	v_mfma_f32_32x32x16_bf16 v[32:47], v[136:139], v[120:123], v[32:47]
	v_cvt_pk_bf16_f32 v99, v70, v71
	v_cvt_pk_bf16_f32 v107, v86, v87
	v_exp_f32_e32 v73, v73
	s_waitcnt vmcnt(3)
	ds_write_b128 v238, v[208:211] offset:9216
	s_waitcnt vmcnt(2)
	ds_write_b128 v241, v[212:215]
	s_waitcnt lgkmcnt(9)
	v_mfma_f32_32x32x16_bf16 v[16:31], v[196:199], v[100:103], v[16:31]
	v_exp_f32_e32 v89, v89
	v_exp_f32_e32 v74, v74
	v_exp_f32_e32 v90, v90
	s_waitcnt lgkmcnt(8)
	v_mfma_f32_32x32x16_bf16 v[48:63], v[140:143], v[120:123], v[48:63]
	v_exp_f32_e32 v75, v75
	v_exp_f32_e32 v91, v91
	v_mfma_f32_16x16x32_bf16 v[234:237], v[246:249], v[100:103], v[234:237]
	v_cvt_pk_bf16_f32 v100, v72, v73
	v_exp_f32_e32 v76, v76
	v_exp_f32_e32 v92, v92
	v_cvt_pk_bf16_f32 v101, v74, v75
	ds_read_b64_tr_b16 v[176:177], v240 offset:36864
	ds_read_b64_tr_b16 v[178:179], v240 offset:38400
	s_waitcnt lgkmcnt(5)
	v_mfma_f32_32x32x16_bf16 v[32:47], v[144:147], v[124:127], v[32:47]
	v_exp_f32_e32 v77, v77
	v_exp_f32_e32 v93, v93
	v_exp_f32_e32 v78, v78
	ds_read_b64_tr_b16 v[180:181], v240 offset:36928
	ds_read_b64_tr_b16 v[182:183], v240 offset:38464
	v_mfma_f32_32x32x16_bf16 v[0:15], v[200:203], v[108:111], v[0:15]
	v_exp_f32_e32 v94, v94
	v_cvt_pk_bf16_f32 v102, v76, v77
	v_exp_f32_e32 v79, v79
	ds_read_b64_tr_b16 v[184:185], v240 offset:43008
	ds_read_b64_tr_b16 v[186:187], v240 offset:44544
	s_waitcnt lgkmcnt(8)
	v_mfma_f32_32x32x16_bf16 v[48:63], v[148:151], v[124:127], v[48:63]
	v_exp_f32_e32 v95, v95
	v_cvt_pk_bf16_f32 v103, v78, v79
	ds_read_b64_tr_b16 v[188:189], v240 offset:43072
	ds_read_b64_tr_b16 v[190:191], v240 offset:44608
	v_mfma_f32_32x32x16_bf16 v[16:31], v[204:207], v[108:111], v[16:31]
	v_mfma_f32_16x16x32_bf16 v[234:237], v[246:249], v[108:111], v[234:237]
	v_cvt_pk_bf16_f32 v108, v88, v89
	v_cvt_pk_bf16_f32 v109, v90, v91
	v_cvt_pk_bf16_f32 v110, v92, v93
	v_cvt_pk_bf16_f32 v111, v94, v95
	s_cmp_lg_u32 s9, 0
	s_cbranch_scc0 .Lagqa_noresc_7
	s_nop 15
	v_mul_f32_e32 v0, v0, v166
	v_mul_f32_e32 v1, v1, v166
	v_mul_f32_e32 v2, v2, v166
	v_mul_f32_e32 v3, v3, v166
	v_mul_f32_e32 v4, v4, v166
	v_mul_f32_e32 v5, v5, v166
	v_mul_f32_e32 v6, v6, v166
	v_mul_f32_e32 v7, v7, v166
	v_mul_f32_e32 v8, v8, v166
	v_mul_f32_e32 v9, v9, v166
	v_mul_f32_e32 v10, v10, v166
	v_mul_f32_e32 v11, v11, v166
	v_mul_f32_e32 v12, v12, v166
	v_mul_f32_e32 v13, v13, v166
	v_mul_f32_e32 v14, v14, v166
	v_mul_f32_e32 v15, v15, v166
	v_mul_f32_e32 v16, v16, v166
	v_mul_f32_e32 v17, v17, v166
	v_mul_f32_e32 v18, v18, v166
	v_mul_f32_e32 v19, v19, v166
	v_mul_f32_e32 v20, v20, v166
	v_mul_f32_e32 v21, v21, v166
	v_mul_f32_e32 v22, v22, v166
	v_mul_f32_e32 v23, v23, v166
	v_mul_f32_e32 v24, v24, v166
	v_mul_f32_e32 v25, v25, v166
	v_mul_f32_e32 v26, v26, v166
	v_mul_f32_e32 v27, v27, v166
	v_mul_f32_e32 v28, v28, v166
	v_mul_f32_e32 v29, v29, v166
	v_mul_f32_e32 v30, v30, v166
	v_mul_f32_e32 v31, v31, v166
	v_add_u32_e32 v170, 64, v175
	ds_bpermute_b32 v173, v170, v166
	v_mul_f32_e32 v234, v234, v166
	s_waitcnt lgkmcnt(0)
	v_mul_f32_e32 v235, v235, v173

; #define AT_STEP(SC0, SC1, SN0, SN1, t, DOK, DOV) do { \
;             if (DOK) AT_GLOADK(((t) + 2) * 64); \
;             if (DOV) { AT_GLOADV(((t) + 1) * 64); AT_QK(SN0, SN1, ((t) + 1) & 1); } \
;             AT_SMPV(SC0, SC1, (t) & 1); \
;             if (DOK) AT_WRITEK((t) & 1); \
;             if (DOV) AT_WRITEV(((t) + 1) & 1); \
;             __syncthreads(); } while (0)
; template <bool MLA>
; DI void attn_phase(const int TID, const int BID, LAS unsigned char* lds, const Params& p, bool need_ctx) {
;     ...
;         for (; t < ntile - 2; t += 2) {
;             AT_STEP(sa0, sa1, sb0, sb1, t, true, true);
;             AT_STEP(sb0, sb1, sa0, sa1, t + 1, true, true);
;         }
.Lagqa_nors_8:
	s_waitcnt lgkmcnt(3)
	v_mfma_f32_32x32x16_bf16 v[64:79], v[136:139], v[112:115], v[218:233]
	v_exp_f32_e32 v32, v32
	v_exp_f32_e32 v48, v48
	v_exp_f32_e32 v33, v33
	ds_read_b128 v[136:139], v243 offset:9280
	ds_read_b64_tr_b16 v[192:193], v240 offset:39936
	ds_read_b64_tr_b16 v[194:195], v240 offset:41472
	v_mfma_f32_32x32x16_bf16 v[0:15], v[184:187], v[104:107], v[0:15]
	v_exp_f32_e32 v49, v49
	v_exp_f32_e32 v34, v34
	ds_read_b64_tr_b16 v[196:197], v240 offset:40000
	ds_read_b64_tr_b16 v[198:199], v240 offset:41536
	s_waitcnt lgkmcnt(7)
	v_mfma_f32_32x32x16_bf16 v[80:95], v[140:143], v[112:115], v[218:233]
	v_exp_f32_e32 v50, v50
	v_cvt_pk_bf16_f32 v96, v32, v33
	v_exp_f32_e32 v35, v35
	ds_read_b128 v[140:143], v243 offset:13888
	ds_read_b64_tr_b16 v[200:201], v240 offset:46080
	ds_read_b64_tr_b16 v[202:203], v240 offset:47616
	v_mfma_f32_32x32x16_bf16 v[16:31], v[188:191], v[104:107], v[16:31]
	v_exp_f32_e32 v51, v51
	v_exp_f32_e32 v36, v36
	v_exp_f32_e32 v52, v52
	ds_read_b64_tr_b16 v[204:205], v240 offset:46144
	ds_read_b64_tr_b16 v[206:207], v240 offset:47680
	s_waitcnt lgkmcnt(11)
	v_mfma_f32_32x32x16_bf16 v[64:79], v[144:147], v[116:119], v[64:79]
	v_cvt_pk_bf16_f32 v97, v34, v35
	v_exp_f32_e32 v37, v37
	v_exp_f32_e32 v53, v53
	ds_read_b128 v[144:147], v243 offset:9312
	v_mfma_f32_16x16x32_bf16 v[234:237], v[246:249], v[104:107], v[234:237]
	v_cvt_pk_bf16_f32 v104, v48, v49
	v_cvt_pk_bf16_f32 v105, v50, v51
	v_exp_f32_e32 v38, v38
	v_exp_f32_e32 v54, v54
	s_waitcnt lgkmcnt(11)
	v_mfma_f32_32x32x16_bf16 v[80:95], v[148:151], v[116:119], v[80:95]
	v_cvt_pk_bf16_f32 v98, v36, v37
	v_cvt_pk_bf16_f32 v106, v52, v53
	v_exp_f32_e32 v39, v39
	v_exp_f32_e32 v55, v55
	ds_read_b128 v[148:151], v243 offset:13920
	s_waitcnt lgkmcnt(9)
	v_mfma_f32_32x32x16_bf16 v[0:15], v[192:195], v[100:103], v[0:15]
	v_exp_f32_e32 v40, v40
	v_exp_f32_e32 v56, v56
	v_mfma_f32_32x32x16_bf16 v[64:79], v[136:139], v[120:123], v[64:79]
	v_cvt_pk_bf16_f32 v99, v38, v39
	v_cvt_pk_bf16_f32 v107, v54, v55
	v_exp_f32_e32 v41, v41
	s_waitcnt vmcnt(3)
	ds_write_b128 v238, v[152:155]
	s_waitcnt vmcnt(2)
	ds_write_b128 v241, v[156:159] offset:12288
	s_waitcnt lgkmcnt(9)
	v_mfma_f32_32x32x16_bf16 v[16:31], v[196:199], v[100:103], v[16:31]
	v_exp_f32_e32 v57, v57
	v_exp_f32_e32 v42, v42
	v_exp_f32_e32 v58, v58
	s_waitcnt lgkmcnt(8)
	v_mfma_f32_32x32x16_bf16 v[80:95], v[140:143], v[120:123], v[80:95]
	v_exp_f32_e32 v43, v43
	v_exp_f32_e32 v59, v59
	v_mfma_f32_16x16x32_bf16 v[234:237], v[246:249], v[100:103], v[234:237]
	v_cvt_pk_bf16_f32 v100, v40, v41
	v_exp_f32_e32 v44, v44
	v_exp_f32_e32 v60, v60
	v_cvt_pk_bf16_f32 v101, v42, v43
	ds_read_b64_tr_b16 v[176:177], v240 offset:0
	ds_read_b64_tr_b16 v[178:179], v240 offset:1536
	s_waitcnt lgkmcnt(5)
	v_mfma_f32_32x32x16_bf16 v[64:79], v[144:147], v[124:127], v[64:79]
	v_exp_f32_e32 v45, v45
	v_exp_f32_e32 v61, v61
	v_exp_f32_e32 v46, v46
	ds_read_b64_tr_b16 v[180:181], v240 offset:64
	ds_read_b64_tr_b16 v[182:183], v240 offset:1600
	v_mfma_f32_32x32x16_bf16 v[0:15], v[200:203], v[108:111], v[0:15]
	v_exp_f32_e32 v62, v62
	v_cvt_pk_bf16_f32 v102, v44, v45
	v_exp_f32_e32 v47, v47
	ds_read_b64_tr_b16 v[184:185], v240 offset:6144
	ds_read_b64_tr_b16 v[186:187], v240 offset:7680
	s_waitcnt lgkmcnt(8)
	v_mfma_f32_32x32x16_bf16 v[80:95], v[148:151], v[124:127], v[80:95]
	v_exp_f32_e32 v63, v63
	v_cvt_pk_bf16_f32 v103, v46, v47
	ds_read_b64_tr_b16 v[188:189], v240 offset:6208
	ds_read_b64_tr_b16 v[190:191], v240 offset:7744
	v_mfma_f32_32x32x16_bf16 v[16:31], v[204:207], v[108:111], v[16:31]
	v_mfma_f32_16x16x32_bf16 v[234:237], v[246:249], v[108:111], v[234:237]
	v_cvt_pk_bf16_f32 v108, v56, v57
	v_cvt_pk_bf16_f32 v109, v58, v59
	v_cvt_pk_bf16_f32 v110, v60, v61
	v_cvt_pk_bf16_f32 v111, v62, v63
	s_cmp_lg_u32 s9, 0
	s_cbranch_scc0 .Lagqa_noresc_9
	s_nop 15
	v_mul_f32_e32 v0, v0, v166
	v_mul_f32_e32 v1, v1, v166
	v_mul_f32_e32 v2, v2, v166
	v_mul_f32_e32 v3, v3, v166
	v_mul_f32_e32 v4, v4, v166
	v_mul_f32_e32 v5, v5, v166
	v_mul_f32_e32 v6, v6, v166
	v_mul_f32_e32 v7, v7, v166
	v_mul_f32_e32 v8, v8, v166
	v_mul_f32_e32 v9, v9, v166
	v_mul_f32_e32 v10, v10, v166
	v_mul_f32_e32 v11, v11, v166
	v_mul_f32_e32 v12, v12, v166
	v_mul_f32_e32 v13, v13, v166
	v_mul_f32_e32 v14, v14, v166
	v_mul_f32_e32 v15, v15, v166
	v_mul_f32_e32 v16, v16, v166
	v_mul_f32_e32 v17, v17, v166
	v_mul_f32_e32 v18, v18, v166
	v_mul_f32_e32 v19, v19, v166
	v_mul_f32_e32 v20, v20, v166
	v_mul_f32_e32 v21, v21, v166
	v_mul_f32_e32 v22, v22, v166
	v_mul_f32_e32 v23, v23, v166
	v_mul_f32_e32 v24, v24, v166
	v_mul_f32_e32 v25, v25, v166
	v_mul_f32_e32 v26, v26, v166
	v_mul_f32_e32 v27, v27, v166
	v_mul_f32_e32 v28, v28, v166
	v_mul_f32_e32 v29, v29, v166
	v_mul_f32_e32 v30, v30, v166
	v_mul_f32_e32 v31, v31, v166
	v_add_u32_e32 v170, 64, v175
	ds_bpermute_b32 v173, v170, v166
	v_mul_f32_e32 v234, v234, v166
	s_waitcnt lgkmcnt(0)
	v_mul_f32_e32 v235, v235, v173

; #define AT_STEP(SC0, SC1, SN0, SN1, t, DOK, DOV) do { \
;             if (DOK) AT_GLOADK(((t) + 2) * 64); \
;             if (DOV) { AT_GLOADV(((t) + 1) * 64); AT_QK(SN0, SN1, ((t) + 1) & 1); } \
;             AT_SMPV(SC0, SC1, (t) & 1); \
;             if (DOK) AT_WRITEK((t) & 1); \
;             if (DOV) AT_WRITEV(((t) + 1) & 1); \
;             __syncthreads(); } while (0)
; template <bool MLA>
; DI void attn_phase(const int TID, const int BID, LAS unsigned char* lds, const Params& p, bool need_ctx) {
;     ...
;         AT_STEP(sa0, sa1, sb0, sb1, t, false, true);
;         AT_STEP(sb0, sb1, sa0, sa1, t + 1, false, false);
.Lagqa_tail:
	ds_read_b128 v[136:139], v243 offset:0
	ds_read_b128 v[140:143], v243 offset:4608
	ds_read_b128 v[144:147], v243 offset:32
	ds_read_b128 v[148:151], v243 offset:4640
	s_waitcnt lgkmcnt(10)
	v_mfma_f32_32x32x16_bf16 v[0:15], v[176:179], v[96:99], v[0:15]
	v_max3_f32 v168, v64, v65, v66
	v_max3_f32 v170, v80, v81, v82
	v_max3_f32 v168, v168, v67, v68
	v_max3_f32 v170, v170, v83, v84
	v_max3_f32 v168, v168, v69, v70
	s_mov_b32 s9, 0
	s_waitcnt lgkmcnt(8)
	v_mfma_f32_32x32x16_bf16 v[16:31], v[180:183], v[96:99], v[16:31]
	v_max3_f32 v170, v170, v85, v86
	v_max3_f32 v168, v168, v71, v72
	v_max3_f32 v170, v170, v87, v88
	v_max3_f32 v168, v168, v73, v74
	v_max3_f32 v170, v170, v89, v90
	global_load_dwordx4 v[156:159], v167, s[4:5]
	s_add_u32 s4, s4, 0x2000
	s_addc_u32 s5, s5, 0
	v_mfma_f32_16x16x32_bf16 v[234:237], v[246:249], v[96:99], v[234:237]
	v_max3_f32 v168, v168, v75, v76
	v_max3_f32 v170, v170, v91, v92
	v_max3_f32 v168, v168, v77, v78
	v_max3_f32 v170, v170, v93, v94
	v_max3_f32 v168, v168, v170, v79
	v_max_f32_e32 v168, v168, v95
	v_cmp_lt_f32_e32 vcc, 0x41000000, v168
	s_cbranch_vccz .Lagqa_nors_10
	v_mov_b32_e32 v170, v168
	s_nop 1
	v_permlane32_swap_b32_e32 v168, v170
	v_max_f32_e32 v168, v168, v170
	v_max_f32_e32 v170, 0, v168
	v_exp_f32_e64 v166, -v170
	v_sub_f32_e32 v218, v218, v170
	v_sub_f32_e32 v219, v219, v170
	v_sub_f32_e32 v220, v220, v170
	v_sub_f32_e32 v221, v221, v170
	v_sub_f32_e32 v222, v222, v170
	v_sub_f32_e32 v223, v223, v170
	v_sub_f32_e32 v224, v224, v170
	v_sub_f32_e32 v225, v225, v170
	v_sub_f32_e32 v226, v226, v170
	v_sub_f32_e32 v227, v227, v170
	v_sub_f32_e32 v228, v228, v170
	v_sub_f32_e32 v229, v229, v170
	v_sub_f32_e32 v230, v230, v170
	v_sub_f32_e32 v231, v231, v170
	v_sub_f32_e32 v232, v232, v170
	v_sub_f32_e32 v233, v233, v170
	v_sub_f32_e32 v64, v64, v170
	v_sub_f32_e32 v65, v65, v170
	v_sub_f32_e32 v66, v66, v170
	v_sub_f32_e32 v67, v67, v170
	v_sub_f32_e32 v68, v68, v170
	v_sub_f32_e32 v69, v69, v170
	v_sub_f32_e32 v70, v70, v170
	v_sub_f32_e32 v71, v71, v170
	v_sub_f32_e32 v72, v72, v170
	v_sub_f32_e32 v73, v73, v170
	v_sub_f32_e32 v74, v74, v170
	v_sub_f32_e32 v75, v75, v170
	v_sub_f32_e32 v76, v76, v170
	v_sub_f32_e32 v77, v77, v170
	v_sub_f32_e32 v78, v78, v170
	v_sub_f32_e32 v79, v79, v170
	v_sub_f32_e32 v80, v80, v170
	v_sub_f32_e32 v81, v81, v170
	v_sub_f32_e32 v82, v82, v170
	v_sub_f32_e32 v83, v83, v170
	v_sub_f32_e32 v84, v84, v170
	v_sub_f32_e32 v85, v85, v170
	v_sub_f32_e32 v86, v86, v170
	v_sub_f32_e32 v87, v87, v170
	v_sub_f32_e32 v88, v88, v170
	v_sub_f32_e32 v89, v89, v170
	v_sub_f32_e32 v90, v90, v170
	v_sub_f32_e32 v91, v91, v170
	v_sub_f32_e32 v92, v92, v170
	v_sub_f32_e32 v93, v93, v170
	v_sub_f32_e32 v94, v94, v170
	v_sub_f32_e32 v95, v95, v170
	s_mov_b32 s9, 1
.Lagqa_nors_10:
	s_waitcnt lgkmcnt(3)
	v_mfma_f32_32x32x16_bf16 v[32:47], v[136:139], v[112:115], v[218:233]
	v_exp_f32_e32 v64, v64
	v_exp_f32_e32 v80, v80
	v_exp_f32_e32 v65, v65
	ds_read_b128 v[136:139], v243 offset:64
	ds_read_b64_tr_b16 v[192:193], v240 offset:3072
	ds_read_b64_tr_b16 v[194:195], v240 offset:4608
	v_mfma_f32_32x32x16_bf16 v[0:15], v[184:187], v[104:107], v[0:15]
	v_exp_f32_e32 v81, v81
	v_exp_f32_e32 v66, v66
	ds_read_b64_tr_b16 v[196:197], v240 offset:3136
	ds_read_b64_tr_b16 v[198:199], v240 offset:4672
	s_waitcnt lgkmcnt(7)
	v_mfma_f32_32x32x16_bf16 v[48:63], v[140:143], v[112:115], v[218:233]
	v_exp_f32_e32 v82, v82
	v_cvt_pk_bf16_f32 v96, v64, v65
	v_exp_f32_e32 v67, v67
	ds_read_b128 v[140:143], v243 offset:4672
	ds_read_b64_tr_b16 v[200:201], v240 offset:9216
	ds_read_b64_tr_b16 v[202:203], v240 offset:10752
	v_mfma_f32_32x32x16_bf16 v[16:31], v[188:191], v[104:107], v[16:31]
	v_exp_f32_e32 v83, v83
	v_exp_f32_e32 v68, v68
	v_exp_f32_e32 v84, v84
	ds_read_b64_tr_b16 v[204:205], v240 offset:9280
	ds_read_b64_tr_b16 v[206:207], v240 offset:10816
	s_waitcnt lgkmcnt(11)
	v_mfma_f32_32x32x16_bf16 v[32:47], v[144:147], v[116:119], v[32:47]
	v_cvt_pk_bf16_f32 v97, v66, v67
	v_exp_f32_e32 v69, v69
	v_exp_f32_e32 v85, v85
	ds_read_b128 v[144:147], v243 offset:96
	v_mfma_f32_16x16x32_bf16 v[234:237], v[246:249], v[104:107], v[234:237]
	v_cvt_pk_bf16_f32 v104, v80, v81
	v_cvt_pk_bf16_f32 v105, v82, v83
	v_exp_f32_e32 v70, v70
	v_exp_f32_e32 v86, v86
	s_waitcnt lgkmcnt(11)
	v_mfma_f32_32x32x16_bf16 v[48:63], v[148:151], v[116:119], v[48:63]
	v_cvt_pk_bf16_f32 v98, v68, v69
	v_cvt_pk_bf16_f32 v106, v84, v85
	v_exp_f32_e32 v71, v71
	v_exp_f32_e32 v87, v87
	ds_read_b128 v[148:151], v243 offset:4704
	s_waitcnt lgkmcnt(9)
	v_mfma_f32_32x32x16_bf16 v[0:15], v[192:195], v[100:103], v[0:15]
	v_exp_f32_e32 v72, v72
	v_exp_f32_e32 v88, v88
	v_mfma_f32_32x32x16_bf16 v[32:47], v[136:139], v[120:123], v[32:47]
	v_cvt_pk_bf16_f32 v99, v70, v71
	v_cvt_pk_bf16_f32 v107, v86, v87
	v_exp_f32_e32 v73, v73
	s_waitcnt vmcnt(2)
	ds_write_b128 v238, v[208:211] offset:9216
	s_waitcnt vmcnt(1)
	ds_write_b128 v241, v[212:215] offset:24576
	s_waitcnt lgkmcnt(9)
	v_mfma_f32_32x32x16_bf16 v[16:31], v[196:199], v[100:103], v[16:31]
	v_exp_f32_e32 v89, v89
	v_exp_f32_e32 v74, v74
	v_exp_f32_e32 v90, v90
	s_waitcnt lgkmcnt(8)
	v_mfma_f32_32x32x16_bf16 v[48:63], v[140:143], v[120:123], v[48:63]
	v_exp_f32_e32 v75, v75
	v_exp_f32_e32 v91, v91
	v_mfma_f32_16x16x32_bf16 v[234:237], v[246:249], v[100:103], v[234:237]
	v_cvt_pk_bf16_f32 v100, v72, v73
	v_exp_f32_e32 v76, v76
	v_exp_f32_e32 v92, v92
	v_cvt_pk_bf16_f32 v101, v74, v75
	ds_read_b64_tr_b16 v[176:177], v240 offset:12288
	ds_read_b64_tr_b16 v[178:179], v240 offset:13824
	s_waitcnt lgkmcnt(5)
	v_mfma_f32_32x32x16_bf16 v[32:47], v[144:147], v[124:127], v[32:47]
	v_exp_f32_e32 v77, v77
	v_exp_f32_e32 v93, v93
	v_exp_f32_e32 v78, v78
	ds_read_b64_tr_b16 v[180:181], v240 offset:12352
	ds_read_b64_tr_b16 v[182:183], v240 offset:13888
	v_mfma_f32_32x32x16_bf16 v[0:15], v[200:203], v[108:111], v[0:15]
	v_exp_f32_e32 v94, v94
	v_cvt_pk_bf16_f32 v102, v76, v77
	v_exp_f32_e32 v79, v79
	ds_read_b64_tr_b16 v[184:185], v240 offset:18432
	ds_read_b64_tr_b16 v[186:187], v240 offset:19968
	s_waitcnt lgkmcnt(8)
	v_mfma_f32_32x32x16_bf16 v[48:63], v[148:151], v[124:127], v[48:63]
	v_exp_f32_e32 v95, v95
	v_cvt_pk_bf16_f32 v103, v78, v79
	ds_read_b64_tr_b16 v[188:189], v240 offset:18496
	ds_read_b64_tr_b16 v[190:191], v240 offset:20032
	v_mfma_f32_32x32x16_bf16 v[16:31], v[204:207], v[108:111], v[16:31]
	v_mfma_f32_16x16x32_bf16 v[234:237], v[246:249], v[108:111], v[234:237]
	v_cvt_pk_bf16_f32 v108, v88, v89
	v_cvt_pk_bf16_f32 v109, v90, v91
	v_cvt_pk_bf16_f32 v110, v92, v93
	v_cvt_pk_bf16_f32 v111, v94, v95
	s_cmp_lg_u32 s9, 0
	s_cbranch_scc0 .Lagqa_noresc_11
; #define AT_STEP(SC0, SC1, SN0, SN1, t, DOK, DOV) do { \
;             if (DOK) AT_GLOADK(((t) + 2) * 64); \
;             if (DOV) { AT_GLOADV(((t) + 1) * 64); AT_QK(SN0, SN1, ((t) + 1) & 1); } \
;             AT_SMPV(SC0, SC1, (t) & 1); \
;             if (DOK) AT_WRITEK((t) & 1); \
;             if (DOV) AT_WRITEV(((t) + 1) & 1); \
;             __syncthreads(); } while (0)
; template <bool MLA>
; DI void attn_phase(const int TID, const int BID, LAS unsigned char* lds, const Params& p, bool need_ctx) {
;     ...
;         AT_STEP(sa0, sa1, sb0, sb1, t, false, true);
;         AT_STEP(sb0, sb1, sa0, sa1, t + 1, false, false);
	s_nop 15
	v_mul_f32_e32 v0, v0, v166
	v_mul_f32_e32 v1, v1, v166
	v_mul_f32_e32 v2, v2, v166
	v_mul_f32_e32 v3, v3, v166
	v_mul_f32_e32 v4, v4, v166
	v_mul_f32_e32 v5, v5, v166
	v_mul_f32_e32 v6, v6, v166
	v_mul_f32_e32 v7, v7, v166
	v_mul_f32_e32 v8, v8, v166
	v_mul_f32_e32 v9, v9, v166
	v_mul_f32_e32 v10, v10, v166
	v_mul_f32_e32 v11, v11, v166
	v_mul_f32_e32 v12, v12, v166
	v_mul_f32_e32 v13, v13, v166
	v_mul_f32_e32 v14, v14, v166
	v_mul_f32_e32 v15, v15, v166
	v_mul_f32_e32 v16, v16, v166
	v_mul_f32_e32 v17, v17, v166
	v_mul_f32_e32 v18, v18, v166
	v_mul_f32_e32 v19, v19, v166
	v_mul_f32_e32 v20, v20, v166
	v_mul_f32_e32 v21, v21, v166
	v_mul_f32_e32 v22, v22, v166
	v_mul_f32_e32 v23, v23, v166
	v_mul_f32_e32 v24, v24, v166
	v_mul_f32_e32 v25, v25, v166
	v_mul_f32_e32 v26, v26, v166
	v_mul_f32_e32 v27, v27, v166
	v_mul_f32_e32 v28, v28, v166
	v_mul_f32_e32 v29, v29, v166
	v_mul_f32_e32 v30, v30, v166
	v_mul_f32_e32 v31, v31, v166
	v_add_u32_e32 v170, 64, v175
	ds_bpermute_b32 v173, v170, v166
	v_mul_f32_e32 v234, v234, v166
	s_waitcnt lgkmcnt(0)
	v_mul_f32_e32 v235, v235, v173
.Lagqa_noresc_11:
	s_nop 1
	s_waitcnt lgkmcnt(8)
	s_barrier
	ds_read_b128 v[136:139], v243 offset:9216
	ds_read_b128 v[140:143], v243 offset:13824
	ds_read_b128 v[144:147], v243 offset:9248
	ds_read_b128 v[148:151], v243 offset:13856
	s_waitcnt lgkmcnt(10)
	v_mfma_f32_32x32x16_bf16 v[0:15], v[176:179], v[96:99], v[0:15]
	v_max3_f32 v168, v32, v33, v34
	v_max3_f32 v170, v48, v49, v50
	v_max3_f32 v168, v168, v35, v36
	v_max3_f32 v170, v170, v51, v52
	v_max3_f32 v168, v168, v37, v38
	s_mov_b32 s9, 0
	s_waitcnt lgkmcnt(8)
	v_mfma_f32_32x32x16_bf16 v[16:31], v[180:183], v[96:99], v[16:31]
	v_max3_f32 v170, v170, v53, v54
	v_max3_f32 v168, v168, v39, v40
	v_max3_f32 v170, v170, v55, v56
	v_max3_f32 v168, v168, v41, v42
	v_max3_f32 v170, v170, v57, v58
	v_mfma_f32_16x16x32_bf16 v[234:237], v[246:249], v[96:99], v[234:237]
	v_max3_f32 v168, v168, v43, v44
	v_max3_f32 v170, v170, v59, v60
	v_max3_f32 v168, v168, v45, v46
	v_max3_f32 v170, v170, v61, v62
	v_max3_f32 v168, v168, v170, v47
	v_max_f32_e32 v168, v168, v63
	v_cmp_lt_f32_e32 vcc, 0x41000000, v168
	s_cbranch_vccz .Lagqa_nors_12
	v_mov_b32_e32 v170, v168
	s_nop 1
	v_permlane32_swap_b32_e32 v168, v170
	v_max_f32_e32 v168, v168, v170
	v_max_f32_e32 v170, 0, v168
	v_exp_f32_e64 v166, -v170
	v_sub_f32_e32 v218, v218, v170
	v_sub_f32_e32 v219, v219, v170
	v_sub_f32_e32 v220, v220, v170
	v_sub_f32_e32 v221, v221, v170
	v_sub_f32_e32 v222, v222, v170
	v_sub_f32_e32 v223, v223, v170
	v_sub_f32_e32 v224, v224, v170
	v_sub_f32_e32 v225, v225, v170
	v_sub_f32_e32 v226, v226, v170
	v_sub_f32_e32 v227, v227, v170
	v_sub_f32_e32 v228, v228, v170
	v_sub_f32_e32 v229, v229, v170
	v_sub_f32_e32 v230, v230, v170
	v_sub_f32_e32 v231, v231, v170
	v_sub_f32_e32 v232, v232, v170
	v_sub_f32_e32 v233, v233, v170
	v_sub_f32_e32 v32, v32, v170
	v_sub_f32_e32 v33, v33, v170
	v_sub_f32_e32 v34, v34, v170
	v_sub_f32_e32 v35, v35, v170
	v_sub_f32_e32 v36, v36, v170
	v_sub_f32_e32 v37, v37, v170
	v_sub_f32_e32 v38, v38, v170
	v_sub_f32_e32 v39, v39, v170
	v_sub_f32_e32 v40, v40, v170
	v_sub_f32_e32 v41, v41, v170
	v_sub_f32_e32 v42, v42, v170
	v_sub_f32_e32 v43, v43, v170
	v_sub_f32_e32 v44, v44, v170
	v_sub_f32_e32 v45, v45, v170
	v_sub_f32_e32 v46, v46, v170
	v_sub_f32_e32 v47, v47, v170
	v_sub_f32_e32 v48, v48, v170
	v_sub_f32_e32 v49, v49, v170
	v_sub_f32_e32 v50, v50, v170
	v_sub_f32_e32 v51, v51, v170
	v_sub_f32_e32 v52, v52, v170
	v_sub_f32_e32 v53, v53, v170
	v_sub_f32_e32 v54, v54, v170
	v_sub_f32_e32 v55, v55, v170
	v_sub_f32_e32 v56, v56, v170
	v_sub_f32_e32 v57, v57, v170
	v_sub_f32_e32 v58, v58, v170
	v_sub_f32_e32 v59, v59, v170
	v_sub_f32_e32 v60, v60, v170
	v_sub_f32_e32 v61, v61, v170
	v_sub_f32_e32 v62, v62, v170
	v_sub_f32_e32 v63, v63, v170
	s_mov_b32 s9, 1
; #define AT_STEP(SC0, SC1, SN0, SN1, t, DOK, DOV) do { \
;             if (DOK) AT_GLOADK(((t) + 2) * 64); \
;             if (DOV) { AT_GLOADV(((t) + 1) * 64); AT_QK(SN0, SN1, ((t) + 1) & 1); } \
;             AT_SMPV(SC0, SC1, (t) & 1); \
;             if (DOK) AT_WRITEK((t) & 1); \
;             if (DOV) AT_WRITEV(((t) + 1) & 1); \
;             __syncthreads(); } while (0)
; template <bool MLA>
; DI void attn_phase(const int TID, const int BID, LAS unsigned char* lds, const Params& p, bool need_ctx) {
;     ...
;         AT_STEP(sa0, sa1, sb0, sb1, t, false, true);
;         AT_STEP(sb0, sb1, sa0, sa1, t + 1, false, false);
.Lagqa_nors_12:
	s_waitcnt lgkmcnt(3)
	v_mfma_f32_32x32x16_bf16 v[64:79], v[136:139], v[112:115], v[218:233]
	v_exp_f32_e32 v32, v32
	v_exp_f32_e32 v48, v48
	v_exp_f32_e32 v33, v33
	ds_read_b128 v[136:139], v243 offset:9280
	ds_read_b64_tr_b16 v[192:193], v240 offset:15360
	ds_read_b64_tr_b16 v[194:195], v240 offset:16896
	v_mfma_f32_32x32x16_bf16 v[0:15], v[184:187], v[104:107], v[0:15]
	v_exp_f32_e32 v49, v49
	v_exp_f32_e32 v34, v34
	ds_read_b64_tr_b16 v[196:197], v240 offset:15424
	ds_read_b64_tr_b16 v[198:199], v240 offset:16960
	s_waitcnt lgkmcnt(7)
	v_mfma_f32_32x32x16_bf16 v[80:95], v[140:143], v[112:115], v[218:233]
	v_exp_f32_e32 v50, v50
	v_cvt_pk_bf16_f32 v96, v32, v33
	v_exp_f32_e32 v35, v35
	ds_read_b128 v[140:143], v243 offset:13888
	ds_read_b64_tr_b16 v[200:201], v240 offset:21504
	ds_read_b64_tr_b16 v[202:203], v240 offset:23040
	v_mfma_f32_32x32x16_bf16 v[16:31], v[188:191], v[104:107], v[16:31]
	v_exp_f32_e32 v51, v51
	v_exp_f32_e32 v36, v36
	v_exp_f32_e32 v52, v52
	ds_read_b64_tr_b16 v[204:205], v240 offset:21568
	ds_read_b64_tr_b16 v[206:207], v240 offset:23104
	s_waitcnt lgkmcnt(11)
	v_mfma_f32_32x32x16_bf16 v[64:79], v[144:147], v[116:119], v[64:79]
	v_cvt_pk_bf16_f32 v97, v34, v35
	v_exp_f32_e32 v37, v37
	v_exp_f32_e32 v53, v53
	ds_read_b128 v[144:147], v243 offset:9312
	v_mfma_f32_16x16x32_bf16 v[234:237], v[246:249], v[104:107], v[234:237]
	v_cvt_pk_bf16_f32 v104, v48, v49
	v_cvt_pk_bf16_f32 v105, v50, v51
	v_exp_f32_e32 v38, v38
	v_exp_f32_e32 v54, v54
	s_waitcnt lgkmcnt(11)
	v_mfma_f32_32x32x16_bf16 v[80:95], v[148:151], v[116:119], v[80:95]
	v_cvt_pk_bf16_f32 v98, v36, v37
	v_cvt_pk_bf16_f32 v106, v52, v53
	v_exp_f32_e32 v39, v39
	v_exp_f32_e32 v55, v55
	ds_read_b128 v[148:151], v243 offset:13920
	s_waitcnt lgkmcnt(9)
	v_mfma_f32_32x32x16_bf16 v[0:15], v[192:195], v[100:103], v[0:15]
	v_exp_f32_e32 v40, v40
	v_exp_f32_e32 v56, v56
	v_mfma_f32_32x32x16_bf16 v[64:79], v[136:139], v[120:123], v[64:79]
	v_cvt_pk_bf16_f32 v99, v38, v39
	v_cvt_pk_bf16_f32 v107, v54, v55
	v_exp_f32_e32 v41, v41
	s_waitcnt vmcnt(0)
	ds_write_b128 v241, v[156:159] offset:36864
	s_waitcnt lgkmcnt(8)
	v_mfma_f32_32x32x16_bf16 v[16:31], v[196:199], v[100:103], v[16:31]
	v_exp_f32_e32 v57, v57
	v_exp_f32_e32 v42, v42
	v_exp_f32_e32 v58, v58
	s_waitcnt lgkmcnt(7)
	v_mfma_f32_32x32x16_bf16 v[80:95], v[140:143], v[120:123], v[80:95]
	v_exp_f32_e32 v43, v43
	v_exp_f32_e32 v59, v59
	v_mfma_f32_16x16x32_bf16 v[234:237], v[246:249], v[100:103], v[234:237]
	v_cvt_pk_bf16_f32 v100, v40, v41
	v_exp_f32_e32 v44, v44
	v_exp_f32_e32 v60, v60
	v_cvt_pk_bf16_f32 v101, v42, v43
	ds_read_b64_tr_b16 v[176:177], v240 offset:24576
	ds_read_b64_tr_b16 v[178:179], v240 offset:26112
	s_waitcnt lgkmcnt(4)
	v_mfma_f32_32x32x16_bf16 v[64:79], v[144:147], v[124:127], v[64:79]
	v_exp_f32_e32 v45, v45
	v_exp_f32_e32 v61, v61
	v_exp_f32_e32 v46, v46
	ds_read_b64_tr_b16 v[180:181], v240 offset:24640
	ds_read_b64_tr_b16 v[182:183], v240 offset:26176
	v_mfma_f32_32x32x16_bf16 v[0:15], v[200:203], v[108:111], v[0:15]
	v_exp_f32_e32 v62, v62
	v_cvt_pk_bf16_f32 v102, v44, v45
	v_exp_f32_e32 v47, v47
	ds_read_b64_tr_b16 v[184:185], v240 offset:30720
	ds_read_b64_tr_b16 v[186:187], v240 offset:32256
	s_waitcnt lgkmcnt(7)
	v_mfma_f32_32x32x16_bf16 v[80:95], v[148:151], v[124:127], v[80:95]
	v_exp_f32_e32 v63, v63
	v_cvt_pk_bf16_f32 v103, v46, v47
	ds_read_b64_tr_b16 v[188:189], v240 offset:30784
	ds_read_b64_tr_b16 v[190:191], v240 offset:32320
	v_mfma_f32_32x32x16_bf16 v[16:31], v[204:207], v[108:111], v[16:31]
	v_mfma_f32_16x16x32_bf16 v[234:237], v[246:249], v[108:111], v[234:237]
	v_cvt_pk_bf16_f32 v108, v56, v57
	v_cvt_pk_bf16_f32 v109, v58, v59
	v_cvt_pk_bf16_f32 v110, v60, v61
	v_cvt_pk_bf16_f32 v111, v62, v63
	s_cmp_lg_u32 s9, 0
	s_cbranch_scc0 .Lagqa_noresc_13
	s_nop 15
	v_mul_f32_e32 v0, v0, v166
	v_mul_f32_e32 v1, v1, v166
	v_mul_f32_e32 v2, v2, v166
	v_mul_f32_e32 v3, v3, v166
	v_mul_f32_e32 v4, v4, v166
	v_mul_f32_e32 v5, v5, v166
	v_mul_f32_e32 v6, v6, v166
	v_mul_f32_e32 v7, v7, v166
	v_mul_f32_e32 v8, v8, v166
	v_mul_f32_e32 v9, v9, v166
	v_mul_f32_e32 v10, v10, v166
	v_mul_f32_e32 v11, v11, v166
	v_mul_f32_e32 v12, v12, v166
	v_mul_f32_e32 v13, v13, v166
	v_mul_f32_e32 v14, v14, v166
	v_mul_f32_e32 v15, v15, v166
	v_mul_f32_e32 v16, v16, v166
	v_mul_f32_e32 v17, v17, v166
	v_mul_f32_e32 v18, v18, v166
	v_mul_f32_e32 v19, v19, v166
	v_mul_f32_e32 v20, v20, v166
	v_mul_f32_e32 v21, v21, v166
	v_mul_f32_e32 v22, v22, v166
	v_mul_f32_e32 v23, v23, v166
	v_mul_f32_e32 v24, v24, v166
	v_mul_f32_e32 v25, v25, v166
	v_mul_f32_e32 v26, v26, v166
	v_mul_f32_e32 v27, v27, v166
	v_mul_f32_e32 v28, v28, v166
	v_mul_f32_e32 v29, v29, v166
	v_mul_f32_e32 v30, v30, v166
	v_mul_f32_e32 v31, v31, v166
	v_add_u32_e32 v170, 64, v175
	ds_bpermute_b32 v173, v170, v166
	v_mul_f32_e32 v234, v234, v166
	s_waitcnt lgkmcnt(0)
	v_mul_f32_e32 v235, v235, v173

; template <bool MLA>
; DI void attn_phase(const int TID, const int BID, LAS unsigned char* lds, const Params& p, bool need_ctx) {
;     ...
;     for (int item = BID; item < n_items; item += gridDim.x) {
;         int b, head, row0, nk;
;         if (item < 1024) {
;             const int rnd = item >> 8, w = item & 255, xcd = w & 7, slot = w >> 3, qb = slot & 7;
;             if (MLA) { const int grp = (rnd * 8 + xcd) * 4 + (slot >> 3); b = grp >> 4; head = grp & 15; }
;             else { const int grp = rnd * 8 + xcd; b = grp >> 2; head = (grp & 3) * 4 + (slot >> 3); }
;             row0 = b * 2048 + qb * 256; nk = NKEY;
;         }
;         else { const int it = item - 1024; b = it >> 4; head = it & 15; row0 = TL + b * 256; nk = 256; }
.Lagqa_mainitem_next:
	s_lshr_b32 s21, s59, 8
	s_and_b32 s55, s59, 7
	s_lshl_b32 s21, s21, 3
	s_add_i32 s21, s21, s55
	s_bfe_u32 s55, s59, 0x30003
	s_bfe_u32 s56, s59, 0x20006
	s_lshr_b32 s15, s21, 2
	s_and_b32 s57, s21, 3
	s_lshl_b32 s18, s57, 2
	s_add_i32 s18, s18, s56
	s_lshl_b32 s20, s15, 11
	s_lshl_b32 s55, s55, 8
	s_add_i32 s20, s20, s55
	s_mov_b32 s7, 8
